# in_proj GEMM epilogue: nt (non-temporal) cache hint on the bf16 projection stores
# baseline (speedup 1.0000x reference)
; __device__ __forceinline__ unsigned pk_bf16(float lo, float hi) { unsigned r; asm("v_cvt_pk_bf16_f32 %0, %1, %2" : "=v"(r) : "v"(lo), "v"(hi)); return r; }
; __device__ __forceinline__ float sigm(float x) { return __builtin_amdgcn_rcpf(1.f + __expf(-x)); }
;     __device__ __forceinline__ void operator()(f32x4 (&acc)[2][2][4][2], const Unit& u, int wr, int wc, int fr, int fq) const {
;     ...
;             const int colb = u.pn * 256 + bj * 128;
;             if (colb >= NIN) continue;
;             const int act = colb >= OFF_MERGE ? 2 : (colb >= OFF_GATE ? 1 : 0);
;             u16* pb = proj + (size_t)(u.pm * 256 + wr * 64 + fr) * NIN + colb + wc * 32 + 8 * fq;
; #pragma unroll
;             for (int ai = 0; ai < 2; ++ai)
; #pragma unroll
;                 for (int m = 0; m < 4; ++m) {
;                     f32x4 v0 = acc[ai][bj][m][0], v1 = acc[ai][bj][m][1];
;                     if (act == 1) {
; #pragma unroll
;                         for (int j = 0; j < 4; ++j) { v0[j] = v0[j] * sigm(v0[j]); v1[j] = v1[j] * sigm(v1[j]); }
;                     } else if (act == 2) {
; #pragma unroll
;                         for (int j = 0; j < 4; ++j) { v0[j] = sigm(v0[j]); v1[j] = sigm(v1[j]); }
;                     }
;                     u32x4 w; w.x = pk_bf16(v0[0], v0[1]); w.y = pk_bf16(v0[2], v0[3]); w.z = pk_bf16(v1[0], v1[1]); w.w = pk_bf16(v1[2], v1[3]);
;                     *(u32x4*)(pb + (size_t)(ai * 128 + m * 16) * NIN) = w;
.LBB0_109:
	v_readlane_b32 s28, v252, 40
	v_readlane_b32 s29, v252, 41
	v_lshl_add_u32 v122, s62, 8, v139
	s_ashr_i32 s67, s66, 31
	v_mov_b64_e32 v[120:121], s[28:29]
	v_mad_i64_i32 v[120:121], s[28:29], v122, s23, v[120:121]
	v_lshl_add_u64 v[120:121], s[66:67], 1, v[120:121]
	s_lshl_b32 s2, s18, 1
	v_lshl_add_u64 v[120:121], v[120:121], 0, s[2:3]
	v_lshlrev_b32_e32 v136, 1, v138
	v_lshl_add_u64 v[120:121], v[120:121], 0, v[136:137]
	v_cvt_pk_bf16_f32 v122, v148, v150
	v_cvt_pk_bf16_f32 v123, v152, v155
	v_cvt_pk_bf16_f32 v124, v149, v151
	v_cvt_pk_bf16_f32 v125, v153, v154
	s_cmp_gt_i32 s11, 1
	s_mov_b64 s[68:69], -1
	global_store_dwordx4 v[120:121], v[122:125], off nt
	s_cbranch_scc0 .LBB0_111
	v_mul_f32_e32 v136, 0xbfb8aa3b, v119
	v_mul_f32_e32 v122, 0xbfb8aa3b, v116
	v_mul_f32_e32 v123, 0xbfb8aa3b, v112
	v_mul_f32_e32 v124, 0xbfb8aa3b, v117
	v_mul_f32_e32 v125, 0xbfb8aa3b, v113
	v_mul_f32_e32 v126, 0xbfb8aa3b, v118
	v_mul_f32_e32 v127, 0xbfb8aa3b, v114
	v_exp_f32_e32 v136, v136
	v_mul_f32_e32 v148, 0xbfb8aa3b, v115
	v_exp_f32_e32 v122, v122
	v_exp_f32_e32 v123, v123
	v_exp_f32_e32 v124, v124
	v_exp_f32_e32 v125, v125
	v_exp_f32_e32 v126, v126
	v_exp_f32_e32 v127, v127
	v_exp_f32_e32 v149, v148
	v_add_f32_e32 v136, 1.0, v136
	v_add_f32_e32 v122, 1.0, v122
	v_add_f32_e32 v123, 1.0, v123
	v_add_f32_e32 v124, 1.0, v124
	v_add_f32_e32 v125, 1.0, v125
	v_add_f32_e32 v126, 1.0, v126
	v_add_f32_e32 v127, 1.0, v127
	v_rcp_f32_e32 v148, v136
	v_add_f32_e32 v136, 1.0, v149
	v_rcp_f32_e32 v122, v122
	v_rcp_f32_e32 v123, v123
	v_rcp_f32_e32 v124, v124
	v_rcp_f32_e32 v125, v125
	v_rcp_f32_e32 v126, v126
	v_rcp_f32_e32 v127, v127
	v_rcp_f32_e32 v136, v136
	s_mov_b64 s[68:69], 0

; __device__ __forceinline__ unsigned pk_bf16(float lo, float hi) { unsigned r; asm("v_cvt_pk_bf16_f32 %0, %1, %2" : "=v"(r) : "v"(lo), "v"(hi)); return r; }
; __device__ __forceinline__ float sigm(float x) { return __builtin_amdgcn_rcpf(1.f + __expf(-x)); }
;     __device__ __forceinline__ void operator()(f32x4 (&acc)[2][2][4][2], const Unit& u, int wr, int wc, int fr, int fq) const {
;     ...
;                     f32x4 v0 = acc[ai][bj][m][0], v1 = acc[ai][bj][m][1];
;                     if (act == 1) {
; #pragma unroll
;                         for (int j = 0; j < 4; ++j) { v0[j] = v0[j] * sigm(v0[j]); v1[j] = v1[j] * sigm(v1[j]); }
;                     } else if (act == 2) {
; #pragma unroll
;                         for (int j = 0; j < 4; ++j) { v0[j] = sigm(v0[j]); v1[j] = sigm(v1[j]); }
;                     }
;                     u32x4 w; w.x = pk_bf16(v0[0], v0[1]); w.y = pk_bf16(v0[2], v0[3]); w.z = pk_bf16(v1[0], v1[1]); w.w = pk_bf16(v1[2], v1[3]);
;                     *(u32x4*)(pb + (size_t)(ai * 128 + m * 16) * NIN) = w;
.LBB0_115:
	v_add_co_u32_e32 v116, vcc, 0x75000, v120
	v_cvt_pk_bf16_f32 v112, v122, v124
	v_cvt_pk_bf16_f32 v113, v126, v148
	v_cvt_pk_bf16_f32 v114, v123, v125
	v_cvt_pk_bf16_f32 v115, v127, v136
	s_nop 1
	v_addc_co_u32_e32 v117, vcc, 0, v121, vcc
	s_cmp_gt_i32 s11, 1
	s_mov_b64 s[68:69], -1
	global_store_dwordx4 v[116:117], v[112:115], off nt
	s_cbranch_scc0 .LBB0_117
	v_mul_f32_e32 v118, 0xbfb8aa3b, v111
	v_mul_f32_e32 v112, 0xbfb8aa3b, v108
	v_mul_f32_e32 v113, 0xbfb8aa3b, v104
	v_mul_f32_e32 v114, 0xbfb8aa3b, v109
	v_mul_f32_e32 v115, 0xbfb8aa3b, v105
	v_mul_f32_e32 v116, 0xbfb8aa3b, v110
	v_mul_f32_e32 v117, 0xbfb8aa3b, v106
	v_exp_f32_e32 v118, v118
	v_mul_f32_e32 v119, 0xbfb8aa3b, v107
	v_exp_f32_e32 v112, v112
	v_exp_f32_e32 v113, v113
	v_exp_f32_e32 v114, v114
	v_exp_f32_e32 v115, v115
	v_exp_f32_e32 v116, v116
	v_exp_f32_e32 v117, v117
	v_exp_f32_e32 v122, v119
	v_add_f32_e32 v118, 1.0, v118
	v_add_f32_e32 v112, 1.0, v112
	v_add_f32_e32 v113, 1.0, v113
	v_add_f32_e32 v114, 1.0, v114
	v_add_f32_e32 v115, 1.0, v115
	v_add_f32_e32 v116, 1.0, v116
	v_add_f32_e32 v117, 1.0, v117
	v_rcp_f32_e32 v119, v118
	v_add_f32_e32 v118, 1.0, v122
	v_rcp_f32_e32 v112, v112
	v_rcp_f32_e32 v113, v113
	v_rcp_f32_e32 v114, v114
	v_rcp_f32_e32 v115, v115
	v_rcp_f32_e32 v116, v116
	v_rcp_f32_e32 v117, v117
	v_rcp_f32_e32 v118, v118
	s_mov_b64 s[68:69], 0

; __device__ __forceinline__ unsigned pk_bf16(float lo, float hi) { unsigned r; asm("v_cvt_pk_bf16_f32 %0, %1, %2" : "=v"(r) : "v"(lo), "v"(hi)); return r; }
; __device__ __forceinline__ float sigm(float x) { return __builtin_amdgcn_rcpf(1.f + __expf(-x)); }
;     __device__ __forceinline__ void operator()(f32x4 (&acc)[2][2][4][2], const Unit& u, int wr, int wc, int fr, int fq) const {
;     ...
;                     f32x4 v0 = acc[ai][bj][m][0], v1 = acc[ai][bj][m][1];
;                     if (act == 1) {
; #pragma unroll
;                         for (int j = 0; j < 4; ++j) { v0[j] = v0[j] * sigm(v0[j]); v1[j] = v1[j] * sigm(v1[j]); }
;                     } else if (act == 2) {
; #pragma unroll
;                         for (int j = 0; j < 4; ++j) { v0[j] = sigm(v0[j]); v1[j] = sigm(v1[j]); }
;                     }
;                     u32x4 w; w.x = pk_bf16(v0[0], v0[1]); w.y = pk_bf16(v0[2], v0[3]); w.z = pk_bf16(v1[0], v1[1]); w.w = pk_bf16(v1[2], v1[3]);
;                     *(u32x4*)(pb + (size_t)(ai * 128 + m * 16) * NIN) = w;
.LBB0_121:
	v_add_co_u32_e32 v108, vcc, 0xea000, v120
	v_cvt_pk_bf16_f32 v104, v112, v114
	v_cvt_pk_bf16_f32 v105, v116, v119
	v_cvt_pk_bf16_f32 v106, v113, v115
	v_cvt_pk_bf16_f32 v107, v117, v118
	s_nop 1
	v_addc_co_u32_e32 v109, vcc, 0, v121, vcc
	s_cmp_gt_i32 s11, 1
	s_mov_b64 s[68:69], -1
	global_store_dwordx4 v[108:109], v[104:107], off nt
	s_cbranch_scc0 .LBB0_123
	v_mul_f32_e32 v110, 0xbfb8aa3b, v103
	v_mul_f32_e32 v104, 0xbfb8aa3b, v100
	v_mul_f32_e32 v105, 0xbfb8aa3b, v96
	v_mul_f32_e32 v106, 0xbfb8aa3b, v101
	v_mul_f32_e32 v107, 0xbfb8aa3b, v97
	v_mul_f32_e32 v108, 0xbfb8aa3b, v102
	v_mul_f32_e32 v109, 0xbfb8aa3b, v98
	v_exp_f32_e32 v110, v110
	v_mul_f32_e32 v111, 0xbfb8aa3b, v99
	v_exp_f32_e32 v104, v104
	v_exp_f32_e32 v105, v105
	v_exp_f32_e32 v106, v106
	v_exp_f32_e32 v107, v107
	v_exp_f32_e32 v108, v108
	v_exp_f32_e32 v109, v109
	v_exp_f32_e32 v112, v111
	v_add_f32_e32 v110, 1.0, v110
	v_add_f32_e32 v104, 1.0, v104
	v_add_f32_e32 v105, 1.0, v105
	v_add_f32_e32 v106, 1.0, v106
	v_add_f32_e32 v107, 1.0, v107
	v_add_f32_e32 v108, 1.0, v108
	v_add_f32_e32 v109, 1.0, v109
	v_rcp_f32_e32 v111, v110
	v_add_f32_e32 v110, 1.0, v112
	v_rcp_f32_e32 v104, v104
	v_rcp_f32_e32 v105, v105
	v_rcp_f32_e32 v106, v106
	v_rcp_f32_e32 v107, v107
	v_rcp_f32_e32 v108, v108
	v_rcp_f32_e32 v109, v109
	v_rcp_f32_e32 v110, v110
	s_mov_b64 s[68:69], 0

; __device__ __forceinline__ unsigned pk_bf16(float lo, float hi) { unsigned r; asm("v_cvt_pk_bf16_f32 %0, %1, %2" : "=v"(r) : "v"(lo), "v"(hi)); return r; }
; __device__ __forceinline__ float sigm(float x) { return __builtin_amdgcn_rcpf(1.f + __expf(-x)); }
;     __device__ __forceinline__ void operator()(f32x4 (&acc)[2][2][4][2], const Unit& u, int wr, int wc, int fr, int fq) const {
;     ...
;                     f32x4 v0 = acc[ai][bj][m][0], v1 = acc[ai][bj][m][1];
;                     if (act == 1) {
; #pragma unroll
;                         for (int j = 0; j < 4; ++j) { v0[j] = v0[j] * sigm(v0[j]); v1[j] = v1[j] * sigm(v1[j]); }
;                     } else if (act == 2) {
; #pragma unroll
;                         for (int j = 0; j < 4; ++j) { v0[j] = sigm(v0[j]); v1[j] = sigm(v1[j]); }
;                     }
;                     u32x4 w; w.x = pk_bf16(v0[0], v0[1]); w.y = pk_bf16(v0[2], v0[3]); w.z = pk_bf16(v1[0], v1[1]); w.w = pk_bf16(v1[2], v1[3]);
;                     *(u32x4*)(pb + (size_t)(ai * 128 + m * 16) * NIN) = w;
.LBB0_127:
	v_add_co_u32_e32 v100, vcc, 0x15f000, v120
	v_cvt_pk_bf16_f32 v96, v104, v106
	v_cvt_pk_bf16_f32 v97, v108, v111
	v_cvt_pk_bf16_f32 v98, v105, v107
	v_cvt_pk_bf16_f32 v99, v109, v110
	s_nop 1
	v_addc_co_u32_e32 v101, vcc, 0, v121, vcc
	s_cmp_gt_i32 s11, 1
	s_mov_b64 s[68:69], -1
	global_store_dwordx4 v[100:101], v[96:99], off nt
	s_cbranch_scc0 .LBB0_129
	v_mul_f32_e32 v102, 0xbfb8aa3b, v95
	v_mul_f32_e32 v96, 0xbfb8aa3b, v92
	v_mul_f32_e32 v97, 0xbfb8aa3b, v88
	v_mul_f32_e32 v98, 0xbfb8aa3b, v93
	v_mul_f32_e32 v99, 0xbfb8aa3b, v89
	v_mul_f32_e32 v100, 0xbfb8aa3b, v94
	v_mul_f32_e32 v101, 0xbfb8aa3b, v90
	v_exp_f32_e32 v102, v102
	v_mul_f32_e32 v103, 0xbfb8aa3b, v91
	v_exp_f32_e32 v96, v96
	v_exp_f32_e32 v97, v97
	v_exp_f32_e32 v98, v98
	v_exp_f32_e32 v99, v99
	v_exp_f32_e32 v100, v100
	v_exp_f32_e32 v101, v101
	v_exp_f32_e32 v104, v103
	v_add_f32_e32 v102, 1.0, v102
	v_add_f32_e32 v96, 1.0, v96
	v_add_f32_e32 v97, 1.0, v97
	v_add_f32_e32 v98, 1.0, v98
	v_add_f32_e32 v99, 1.0, v99
	v_add_f32_e32 v100, 1.0, v100
	v_add_f32_e32 v101, 1.0, v101
	v_rcp_f32_e32 v103, v102
	v_add_f32_e32 v102, 1.0, v104
	v_rcp_f32_e32 v96, v96
	v_rcp_f32_e32 v97, v97
	v_rcp_f32_e32 v98, v98
	v_rcp_f32_e32 v99, v99
	v_rcp_f32_e32 v100, v100
	v_rcp_f32_e32 v101, v101
	v_rcp_f32_e32 v102, v102
	s_mov_b64 s[68:69], 0

; __device__ __forceinline__ unsigned pk_bf16(float lo, float hi) { unsigned r; asm("v_cvt_pk_bf16_f32 %0, %1, %2" : "=v"(r) : "v"(lo), "v"(hi)); return r; }
; __device__ __forceinline__ float sigm(float x) { return __builtin_amdgcn_rcpf(1.f + __expf(-x)); }
;     __device__ __forceinline__ void operator()(f32x4 (&acc)[2][2][4][2], const Unit& u, int wr, int wc, int fr, int fq) const {
;     ...
;                     f32x4 v0 = acc[ai][bj][m][0], v1 = acc[ai][bj][m][1];
;                     if (act == 1) {
; #pragma unroll
;                         for (int j = 0; j < 4; ++j) { v0[j] = v0[j] * sigm(v0[j]); v1[j] = v1[j] * sigm(v1[j]); }
;                     } else if (act == 2) {
; #pragma unroll
;                         for (int j = 0; j < 4; ++j) { v0[j] = sigm(v0[j]); v1[j] = sigm(v1[j]); }
;                     }
;                     u32x4 w; w.x = pk_bf16(v0[0], v0[1]); w.y = pk_bf16(v0[2], v0[3]); w.z = pk_bf16(v1[0], v1[1]); w.w = pk_bf16(v1[2], v1[3]);
;                     *(u32x4*)(pb + (size_t)(ai * 128 + m * 16) * NIN) = w;
.LBB0_133:
	v_add_co_u32_e32 v92, vcc, 0x3a8000, v120
	v_cvt_pk_bf16_f32 v88, v96, v98
	v_cvt_pk_bf16_f32 v89, v100, v103
	v_cvt_pk_bf16_f32 v90, v97, v99
	v_cvt_pk_bf16_f32 v91, v101, v102
	s_nop 1
	v_addc_co_u32_e32 v93, vcc, 0, v121, vcc
	s_cmp_gt_i32 s11, 1
	s_mov_b64 s[68:69], -1
	global_store_dwordx4 v[92:93], v[88:91], off nt
	s_cbranch_scc0 .LBB0_135
	v_mul_f32_e32 v94, 0xbfb8aa3b, v87
	v_mul_f32_e32 v88, 0xbfb8aa3b, v84
	v_mul_f32_e32 v89, 0xbfb8aa3b, v80
	v_mul_f32_e32 v90, 0xbfb8aa3b, v85
	v_mul_f32_e32 v91, 0xbfb8aa3b, v81
	v_mul_f32_e32 v92, 0xbfb8aa3b, v86
	v_mul_f32_e32 v93, 0xbfb8aa3b, v82
	v_exp_f32_e32 v94, v94
	v_mul_f32_e32 v95, 0xbfb8aa3b, v83
	v_exp_f32_e32 v88, v88
	v_exp_f32_e32 v89, v89
	v_exp_f32_e32 v90, v90
	v_exp_f32_e32 v91, v91
	v_exp_f32_e32 v92, v92
	v_exp_f32_e32 v93, v93
	v_exp_f32_e32 v96, v95
	v_add_f32_e32 v94, 1.0, v94
	v_add_f32_e32 v88, 1.0, v88
	v_add_f32_e32 v89, 1.0, v89
	v_add_f32_e32 v90, 1.0, v90
	v_add_f32_e32 v91, 1.0, v91
	v_add_f32_e32 v92, 1.0, v92
	v_add_f32_e32 v93, 1.0, v93
	v_rcp_f32_e32 v95, v94
	v_add_f32_e32 v94, 1.0, v96
	v_rcp_f32_e32 v88, v88
	v_rcp_f32_e32 v89, v89
	v_rcp_f32_e32 v90, v90
	v_rcp_f32_e32 v91, v91
	v_rcp_f32_e32 v92, v92
	v_rcp_f32_e32 v93, v93
	v_rcp_f32_e32 v94, v94
	s_mov_b64 s[68:69], 0

; __device__ __forceinline__ unsigned pk_bf16(float lo, float hi) { unsigned r; asm("v_cvt_pk_bf16_f32 %0, %1, %2" : "=v"(r) : "v"(lo), "v"(hi)); return r; }
; __device__ __forceinline__ float sigm(float x) { return __builtin_amdgcn_rcpf(1.f + __expf(-x)); }
;     __device__ __forceinline__ void operator()(f32x4 (&acc)[2][2][4][2], const Unit& u, int wr, int wc, int fr, int fq) const {
;     ...
;                     f32x4 v0 = acc[ai][bj][m][0], v1 = acc[ai][bj][m][1];
;                     if (act == 1) {
; #pragma unroll
;                         for (int j = 0; j < 4; ++j) { v0[j] = v0[j] * sigm(v0[j]); v1[j] = v1[j] * sigm(v1[j]); }
;                     } else if (act == 2) {
; #pragma unroll
;                         for (int j = 0; j < 4; ++j) { v0[j] = sigm(v0[j]); v1[j] = sigm(v1[j]); }
;                     }
;                     u32x4 w; w.x = pk_bf16(v0[0], v0[1]); w.y = pk_bf16(v0[2], v0[3]); w.z = pk_bf16(v1[0], v1[1]); w.w = pk_bf16(v1[2], v1[3]);
;                     *(u32x4*)(pb + (size_t)(ai * 128 + m * 16) * NIN) = w;
.LBB0_139:
	v_add_co_u32_e32 v84, vcc, 0x41d000, v120
	v_cvt_pk_bf16_f32 v80, v88, v90
	v_cvt_pk_bf16_f32 v81, v92, v95
	v_cvt_pk_bf16_f32 v82, v89, v91
	v_cvt_pk_bf16_f32 v83, v93, v94
	s_nop 1
	v_addc_co_u32_e32 v85, vcc, 0, v121, vcc
	s_cmp_gt_i32 s11, 1
	s_mov_b64 s[68:69], -1
	global_store_dwordx4 v[84:85], v[80:83], off nt
	s_cbranch_scc0 .LBB0_141
	v_mul_f32_e32 v86, 0xbfb8aa3b, v79
	v_mul_f32_e32 v80, 0xbfb8aa3b, v76
	v_mul_f32_e32 v81, 0xbfb8aa3b, v72
	v_mul_f32_e32 v82, 0xbfb8aa3b, v77
	v_mul_f32_e32 v83, 0xbfb8aa3b, v73
	v_mul_f32_e32 v84, 0xbfb8aa3b, v78
	v_mul_f32_e32 v85, 0xbfb8aa3b, v74
	v_exp_f32_e32 v86, v86
	v_mul_f32_e32 v87, 0xbfb8aa3b, v75
	v_exp_f32_e32 v80, v80
	v_exp_f32_e32 v81, v81
	v_exp_f32_e32 v82, v82
	v_exp_f32_e32 v83, v83
	v_exp_f32_e32 v84, v84
	v_exp_f32_e32 v85, v85
	v_exp_f32_e32 v88, v87
	v_add_f32_e32 v86, 1.0, v86
	v_add_f32_e32 v80, 1.0, v80
	v_add_f32_e32 v81, 1.0, v81
	v_add_f32_e32 v82, 1.0, v82
	v_add_f32_e32 v83, 1.0, v83
	v_add_f32_e32 v84, 1.0, v84
	v_add_f32_e32 v85, 1.0, v85
	v_rcp_f32_e32 v87, v86
	v_add_f32_e32 v86, 1.0, v88
	v_rcp_f32_e32 v80, v80
	v_rcp_f32_e32 v81, v81
	v_rcp_f32_e32 v82, v82
	v_rcp_f32_e32 v83, v83
	v_rcp_f32_e32 v84, v84
	v_rcp_f32_e32 v85, v85
	v_rcp_f32_e32 v86, v86
	s_mov_b64 s[68:69], 0

; __device__ __forceinline__ unsigned pk_bf16(float lo, float hi) { unsigned r; asm("v_cvt_pk_bf16_f32 %0, %1, %2" : "=v"(r) : "v"(lo), "v"(hi)); return r; }
; __device__ __forceinline__ float sigm(float x) { return __builtin_amdgcn_rcpf(1.f + __expf(-x)); }
;     __device__ __forceinline__ void operator()(f32x4 (&acc)[2][2][4][2], const Unit& u, int wr, int wc, int fr, int fq) const {
;     ...
;                     f32x4 v0 = acc[ai][bj][m][0], v1 = acc[ai][bj][m][1];
;                     if (act == 1) {
; #pragma unroll
;                         for (int j = 0; j < 4; ++j) { v0[j] = v0[j] * sigm(v0[j]); v1[j] = v1[j] * sigm(v1[j]); }
;                     } else if (act == 2) {
; #pragma unroll
;                         for (int j = 0; j < 4; ++j) { v0[j] = sigm(v0[j]); v1[j] = sigm(v1[j]); }
;                     }
;                     u32x4 w; w.x = pk_bf16(v0[0], v0[1]); w.y = pk_bf16(v0[2], v0[3]); w.z = pk_bf16(v1[0], v1[1]); w.w = pk_bf16(v1[2], v1[3]);
;                     *(u32x4*)(pb + (size_t)(ai * 128 + m * 16) * NIN) = w;
.LBB0_145:
	v_add_co_u32_e32 v76, vcc, 0x492000, v120
	v_cvt_pk_bf16_f32 v72, v80, v82
	v_cvt_pk_bf16_f32 v73, v84, v87
	v_cvt_pk_bf16_f32 v74, v81, v83
	v_cvt_pk_bf16_f32 v75, v85, v86
	s_nop 1
	v_addc_co_u32_e32 v77, vcc, 0, v121, vcc
	s_cmp_gt_i32 s11, 1
	s_mov_b64 s[68:69], -1
	global_store_dwordx4 v[76:77], v[72:75], off nt
	s_cbranch_scc0 .LBB0_147
	v_mul_f32_e32 v78, 0xbfb8aa3b, v71
	v_mul_f32_e32 v72, 0xbfb8aa3b, v68
	v_mul_f32_e32 v73, 0xbfb8aa3b, v64
	v_mul_f32_e32 v74, 0xbfb8aa3b, v69
	v_mul_f32_e32 v75, 0xbfb8aa3b, v65
	v_mul_f32_e32 v76, 0xbfb8aa3b, v70
	v_mul_f32_e32 v77, 0xbfb8aa3b, v66
	v_exp_f32_e32 v78, v78
	v_mul_f32_e32 v79, 0xbfb8aa3b, v67
	v_exp_f32_e32 v72, v72
	v_exp_f32_e32 v73, v73
	v_exp_f32_e32 v74, v74
	v_exp_f32_e32 v75, v75
	v_exp_f32_e32 v76, v76
	v_exp_f32_e32 v77, v77
	v_exp_f32_e32 v80, v79
	v_add_f32_e32 v78, 1.0, v78
	v_add_f32_e32 v72, 1.0, v72
	v_add_f32_e32 v73, 1.0, v73
	v_add_f32_e32 v74, 1.0, v74
	v_add_f32_e32 v75, 1.0, v75
	v_add_f32_e32 v76, 1.0, v76
	v_add_f32_e32 v77, 1.0, v77
	v_rcp_f32_e32 v79, v78
	v_add_f32_e32 v78, 1.0, v80
	v_rcp_f32_e32 v72, v72
	v_rcp_f32_e32 v73, v73
	v_rcp_f32_e32 v74, v74
	v_rcp_f32_e32 v75, v75
	v_rcp_f32_e32 v76, v76
	v_rcp_f32_e32 v77, v77
	v_rcp_f32_e32 v78, v78
	s_mov_b64 s[68:69], 0

; __device__ __forceinline__ unsigned pk_bf16(float lo, float hi) { unsigned r; asm("v_cvt_pk_bf16_f32 %0, %1, %2" : "=v"(r) : "v"(lo), "v"(hi)); return r; }
; __device__ __forceinline__ float sigm(float x) { return __builtin_amdgcn_rcpf(1.f + __expf(-x)); }
;     __device__ __forceinline__ void operator()(f32x4 (&acc)[2][2][4][2], const Unit& u, int wr, int wc, int fr, int fq) const {
;     ...
;                     f32x4 v0 = acc[ai][bj][m][0], v1 = acc[ai][bj][m][1];
;                     if (act == 1) {
; #pragma unroll
;                         for (int j = 0; j < 4; ++j) { v0[j] = v0[j] * sigm(v0[j]); v1[j] = v1[j] * sigm(v1[j]); }
;                     } else if (act == 2) {
; #pragma unroll
;                         for (int j = 0; j < 4; ++j) { v0[j] = sigm(v0[j]); v1[j] = sigm(v1[j]); }
;                     }
;                     u32x4 w; w.x = pk_bf16(v0[0], v0[1]); w.y = pk_bf16(v0[2], v0[3]); w.z = pk_bf16(v1[0], v1[1]); w.w = pk_bf16(v1[2], v1[3]);
;                     *(u32x4*)(pb + (size_t)(ai * 128 + m * 16) * NIN) = w;
.LBB0_151:
	v_add_co_u32_e32 v68, vcc, 0x507000, v120
	v_cvt_pk_bf16_f32 v64, v72, v74
	v_cvt_pk_bf16_f32 v65, v76, v79
	v_cvt_pk_bf16_f32 v66, v73, v75
	v_cvt_pk_bf16_f32 v67, v77, v78
	s_nop 1
	v_addc_co_u32_e32 v69, vcc, 0, v121, vcc
	global_store_dwordx4 v[68:69], v[64:67], off nt

; __device__ __forceinline__ unsigned pk_bf16(float lo, float hi) { unsigned r; asm("v_cvt_pk_bf16_f32 %0, %1, %2" : "=v"(r) : "v"(lo), "v"(hi)); return r; }
; __device__ __forceinline__ float sigm(float x) { return __builtin_amdgcn_rcpf(1.f + __expf(-x)); }
;     __device__ __forceinline__ void operator()(f32x4 (&acc)[2][2][4][2], const Unit& u, int wr, int wc, int fr, int fq) const {
;     ...
;             const int colb = u.pn * 256 + bj * 128;
;             if (colb >= NIN) continue;
;             const int act = colb >= OFF_MERGE ? 2 : (colb >= OFF_GATE ? 1 : 0);
;             u16* pb = proj + (size_t)(u.pm * 256 + wr * 64 + fr) * NIN + colb + wc * 32 + 8 * fq;
; #pragma unroll
;             for (int ai = 0; ai < 2; ++ai)
; #pragma unroll
;                 for (int m = 0; m < 4; ++m) {
;                     f32x4 v0 = acc[ai][bj][m][0], v1 = acc[ai][bj][m][1];
;                     if (act == 1) {
; #pragma unroll
;                         for (int j = 0; j < 4; ++j) { v0[j] = v0[j] * sigm(v0[j]); v1[j] = v1[j] * sigm(v1[j]); }
;                     } else if (act == 2) {
; #pragma unroll
;                         for (int j = 0; j < 4; ++j) { v0[j] = sigm(v0[j]); v1[j] = sigm(v1[j]); }
;                     }
;                     u32x4 w; w.x = pk_bf16(v0[0], v0[1]); w.y = pk_bf16(v0[2], v0[3]); w.z = pk_bf16(v1[0], v1[1]); w.w = pk_bf16(v1[2], v1[3]);
;                     *(u32x4*)(pb + (size_t)(ai * 128 + m * 16) * NIN) = w;
.LBB0_159:
	v_readlane_b32 s28, v252, 40
	v_readlane_b32 s29, v252, 41
	v_lshl_add_u32 v58, s62, 8, v139
	s_ashr_i32 s67, s66, 31
	v_mov_b64_e32 v[56:57], s[28:29]
	v_mad_i64_i32 v[56:57], s[28:29], v58, s23, v[56:57]
	v_lshl_add_u64 v[56:57], s[66:67], 1, v[56:57]
	s_lshl_b32 s2, s18, 1
	v_lshl_add_u64 v[56:57], v[56:57], 0, s[2:3]
	v_lshlrev_b32_e32 v136, 1, v138
	v_lshl_add_u64 v[62:63], v[56:57], 0, v[136:137]
	s_mov_b64 s[28:29], 0x100
	v_lshl_add_u64 v[56:57], v[62:63], 0, s[28:29]
	v_cvt_pk_bf16_f32 v58, v64, v66
	v_cvt_pk_bf16_f32 v59, v68, v71
	v_cvt_pk_bf16_f32 v60, v65, v67
	v_cvt_pk_bf16_f32 v61, v69, v70
	s_cmp_gt_i32 s11, 1
	s_mov_b64 s[62:63], -1
	global_store_dwordx4 v[62:63], v[58:61], off offset:256 nt
	s_cbranch_scc0 .LBB0_161
	v_mul_f32_e32 v64, 0xbfb8aa3b, v55
	v_mul_f32_e32 v58, 0xbfb8aa3b, v52
	v_mul_f32_e32 v59, 0xbfb8aa3b, v48
	v_mul_f32_e32 v60, 0xbfb8aa3b, v53
	v_mul_f32_e32 v61, 0xbfb8aa3b, v49
	v_mul_f32_e32 v62, 0xbfb8aa3b, v54
	v_mul_f32_e32 v63, 0xbfb8aa3b, v50
	v_exp_f32_e32 v64, v64
	v_mul_f32_e32 v65, 0xbfb8aa3b, v51
	v_exp_f32_e32 v58, v58
	v_exp_f32_e32 v59, v59
	v_exp_f32_e32 v60, v60
	v_exp_f32_e32 v61, v61
	v_exp_f32_e32 v62, v62
	v_exp_f32_e32 v63, v63
	v_exp_f32_e32 v66, v65
	v_add_f32_e32 v64, 1.0, v64
	v_add_f32_e32 v58, 1.0, v58
	v_add_f32_e32 v59, 1.0, v59
	v_add_f32_e32 v60, 1.0, v60
	v_add_f32_e32 v61, 1.0, v61
	v_add_f32_e32 v62, 1.0, v62
	v_add_f32_e32 v63, 1.0, v63
	v_rcp_f32_e32 v65, v64
	v_add_f32_e32 v64, 1.0, v66
	v_rcp_f32_e32 v58, v58
	v_rcp_f32_e32 v59, v59
	v_rcp_f32_e32 v60, v60
	v_rcp_f32_e32 v61, v61
	v_rcp_f32_e32 v62, v62
	v_rcp_f32_e32 v63, v63
	v_rcp_f32_e32 v64, v64
	s_mov_b64 s[62:63], 0

; __device__ __forceinline__ unsigned pk_bf16(float lo, float hi) { unsigned r; asm("v_cvt_pk_bf16_f32 %0, %1, %2" : "=v"(r) : "v"(lo), "v"(hi)); return r; }
; __device__ __forceinline__ float sigm(float x) { return __builtin_amdgcn_rcpf(1.f + __expf(-x)); }
;     __device__ __forceinline__ void operator()(f32x4 (&acc)[2][2][4][2], const Unit& u, int wr, int wc, int fr, int fq) const {
;     ...
;                     f32x4 v0 = acc[ai][bj][m][0], v1 = acc[ai][bj][m][1];
;                     if (act == 1) {
; #pragma unroll
;                         for (int j = 0; j < 4; ++j) { v0[j] = v0[j] * sigm(v0[j]); v1[j] = v1[j] * sigm(v1[j]); }
;                     } else if (act == 2) {
; #pragma unroll
;                         for (int j = 0; j < 4; ++j) { v0[j] = sigm(v0[j]); v1[j] = sigm(v1[j]); }
;                     }
;                     u32x4 w; w.x = pk_bf16(v0[0], v0[1]); w.y = pk_bf16(v0[2], v0[3]); w.z = pk_bf16(v1[0], v1[1]); w.w = pk_bf16(v1[2], v1[3]);
;                     *(u32x4*)(pb + (size_t)(ai * 128 + m * 16) * NIN) = w;
.LBB0_165:
	v_add_co_u32_e32 v52, vcc, 0x75000, v56
	v_cvt_pk_bf16_f32 v48, v58, v60
	v_cvt_pk_bf16_f32 v49, v62, v65
	v_cvt_pk_bf16_f32 v50, v59, v61
	v_cvt_pk_bf16_f32 v51, v63, v64
	s_nop 1
	v_addc_co_u32_e32 v53, vcc, 0, v57, vcc
	s_cmp_gt_i32 s11, 1
	s_mov_b64 s[62:63], -1
	global_store_dwordx4 v[52:53], v[48:51], off nt
	s_cbranch_scc0 .LBB0_167
	v_mul_f32_e32 v54, 0xbfb8aa3b, v47
	v_mul_f32_e32 v48, 0xbfb8aa3b, v44
	v_mul_f32_e32 v49, 0xbfb8aa3b, v40
	v_mul_f32_e32 v50, 0xbfb8aa3b, v45
	v_mul_f32_e32 v51, 0xbfb8aa3b, v41
	v_mul_f32_e32 v52, 0xbfb8aa3b, v46
	v_mul_f32_e32 v53, 0xbfb8aa3b, v42
	v_exp_f32_e32 v54, v54
	v_mul_f32_e32 v55, 0xbfb8aa3b, v43
	v_exp_f32_e32 v48, v48
	v_exp_f32_e32 v49, v49
	v_exp_f32_e32 v50, v50
	v_exp_f32_e32 v51, v51
	v_exp_f32_e32 v52, v52
	v_exp_f32_e32 v53, v53
	v_exp_f32_e32 v58, v55
	v_add_f32_e32 v54, 1.0, v54
	v_add_f32_e32 v48, 1.0, v48
	v_add_f32_e32 v49, 1.0, v49
	v_add_f32_e32 v50, 1.0, v50
	v_add_f32_e32 v51, 1.0, v51
	v_add_f32_e32 v52, 1.0, v52
	v_add_f32_e32 v53, 1.0, v53
	v_rcp_f32_e32 v55, v54
	v_add_f32_e32 v54, 1.0, v58
	v_rcp_f32_e32 v48, v48
	v_rcp_f32_e32 v49, v49
	v_rcp_f32_e32 v50, v50
	v_rcp_f32_e32 v51, v51
	v_rcp_f32_e32 v52, v52
	v_rcp_f32_e32 v53, v53
	v_rcp_f32_e32 v54, v54
	s_mov_b64 s[62:63], 0

; __device__ __forceinline__ unsigned pk_bf16(float lo, float hi) { unsigned r; asm("v_cvt_pk_bf16_f32 %0, %1, %2" : "=v"(r) : "v"(lo), "v"(hi)); return r; }
; __device__ __forceinline__ float sigm(float x) { return __builtin_amdgcn_rcpf(1.f + __expf(-x)); }
;     __device__ __forceinline__ void operator()(f32x4 (&acc)[2][2][4][2], const Unit& u, int wr, int wc, int fr, int fq) const {
;     ...
;                     f32x4 v0 = acc[ai][bj][m][0], v1 = acc[ai][bj][m][1];
;                     if (act == 1) {
; #pragma unroll
;                         for (int j = 0; j < 4; ++j) { v0[j] = v0[j] * sigm(v0[j]); v1[j] = v1[j] * sigm(v1[j]); }
;                     } else if (act == 2) {
; #pragma unroll
;                         for (int j = 0; j < 4; ++j) { v0[j] = sigm(v0[j]); v1[j] = sigm(v1[j]); }
;                     }
;                     u32x4 w; w.x = pk_bf16(v0[0], v0[1]); w.y = pk_bf16(v0[2], v0[3]); w.z = pk_bf16(v1[0], v1[1]); w.w = pk_bf16(v1[2], v1[3]);
;                     *(u32x4*)(pb + (size_t)(ai * 128 + m * 16) * NIN) = w;
.LBB0_171:
	v_add_co_u32_e32 v44, vcc, 0xea000, v56
	v_cvt_pk_bf16_f32 v40, v48, v50
	v_cvt_pk_bf16_f32 v41, v52, v55
	v_cvt_pk_bf16_f32 v42, v49, v51
	v_cvt_pk_bf16_f32 v43, v53, v54
	s_nop 1
	v_addc_co_u32_e32 v45, vcc, 0, v57, vcc
	s_cmp_gt_i32 s11, 1
	s_mov_b64 s[62:63], -1
	global_store_dwordx4 v[44:45], v[40:43], off nt
	s_cbranch_scc0 .LBB0_173
	v_mul_f32_e32 v46, 0xbfb8aa3b, v39
	v_mul_f32_e32 v40, 0xbfb8aa3b, v36
	v_mul_f32_e32 v41, 0xbfb8aa3b, v32
	v_mul_f32_e32 v42, 0xbfb8aa3b, v37
	v_mul_f32_e32 v43, 0xbfb8aa3b, v33
	v_mul_f32_e32 v44, 0xbfb8aa3b, v38
	v_mul_f32_e32 v45, 0xbfb8aa3b, v34
	v_exp_f32_e32 v46, v46
	v_mul_f32_e32 v47, 0xbfb8aa3b, v35
	v_exp_f32_e32 v40, v40
	v_exp_f32_e32 v41, v41
	v_exp_f32_e32 v42, v42
	v_exp_f32_e32 v43, v43
	v_exp_f32_e32 v44, v44
	v_exp_f32_e32 v45, v45
	v_exp_f32_e32 v48, v47
	v_add_f32_e32 v46, 1.0, v46
	v_add_f32_e32 v40, 1.0, v40
	v_add_f32_e32 v41, 1.0, v41
	v_add_f32_e32 v42, 1.0, v42
	v_add_f32_e32 v43, 1.0, v43
	v_add_f32_e32 v44, 1.0, v44
	v_add_f32_e32 v45, 1.0, v45
	v_rcp_f32_e32 v47, v46
	v_add_f32_e32 v46, 1.0, v48
	v_rcp_f32_e32 v40, v40
	v_rcp_f32_e32 v41, v41
	v_rcp_f32_e32 v42, v42
	v_rcp_f32_e32 v43, v43
	v_rcp_f32_e32 v44, v44
	v_rcp_f32_e32 v45, v45
	v_rcp_f32_e32 v46, v46
	s_mov_b64 s[62:63], 0

; __device__ __forceinline__ unsigned pk_bf16(float lo, float hi) { unsigned r; asm("v_cvt_pk_bf16_f32 %0, %1, %2" : "=v"(r) : "v"(lo), "v"(hi)); return r; }
; __device__ __forceinline__ float sigm(float x) { return __builtin_amdgcn_rcpf(1.f + __expf(-x)); }
;     __device__ __forceinline__ void operator()(f32x4 (&acc)[2][2][4][2], const Unit& u, int wr, int wc, int fr, int fq) const {
;     ...
;                     f32x4 v0 = acc[ai][bj][m][0], v1 = acc[ai][bj][m][1];
;                     if (act == 1) {
; #pragma unroll
;                         for (int j = 0; j < 4; ++j) { v0[j] = v0[j] * sigm(v0[j]); v1[j] = v1[j] * sigm(v1[j]); }
;                     } else if (act == 2) {
; #pragma unroll
;                         for (int j = 0; j < 4; ++j) { v0[j] = sigm(v0[j]); v1[j] = sigm(v1[j]); }
;                     }
;                     u32x4 w; w.x = pk_bf16(v0[0], v0[1]); w.y = pk_bf16(v0[2], v0[3]); w.z = pk_bf16(v1[0], v1[1]); w.w = pk_bf16(v1[2], v1[3]);
;                     *(u32x4*)(pb + (size_t)(ai * 128 + m * 16) * NIN) = w;
.LBB0_177:
	v_add_co_u32_e32 v36, vcc, 0x15f000, v56
	v_cvt_pk_bf16_f32 v32, v40, v42
	v_cvt_pk_bf16_f32 v33, v44, v47
	v_cvt_pk_bf16_f32 v34, v41, v43
	v_cvt_pk_bf16_f32 v35, v45, v46
	s_nop 1
	v_addc_co_u32_e32 v37, vcc, 0, v57, vcc
	s_cmp_gt_i32 s11, 1
	s_mov_b64 s[62:63], -1
	global_store_dwordx4 v[36:37], v[32:35], off nt
	s_cbranch_scc0 .LBB0_179
	v_mul_f32_e32 v38, 0xbfb8aa3b, v31
	v_mul_f32_e32 v32, 0xbfb8aa3b, v28
	v_mul_f32_e32 v33, 0xbfb8aa3b, v24
	v_mul_f32_e32 v34, 0xbfb8aa3b, v29
	v_mul_f32_e32 v35, 0xbfb8aa3b, v25
	v_mul_f32_e32 v36, 0xbfb8aa3b, v30
	v_mul_f32_e32 v37, 0xbfb8aa3b, v26
	v_exp_f32_e32 v38, v38
	v_mul_f32_e32 v39, 0xbfb8aa3b, v27
	v_exp_f32_e32 v32, v32
	v_exp_f32_e32 v33, v33
	v_exp_f32_e32 v34, v34
	v_exp_f32_e32 v35, v35
	v_exp_f32_e32 v36, v36
	v_exp_f32_e32 v37, v37
	v_exp_f32_e32 v40, v39
	v_add_f32_e32 v38, 1.0, v38
	v_add_f32_e32 v32, 1.0, v32
	v_add_f32_e32 v33, 1.0, v33
	v_add_f32_e32 v34, 1.0, v34
	v_add_f32_e32 v35, 1.0, v35
	v_add_f32_e32 v36, 1.0, v36
	v_add_f32_e32 v37, 1.0, v37
	v_rcp_f32_e32 v39, v38
	v_add_f32_e32 v38, 1.0, v40
	v_rcp_f32_e32 v32, v32
	v_rcp_f32_e32 v33, v33
	v_rcp_f32_e32 v34, v34
	v_rcp_f32_e32 v35, v35
	v_rcp_f32_e32 v36, v36
	v_rcp_f32_e32 v37, v37
	v_rcp_f32_e32 v38, v38
	s_mov_b64 s[62:63], 0

; __device__ __forceinline__ unsigned pk_bf16(float lo, float hi) { unsigned r; asm("v_cvt_pk_bf16_f32 %0, %1, %2" : "=v"(r) : "v"(lo), "v"(hi)); return r; }
; __device__ __forceinline__ float sigm(float x) { return __builtin_amdgcn_rcpf(1.f + __expf(-x)); }
;     __device__ __forceinline__ void operator()(f32x4 (&acc)[2][2][4][2], const Unit& u, int wr, int wc, int fr, int fq) const {
;     ...
;                     f32x4 v0 = acc[ai][bj][m][0], v1 = acc[ai][bj][m][1];
;                     if (act == 1) {
; #pragma unroll
;                         for (int j = 0; j < 4; ++j) { v0[j] = v0[j] * sigm(v0[j]); v1[j] = v1[j] * sigm(v1[j]); }
;                     } else if (act == 2) {
; #pragma unroll
;                         for (int j = 0; j < 4; ++j) { v0[j] = sigm(v0[j]); v1[j] = sigm(v1[j]); }
;                     }
;                     u32x4 w; w.x = pk_bf16(v0[0], v0[1]); w.y = pk_bf16(v0[2], v0[3]); w.z = pk_bf16(v1[0], v1[1]); w.w = pk_bf16(v1[2], v1[3]);
;                     *(u32x4*)(pb + (size_t)(ai * 128 + m * 16) * NIN) = w;
.LBB0_183:
	v_add_co_u32_e32 v28, vcc, 0x3a8000, v56
	v_cvt_pk_bf16_f32 v24, v32, v34
	v_cvt_pk_bf16_f32 v25, v36, v39
	v_cvt_pk_bf16_f32 v26, v33, v35
	v_cvt_pk_bf16_f32 v27, v37, v38
	s_nop 1
	v_addc_co_u32_e32 v29, vcc, 0, v57, vcc
	s_cmp_gt_i32 s11, 1
	s_mov_b64 s[62:63], -1
	global_store_dwordx4 v[28:29], v[24:27], off nt
	s_cbranch_scc0 .LBB0_185
	v_mul_f32_e32 v30, 0xbfb8aa3b, v23
	v_mul_f32_e32 v24, 0xbfb8aa3b, v20
	v_mul_f32_e32 v25, 0xbfb8aa3b, v16
	v_mul_f32_e32 v26, 0xbfb8aa3b, v21
	v_mul_f32_e32 v27, 0xbfb8aa3b, v17
	v_mul_f32_e32 v28, 0xbfb8aa3b, v22
	v_mul_f32_e32 v29, 0xbfb8aa3b, v18
	v_exp_f32_e32 v30, v30
	v_mul_f32_e32 v31, 0xbfb8aa3b, v19
	v_exp_f32_e32 v24, v24
	v_exp_f32_e32 v25, v25
	v_exp_f32_e32 v26, v26
	v_exp_f32_e32 v27, v27
	v_exp_f32_e32 v28, v28
	v_exp_f32_e32 v29, v29
	v_exp_f32_e32 v32, v31
	v_add_f32_e32 v30, 1.0, v30
	v_add_f32_e32 v24, 1.0, v24
	v_add_f32_e32 v25, 1.0, v25
	v_add_f32_e32 v26, 1.0, v26
	v_add_f32_e32 v27, 1.0, v27
	v_add_f32_e32 v28, 1.0, v28
	v_add_f32_e32 v29, 1.0, v29
	v_rcp_f32_e32 v31, v30
	v_add_f32_e32 v30, 1.0, v32
	v_rcp_f32_e32 v24, v24
	v_rcp_f32_e32 v25, v25
	v_rcp_f32_e32 v26, v26
	v_rcp_f32_e32 v27, v27
	v_rcp_f32_e32 v28, v28
	v_rcp_f32_e32 v29, v29
	v_rcp_f32_e32 v30, v30
	s_mov_b64 s[62:63], 0

; __device__ __forceinline__ unsigned pk_bf16(float lo, float hi) { unsigned r; asm("v_cvt_pk_bf16_f32 %0, %1, %2" : "=v"(r) : "v"(lo), "v"(hi)); return r; }
; __device__ __forceinline__ float sigm(float x) { return __builtin_amdgcn_rcpf(1.f + __expf(-x)); }
;     __device__ __forceinline__ void operator()(f32x4 (&acc)[2][2][4][2], const Unit& u, int wr, int wc, int fr, int fq) const {
;     ...
;                     f32x4 v0 = acc[ai][bj][m][0], v1 = acc[ai][bj][m][1];
;                     if (act == 1) {
; #pragma unroll
;                         for (int j = 0; j < 4; ++j) { v0[j] = v0[j] * sigm(v0[j]); v1[j] = v1[j] * sigm(v1[j]); }
;                     } else if (act == 2) {
; #pragma unroll
;                         for (int j = 0; j < 4; ++j) { v0[j] = sigm(v0[j]); v1[j] = sigm(v1[j]); }
;                     }
;                     u32x4 w; w.x = pk_bf16(v0[0], v0[1]); w.y = pk_bf16(v0[2], v0[3]); w.z = pk_bf16(v1[0], v1[1]); w.w = pk_bf16(v1[2], v1[3]);
;                     *(u32x4*)(pb + (size_t)(ai * 128 + m * 16) * NIN) = w;
.LBB0_189:
	v_add_co_u32_e32 v20, vcc, 0x41d000, v56
	v_cvt_pk_bf16_f32 v16, v24, v26
	v_cvt_pk_bf16_f32 v17, v28, v31
	v_cvt_pk_bf16_f32 v18, v25, v27
	v_cvt_pk_bf16_f32 v19, v29, v30
	s_nop 1
	v_addc_co_u32_e32 v21, vcc, 0, v57, vcc
	s_cmp_gt_i32 s11, 1
	s_mov_b64 s[62:63], -1
	global_store_dwordx4 v[20:21], v[16:19], off nt
	s_cbranch_scc0 .LBB0_191
	v_mul_f32_e32 v22, 0xbfb8aa3b, v15
	v_mul_f32_e32 v16, 0xbfb8aa3b, v12
	v_mul_f32_e32 v17, 0xbfb8aa3b, v8
	v_mul_f32_e32 v18, 0xbfb8aa3b, v13
	v_mul_f32_e32 v19, 0xbfb8aa3b, v9
	v_mul_f32_e32 v20, 0xbfb8aa3b, v14
	v_mul_f32_e32 v21, 0xbfb8aa3b, v10
	v_exp_f32_e32 v22, v22
	v_mul_f32_e32 v23, 0xbfb8aa3b, v11
	v_exp_f32_e32 v16, v16
	v_exp_f32_e32 v17, v17
	v_exp_f32_e32 v18, v18
	v_exp_f32_e32 v19, v19
	v_exp_f32_e32 v20, v20
	v_exp_f32_e32 v21, v21
	v_exp_f32_e32 v24, v23
	v_add_f32_e32 v22, 1.0, v22
	v_add_f32_e32 v16, 1.0, v16
	v_add_f32_e32 v17, 1.0, v17
	v_add_f32_e32 v18, 1.0, v18
	v_add_f32_e32 v19, 1.0, v19
	v_add_f32_e32 v20, 1.0, v20
	v_add_f32_e32 v21, 1.0, v21
	v_rcp_f32_e32 v23, v22
	v_add_f32_e32 v22, 1.0, v24
	v_rcp_f32_e32 v16, v16
	v_rcp_f32_e32 v17, v17
	v_rcp_f32_e32 v18, v18
	v_rcp_f32_e32 v19, v19
	v_rcp_f32_e32 v20, v20
	v_rcp_f32_e32 v21, v21
	v_rcp_f32_e32 v22, v22
	s_mov_b64 s[62:63], 0

; __device__ __forceinline__ unsigned pk_bf16(float lo, float hi) { unsigned r; asm("v_cvt_pk_bf16_f32 %0, %1, %2" : "=v"(r) : "v"(lo), "v"(hi)); return r; }
; __device__ __forceinline__ float sigm(float x) { return __builtin_amdgcn_rcpf(1.f + __expf(-x)); }
;     __device__ __forceinline__ void operator()(f32x4 (&acc)[2][2][4][2], const Unit& u, int wr, int wc, int fr, int fq) const {
;     ...
;                     f32x4 v0 = acc[ai][bj][m][0], v1 = acc[ai][bj][m][1];
;                     if (act == 1) {
; #pragma unroll
;                         for (int j = 0; j < 4; ++j) { v0[j] = v0[j] * sigm(v0[j]); v1[j] = v1[j] * sigm(v1[j]); }
;                     } else if (act == 2) {
; #pragma unroll
;                         for (int j = 0; j < 4; ++j) { v0[j] = sigm(v0[j]); v1[j] = sigm(v1[j]); }
;                     }
;                     u32x4 w; w.x = pk_bf16(v0[0], v0[1]); w.y = pk_bf16(v0[2], v0[3]); w.z = pk_bf16(v1[0], v1[1]); w.w = pk_bf16(v1[2], v1[3]);
;                     *(u32x4*)(pb + (size_t)(ai * 128 + m * 16) * NIN) = w;
.LBB0_195:
	v_add_co_u32_e32 v12, vcc, 0x492000, v56
	v_cvt_pk_bf16_f32 v8, v16, v18
	v_cvt_pk_bf16_f32 v9, v20, v23
	v_cvt_pk_bf16_f32 v10, v17, v19
	v_cvt_pk_bf16_f32 v11, v21, v22
	s_nop 1
	v_addc_co_u32_e32 v13, vcc, 0, v57, vcc
	s_cmp_gt_i32 s11, 1
	s_mov_b64 s[62:63], -1
	global_store_dwordx4 v[12:13], v[8:11], off nt
	s_cbranch_scc0 .LBB0_197
	v_mul_f32_e32 v14, 0xbfb8aa3b, v7
	v_mul_f32_e32 v8, 0xbfb8aa3b, v4
	v_mul_f32_e32 v9, 0xbfb8aa3b, v0
	v_mul_f32_e32 v10, 0xbfb8aa3b, v5
	v_mul_f32_e32 v11, 0xbfb8aa3b, v1
	v_mul_f32_e32 v12, 0xbfb8aa3b, v6
	v_mul_f32_e32 v13, 0xbfb8aa3b, v2
	v_exp_f32_e32 v14, v14
	v_mul_f32_e32 v15, 0xbfb8aa3b, v3
	v_exp_f32_e32 v8, v8
	v_exp_f32_e32 v9, v9
	v_exp_f32_e32 v10, v10
	v_exp_f32_e32 v11, v11
	v_exp_f32_e32 v12, v12
	v_exp_f32_e32 v13, v13
	v_exp_f32_e32 v16, v15
	v_add_f32_e32 v14, 1.0, v14
	v_add_f32_e32 v8, 1.0, v8
	v_add_f32_e32 v9, 1.0, v9
	v_add_f32_e32 v10, 1.0, v10
	v_add_f32_e32 v11, 1.0, v11
	v_add_f32_e32 v12, 1.0, v12
	v_add_f32_e32 v13, 1.0, v13
	v_rcp_f32_e32 v15, v14
	v_add_f32_e32 v14, 1.0, v16
	v_rcp_f32_e32 v8, v8
	v_rcp_f32_e32 v9, v9
	v_rcp_f32_e32 v10, v10
	v_rcp_f32_e32 v11, v11
	v_rcp_f32_e32 v12, v12
	v_rcp_f32_e32 v13, v13
	v_rcp_f32_e32 v14, v14
	s_mov_b64 s[62:63], 0

; __device__ __forceinline__ unsigned pk_bf16(float lo, float hi) { unsigned r; asm("v_cvt_pk_bf16_f32 %0, %1, %2" : "=v"(r) : "v"(lo), "v"(hi)); return r; }
; __device__ __forceinline__ float sigm(float x) { return __builtin_amdgcn_rcpf(1.f + __expf(-x)); }
;     __device__ __forceinline__ void operator()(f32x4 (&acc)[2][2][4][2], const Unit& u, int wr, int wc, int fr, int fq) const {
;     ...
;             const int colb = u.pn * 256 + bj * 128;
;             if (colb >= NIN) continue;
;             const int act = colb >= OFF_MERGE ? 2 : (colb >= OFF_GATE ? 1 : 0);
;             u16* pb = proj + (size_t)(u.pm * 256 + wr * 64 + fr) * NIN + colb + wc * 32 + 8 * fq;
; #pragma unroll
;             for (int ai = 0; ai < 2; ++ai)
; #pragma unroll
;                 for (int m = 0; m < 4; ++m) {
;                     f32x4 v0 = acc[ai][bj][m][0], v1 = acc[ai][bj][m][1];
;                     if (act == 1) {
; #pragma unroll
;                         for (int j = 0; j < 4; ++j) { v0[j] = v0[j] * sigm(v0[j]); v1[j] = v1[j] * sigm(v1[j]); }
;                     } else if (act == 2) {
; #pragma unroll
;                         for (int j = 0; j < 4; ++j) { v0[j] = sigm(v0[j]); v1[j] = sigm(v1[j]); }
;                     }
;                     u32x4 w; w.x = pk_bf16(v0[0], v0[1]); w.y = pk_bf16(v0[2], v0[3]); w.z = pk_bf16(v1[0], v1[1]); w.w = pk_bf16(v1[2], v1[3]);
;                     *(u32x4*)(pb + (size_t)(ai * 128 + m * 16) * NIN) = w;
.LBB0_1296:
	v_readlane_b32 s28, v252, 40
	v_readlane_b32 s29, v252, 41
	v_lshl_add_u32 v136, s6, 8, v139
	s_ashr_i32 s87, s86, 31
	v_mov_b64_e32 v[144:145], s[28:29]
	v_mad_i64_i32 v[144:145], s[28:29], v136, s21, v[144:145]
	v_lshl_add_u64 v[144:145], s[86:87], 1, v[144:145]
	s_lshl_b32 s10, s16, 1
	v_lshl_add_u64 v[144:145], v[144:145], 0, s[10:11]
	v_lshlrev_b32_e32 v136, 1, v138
	v_lshl_add_u64 v[144:145], v[144:145], 0, v[136:137]
	v_cvt_pk_bf16_f32 v146, v146, v147
	v_cvt_pk_bf16_f32 v147, v150, v151
	v_cvt_pk_bf16_f32 v148, v148, v149
	v_cvt_pk_bf16_f32 v149, v152, v153
	s_cmp_gt_i32 s27, 1
	s_mov_b64 s[88:89], -1
	global_store_dwordx4 v[144:145], v[146:149], off nt
	s_cbranch_scc0 .LBB0_1298
	v_mul_f32_e32 v136, 0xbfb8aa3b, v116
	v_exp_f32_e32 v136, v136
	v_mul_f32_e32 v146, 0xbfb8aa3b, v112
	v_exp_f32_e32 v146, v146
	v_mul_f32_e32 v148, 0xbfb8aa3b, v113
	v_add_f32_e32 v136, 1.0, v136
	v_exp_f32_e32 v149, v148
	v_add_f32_e32 v147, 1.0, v146
	v_rcp_f32_e32 v146, v136
	v_mul_f32_e32 v136, 0xbfb8aa3b, v117
	v_exp_f32_e32 v136, v136
	v_rcp_f32_e32 v148, v147
	v_mul_f32_e32 v152, 0xbfb8aa3b, v115
	v_exp_f32_e32 v153, v152
	v_add_f32_e32 v136, 1.0, v136
	v_rcp_f32_e32 v147, v136
	v_add_f32_e32 v136, 1.0, v149
	v_mul_f32_e32 v149, 0xbfb8aa3b, v118
	v_exp_f32_e32 v150, v149
	v_mul_f32_e32 v149, 0xbfb8aa3b, v114
	v_exp_f32_e32 v151, v149
	v_rcp_f32_e32 v149, v136
	v_add_f32_e32 v136, 1.0, v150
	v_rcp_f32_e32 v150, v136
	v_add_f32_e32 v136, 1.0, v151
	v_mul_f32_e32 v151, 0xbfb8aa3b, v119
	v_exp_f32_e32 v151, v151
	v_rcp_f32_e32 v152, v136
	s_mov_b64 s[88:89], 0
	v_add_f32_e32 v136, 1.0, v151
	v_rcp_f32_e32 v151, v136
	v_add_f32_e32 v136, 1.0, v153
	v_rcp_f32_e32 v153, v136

; __device__ __forceinline__ unsigned pk_bf16(float lo, float hi) { unsigned r; asm("v_cvt_pk_bf16_f32 %0, %1, %2" : "=v"(r) : "v"(lo), "v"(hi)); return r; }
; __device__ __forceinline__ float sigm(float x) { return __builtin_amdgcn_rcpf(1.f + __expf(-x)); }
;     __device__ __forceinline__ void operator()(f32x4 (&acc)[2][2][4][2], const Unit& u, int wr, int wc, int fr, int fq) const {
;     ...
;                     f32x4 v0 = acc[ai][bj][m][0], v1 = acc[ai][bj][m][1];
;                     if (act == 1) {
; #pragma unroll
;                         for (int j = 0; j < 4; ++j) { v0[j] = v0[j] * sigm(v0[j]); v1[j] = v1[j] * sigm(v1[j]); }
;                     } else if (act == 2) {
; #pragma unroll
;                         for (int j = 0; j < 4; ++j) { v0[j] = sigm(v0[j]); v1[j] = sigm(v1[j]); }
;                     }
;                     u32x4 w; w.x = pk_bf16(v0[0], v0[1]); w.y = pk_bf16(v0[2], v0[3]); w.z = pk_bf16(v1[0], v1[1]); w.w = pk_bf16(v1[2], v1[3]);
;                     *(u32x4*)(pb + (size_t)(ai * 128 + m * 16) * NIN) = w;
.LBB0_1301:
	v_cvt_pk_bf16_f32 v146, v146, v147
	v_cvt_pk_bf16_f32 v147, v150, v151
	v_add_co_u32_e32 v150, vcc, 0x75000, v144
	v_cvt_pk_bf16_f32 v148, v148, v149
	v_cvt_pk_bf16_f32 v149, v152, v153
	s_cmp_gt_i32 s27, 1
	s_nop 0
	v_addc_co_u32_e32 v151, vcc, 0, v145, vcc
	s_mov_b64 s[88:89], -1
	global_store_dwordx4 v[150:151], v[146:149], off nt
	s_cbranch_scc0 .LBB0_1303
	v_mul_f32_e32 v136, 0xbfb8aa3b, v108
	v_exp_f32_e32 v136, v136
	v_mul_f32_e32 v146, 0xbfb8aa3b, v104
	v_exp_f32_e32 v146, v146
	v_mul_f32_e32 v148, 0xbfb8aa3b, v105
	v_add_f32_e32 v136, 1.0, v136
	v_exp_f32_e32 v149, v148
	v_add_f32_e32 v147, 1.0, v146
	v_rcp_f32_e32 v146, v136
	v_mul_f32_e32 v136, 0xbfb8aa3b, v109
	v_exp_f32_e32 v136, v136
	v_rcp_f32_e32 v148, v147
	v_mul_f32_e32 v152, 0xbfb8aa3b, v107
	v_exp_f32_e32 v153, v152
	v_add_f32_e32 v136, 1.0, v136
	v_rcp_f32_e32 v147, v136
	v_add_f32_e32 v136, 1.0, v149
	v_mul_f32_e32 v149, 0xbfb8aa3b, v110
	v_exp_f32_e32 v150, v149
	v_mul_f32_e32 v149, 0xbfb8aa3b, v106
	v_exp_f32_e32 v151, v149
	v_rcp_f32_e32 v149, v136
	v_add_f32_e32 v136, 1.0, v150
	v_rcp_f32_e32 v150, v136
	v_add_f32_e32 v136, 1.0, v151
	v_mul_f32_e32 v151, 0xbfb8aa3b, v111
	v_exp_f32_e32 v151, v151
	v_rcp_f32_e32 v152, v136
	s_mov_b64 s[88:89], 0
	v_add_f32_e32 v136, 1.0, v151
	v_rcp_f32_e32 v151, v136
	v_add_f32_e32 v136, 1.0, v153
	v_rcp_f32_e32 v153, v136

; __device__ __forceinline__ unsigned pk_bf16(float lo, float hi) { unsigned r; asm("v_cvt_pk_bf16_f32 %0, %1, %2" : "=v"(r) : "v"(lo), "v"(hi)); return r; }
; __device__ __forceinline__ float sigm(float x) { return __builtin_amdgcn_rcpf(1.f + __expf(-x)); }
;     __device__ __forceinline__ void operator()(f32x4 (&acc)[2][2][4][2], const Unit& u, int wr, int wc, int fr, int fq) const {
;     ...
;                     f32x4 v0 = acc[ai][bj][m][0], v1 = acc[ai][bj][m][1];
;                     if (act == 1) {
; #pragma unroll
;                         for (int j = 0; j < 4; ++j) { v0[j] = v0[j] * sigm(v0[j]); v1[j] = v1[j] * sigm(v1[j]); }
;                     } else if (act == 2) {
; #pragma unroll
;                         for (int j = 0; j < 4; ++j) { v0[j] = sigm(v0[j]); v1[j] = sigm(v1[j]); }
;                     }
;                     u32x4 w; w.x = pk_bf16(v0[0], v0[1]); w.y = pk_bf16(v0[2], v0[3]); w.z = pk_bf16(v1[0], v1[1]); w.w = pk_bf16(v1[2], v1[3]);
;                     *(u32x4*)(pb + (size_t)(ai * 128 + m * 16) * NIN) = w;
.LBB0_1306:
	v_cvt_pk_bf16_f32 v146, v146, v147
	v_cvt_pk_bf16_f32 v147, v150, v151
	v_add_co_u32_e32 v150, vcc, 0xea000, v144
	v_cvt_pk_bf16_f32 v148, v148, v149
	v_cvt_pk_bf16_f32 v149, v152, v153
	s_cmp_gt_i32 s27, 1
	s_nop 0
	v_addc_co_u32_e32 v151, vcc, 0, v145, vcc
	s_mov_b64 s[88:89], -1
	global_store_dwordx4 v[150:151], v[146:149], off nt
	s_cbranch_scc0 .LBB0_1308
	v_mul_f32_e32 v136, 0xbfb8aa3b, v100
	v_exp_f32_e32 v136, v136
	v_mul_f32_e32 v146, 0xbfb8aa3b, v96
	v_exp_f32_e32 v146, v146
	v_mul_f32_e32 v148, 0xbfb8aa3b, v97
	v_add_f32_e32 v136, 1.0, v136
	v_exp_f32_e32 v149, v148
	v_add_f32_e32 v147, 1.0, v146
	v_rcp_f32_e32 v146, v136
	v_mul_f32_e32 v136, 0xbfb8aa3b, v101
	v_exp_f32_e32 v136, v136
	v_rcp_f32_e32 v148, v147
	v_mul_f32_e32 v152, 0xbfb8aa3b, v99
	v_exp_f32_e32 v153, v152
	v_add_f32_e32 v136, 1.0, v136
	v_rcp_f32_e32 v147, v136
	v_add_f32_e32 v136, 1.0, v149
	v_mul_f32_e32 v149, 0xbfb8aa3b, v102
	v_exp_f32_e32 v150, v149
	v_mul_f32_e32 v149, 0xbfb8aa3b, v98
	v_exp_f32_e32 v151, v149
	v_rcp_f32_e32 v149, v136
	v_add_f32_e32 v136, 1.0, v150
	v_rcp_f32_e32 v150, v136
	v_add_f32_e32 v136, 1.0, v151
	v_mul_f32_e32 v151, 0xbfb8aa3b, v103
	v_exp_f32_e32 v151, v151
	v_rcp_f32_e32 v152, v136
	s_mov_b64 s[88:89], 0
	v_add_f32_e32 v136, 1.0, v151
	v_rcp_f32_e32 v151, v136
	v_add_f32_e32 v136, 1.0, v153
	v_rcp_f32_e32 v153, v136

; __device__ __forceinline__ unsigned pk_bf16(float lo, float hi) { unsigned r; asm("v_cvt_pk_bf16_f32 %0, %1, %2" : "=v"(r) : "v"(lo), "v"(hi)); return r; }
; __device__ __forceinline__ float sigm(float x) { return __builtin_amdgcn_rcpf(1.f + __expf(-x)); }
;     __device__ __forceinline__ void operator()(f32x4 (&acc)[2][2][4][2], const Unit& u, int wr, int wc, int fr, int fq) const {
;     ...
;                     f32x4 v0 = acc[ai][bj][m][0], v1 = acc[ai][bj][m][1];
;                     if (act == 1) {
; #pragma unroll
;                         for (int j = 0; j < 4; ++j) { v0[j] = v0[j] * sigm(v0[j]); v1[j] = v1[j] * sigm(v1[j]); }
;                     } else if (act == 2) {
; #pragma unroll
;                         for (int j = 0; j < 4; ++j) { v0[j] = sigm(v0[j]); v1[j] = sigm(v1[j]); }
;                     }
;                     u32x4 w; w.x = pk_bf16(v0[0], v0[1]); w.y = pk_bf16(v0[2], v0[3]); w.z = pk_bf16(v1[0], v1[1]); w.w = pk_bf16(v1[2], v1[3]);
;                     *(u32x4*)(pb + (size_t)(ai * 128 + m * 16) * NIN) = w;
.LBB0_1311:
	v_cvt_pk_bf16_f32 v146, v146, v147
	v_cvt_pk_bf16_f32 v147, v150, v151
	v_add_co_u32_e32 v150, vcc, 0x15f000, v144
	v_cvt_pk_bf16_f32 v148, v148, v149
	v_cvt_pk_bf16_f32 v149, v152, v153
	s_cmp_gt_i32 s27, 1
	s_nop 0
	v_addc_co_u32_e32 v151, vcc, 0, v145, vcc
	s_mov_b64 s[88:89], -1
	global_store_dwordx4 v[150:151], v[146:149], off nt
	s_cbranch_scc0 .LBB0_1313
	v_mul_f32_e32 v136, 0xbfb8aa3b, v60
	v_exp_f32_e32 v136, v136
	v_mul_f32_e32 v146, 0xbfb8aa3b, v56
	v_exp_f32_e32 v146, v146
	v_mul_f32_e32 v148, 0xbfb8aa3b, v57
	v_add_f32_e32 v136, 1.0, v136
	v_exp_f32_e32 v149, v148
	v_add_f32_e32 v147, 1.0, v146
	v_rcp_f32_e32 v146, v136
	v_mul_f32_e32 v136, 0xbfb8aa3b, v61
	v_exp_f32_e32 v136, v136
	v_rcp_f32_e32 v148, v147
	v_mul_f32_e32 v152, 0xbfb8aa3b, v59
	v_exp_f32_e32 v153, v152
	v_add_f32_e32 v136, 1.0, v136
	v_rcp_f32_e32 v147, v136
	v_add_f32_e32 v136, 1.0, v149
	v_mul_f32_e32 v149, 0xbfb8aa3b, v62
	v_exp_f32_e32 v150, v149
	v_mul_f32_e32 v149, 0xbfb8aa3b, v58
	v_exp_f32_e32 v151, v149
	v_rcp_f32_e32 v149, v136
	v_add_f32_e32 v136, 1.0, v150
	v_rcp_f32_e32 v150, v136
	v_add_f32_e32 v136, 1.0, v151
	v_mul_f32_e32 v151, 0xbfb8aa3b, v63
	v_exp_f32_e32 v151, v151
	v_rcp_f32_e32 v152, v136
	s_mov_b64 s[88:89], 0
	v_add_f32_e32 v136, 1.0, v151
	v_rcp_f32_e32 v151, v136
	v_add_f32_e32 v136, 1.0, v153
	v_rcp_f32_e32 v153, v136

; __device__ __forceinline__ unsigned pk_bf16(float lo, float hi) { unsigned r; asm("v_cvt_pk_bf16_f32 %0, %1, %2" : "=v"(r) : "v"(lo), "v"(hi)); return r; }
; __device__ __forceinline__ float sigm(float x) { return __builtin_amdgcn_rcpf(1.f + __expf(-x)); }
;     __device__ __forceinline__ void operator()(f32x4 (&acc)[2][2][4][2], const Unit& u, int wr, int wc, int fr, int fq) const {
;     ...
;                     f32x4 v0 = acc[ai][bj][m][0], v1 = acc[ai][bj][m][1];
;                     if (act == 1) {
; #pragma unroll
;                         for (int j = 0; j < 4; ++j) { v0[j] = v0[j] * sigm(v0[j]); v1[j] = v1[j] * sigm(v1[j]); }
;                     } else if (act == 2) {
; #pragma unroll
;                         for (int j = 0; j < 4; ++j) { v0[j] = sigm(v0[j]); v1[j] = sigm(v1[j]); }
;                     }
;                     u32x4 w; w.x = pk_bf16(v0[0], v0[1]); w.y = pk_bf16(v0[2], v0[3]); w.z = pk_bf16(v1[0], v1[1]); w.w = pk_bf16(v1[2], v1[3]);
;                     *(u32x4*)(pb + (size_t)(ai * 128 + m * 16) * NIN) = w;
.LBB0_1316:
	v_cvt_pk_bf16_f32 v146, v146, v147
	v_cvt_pk_bf16_f32 v147, v150, v151
	v_add_co_u32_e32 v150, vcc, 0x3a8000, v144
	v_cvt_pk_bf16_f32 v148, v148, v149
	v_cvt_pk_bf16_f32 v149, v152, v153
	s_cmp_gt_i32 s27, 1
	s_nop 0
	v_addc_co_u32_e32 v151, vcc, 0, v145, vcc
	s_mov_b64 s[88:89], -1
	global_store_dwordx4 v[150:151], v[146:149], off nt
	s_cbranch_scc0 .LBB0_1318
	v_mul_f32_e32 v136, 0xbfb8aa3b, v52
	v_exp_f32_e32 v136, v136
	v_mul_f32_e32 v146, 0xbfb8aa3b, v48
	v_exp_f32_e32 v146, v146
	v_mul_f32_e32 v148, 0xbfb8aa3b, v49
	v_add_f32_e32 v136, 1.0, v136
	v_exp_f32_e32 v149, v148
	v_add_f32_e32 v147, 1.0, v146
	v_rcp_f32_e32 v146, v136
	v_mul_f32_e32 v136, 0xbfb8aa3b, v53
	v_exp_f32_e32 v136, v136
	v_rcp_f32_e32 v148, v147
	v_mul_f32_e32 v152, 0xbfb8aa3b, v51
	v_exp_f32_e32 v153, v152
	v_add_f32_e32 v136, 1.0, v136
	v_rcp_f32_e32 v147, v136
	v_add_f32_e32 v136, 1.0, v149
	v_mul_f32_e32 v149, 0xbfb8aa3b, v54
	v_exp_f32_e32 v150, v149
	v_mul_f32_e32 v149, 0xbfb8aa3b, v50
	v_exp_f32_e32 v151, v149
	v_rcp_f32_e32 v149, v136
	v_add_f32_e32 v136, 1.0, v150
	v_rcp_f32_e32 v150, v136
	v_add_f32_e32 v136, 1.0, v151
	v_mul_f32_e32 v151, 0xbfb8aa3b, v55
	v_exp_f32_e32 v151, v151
	v_rcp_f32_e32 v152, v136
	s_mov_b64 s[88:89], 0
	v_add_f32_e32 v136, 1.0, v151
	v_rcp_f32_e32 v151, v136
	v_add_f32_e32 v136, 1.0, v153
	v_rcp_f32_e32 v153, v136

; __device__ __forceinline__ unsigned pk_bf16(float lo, float hi) { unsigned r; asm("v_cvt_pk_bf16_f32 %0, %1, %2" : "=v"(r) : "v"(lo), "v"(hi)); return r; }
; __device__ __forceinline__ float sigm(float x) { return __builtin_amdgcn_rcpf(1.f + __expf(-x)); }
;     __device__ __forceinline__ void operator()(f32x4 (&acc)[2][2][4][2], const Unit& u, int wr, int wc, int fr, int fq) const {
;     ...
;                     f32x4 v0 = acc[ai][bj][m][0], v1 = acc[ai][bj][m][1];
;                     if (act == 1) {
; #pragma unroll
;                         for (int j = 0; j < 4; ++j) { v0[j] = v0[j] * sigm(v0[j]); v1[j] = v1[j] * sigm(v1[j]); }
;                     } else if (act == 2) {
; #pragma unroll
;                         for (int j = 0; j < 4; ++j) { v0[j] = sigm(v0[j]); v1[j] = sigm(v1[j]); }
;                     }
;                     u32x4 w; w.x = pk_bf16(v0[0], v0[1]); w.y = pk_bf16(v0[2], v0[3]); w.z = pk_bf16(v1[0], v1[1]); w.w = pk_bf16(v1[2], v1[3]);
;                     *(u32x4*)(pb + (size_t)(ai * 128 + m * 16) * NIN) = w;
.LBB0_1321:
	v_cvt_pk_bf16_f32 v146, v146, v147
	v_cvt_pk_bf16_f32 v147, v150, v151
	v_add_co_u32_e32 v150, vcc, 0x41d000, v144
	v_cvt_pk_bf16_f32 v148, v148, v149
	v_cvt_pk_bf16_f32 v149, v152, v153
	s_cmp_gt_i32 s27, 1
	s_nop 0
	v_addc_co_u32_e32 v151, vcc, 0, v145, vcc
	s_mov_b64 s[88:89], -1
	global_store_dwordx4 v[150:151], v[146:149], off nt
	s_cbranch_scc0 .LBB0_1323
	v_mul_f32_e32 v136, 0xbfb8aa3b, v44
	v_exp_f32_e32 v136, v136
	v_mul_f32_e32 v146, 0xbfb8aa3b, v40
	v_exp_f32_e32 v146, v146
	v_mul_f32_e32 v148, 0xbfb8aa3b, v41
	v_add_f32_e32 v136, 1.0, v136
	v_exp_f32_e32 v149, v148
	v_add_f32_e32 v147, 1.0, v146
	v_rcp_f32_e32 v146, v136
	v_mul_f32_e32 v136, 0xbfb8aa3b, v45
	v_exp_f32_e32 v136, v136
	v_rcp_f32_e32 v148, v147
	v_mul_f32_e32 v152, 0xbfb8aa3b, v43
	v_exp_f32_e32 v153, v152
	v_add_f32_e32 v136, 1.0, v136
	v_rcp_f32_e32 v147, v136
	v_add_f32_e32 v136, 1.0, v149
	v_mul_f32_e32 v149, 0xbfb8aa3b, v46
	v_exp_f32_e32 v150, v149
	v_mul_f32_e32 v149, 0xbfb8aa3b, v42
	v_exp_f32_e32 v151, v149
	v_rcp_f32_e32 v149, v136
	v_add_f32_e32 v136, 1.0, v150
	v_rcp_f32_e32 v150, v136
	v_add_f32_e32 v136, 1.0, v151
	v_mul_f32_e32 v151, 0xbfb8aa3b, v47
	v_exp_f32_e32 v151, v151
	v_rcp_f32_e32 v152, v136
	s_mov_b64 s[88:89], 0
	v_add_f32_e32 v136, 1.0, v151
	v_rcp_f32_e32 v151, v136
	v_add_f32_e32 v136, 1.0, v153
	v_rcp_f32_e32 v153, v136

; __device__ __forceinline__ unsigned pk_bf16(float lo, float hi) { unsigned r; asm("v_cvt_pk_bf16_f32 %0, %1, %2" : "=v"(r) : "v"(lo), "v"(hi)); return r; }
; __device__ __forceinline__ float sigm(float x) { return __builtin_amdgcn_rcpf(1.f + __expf(-x)); }
;     __device__ __forceinline__ void operator()(f32x4 (&acc)[2][2][4][2], const Unit& u, int wr, int wc, int fr, int fq) const {
;     ...
;                     f32x4 v0 = acc[ai][bj][m][0], v1 = acc[ai][bj][m][1];
;                     if (act == 1) {
; #pragma unroll
;                         for (int j = 0; j < 4; ++j) { v0[j] = v0[j] * sigm(v0[j]); v1[j] = v1[j] * sigm(v1[j]); }
;                     } else if (act == 2) {
; #pragma unroll
;                         for (int j = 0; j < 4; ++j) { v0[j] = sigm(v0[j]); v1[j] = sigm(v1[j]); }
;                     }
;                     u32x4 w; w.x = pk_bf16(v0[0], v0[1]); w.y = pk_bf16(v0[2], v0[3]); w.z = pk_bf16(v1[0], v1[1]); w.w = pk_bf16(v1[2], v1[3]);
;                     *(u32x4*)(pb + (size_t)(ai * 128 + m * 16) * NIN) = w;
.LBB0_1326:
	v_cvt_pk_bf16_f32 v146, v146, v147
	v_cvt_pk_bf16_f32 v147, v150, v151
	v_add_co_u32_e32 v150, vcc, 0x492000, v144
	v_cvt_pk_bf16_f32 v148, v148, v149
	v_cvt_pk_bf16_f32 v149, v152, v153
	s_cmp_gt_i32 s27, 1
	s_nop 0
	v_addc_co_u32_e32 v151, vcc, 0, v145, vcc
	s_mov_b64 s[88:89], -1
	global_store_dwordx4 v[150:151], v[146:149], off nt
	s_cbranch_scc0 .LBB0_1328
	v_mul_f32_e32 v136, 0xbfb8aa3b, v36
	v_exp_f32_e32 v136, v136
	v_mul_f32_e32 v146, 0xbfb8aa3b, v32
	v_exp_f32_e32 v146, v146
	v_mul_f32_e32 v148, 0xbfb8aa3b, v33
	v_add_f32_e32 v136, 1.0, v136
	v_exp_f32_e32 v149, v148
	v_add_f32_e32 v147, 1.0, v146
	v_rcp_f32_e32 v146, v136
	v_mul_f32_e32 v136, 0xbfb8aa3b, v37
	v_exp_f32_e32 v136, v136
	v_rcp_f32_e32 v148, v147
	v_mul_f32_e32 v152, 0xbfb8aa3b, v35
	v_exp_f32_e32 v153, v152
	v_add_f32_e32 v136, 1.0, v136
	v_rcp_f32_e32 v147, v136
	v_add_f32_e32 v136, 1.0, v149
	v_mul_f32_e32 v149, 0xbfb8aa3b, v38
	v_exp_f32_e32 v150, v149
	v_mul_f32_e32 v149, 0xbfb8aa3b, v34
	v_exp_f32_e32 v151, v149
	v_rcp_f32_e32 v149, v136
	v_add_f32_e32 v136, 1.0, v150
	v_rcp_f32_e32 v150, v136
	v_add_f32_e32 v136, 1.0, v151
	v_mul_f32_e32 v151, 0xbfb8aa3b, v39
	v_exp_f32_e32 v151, v151
	v_rcp_f32_e32 v152, v136
	s_mov_b64 s[88:89], 0
	v_add_f32_e32 v136, 1.0, v151
	v_rcp_f32_e32 v151, v136
	v_add_f32_e32 v136, 1.0, v153
	v_rcp_f32_e32 v153, v136

; __device__ __forceinline__ unsigned pk_bf16(float lo, float hi) { unsigned r; asm("v_cvt_pk_bf16_f32 %0, %1, %2" : "=v"(r) : "v"(lo), "v"(hi)); return r; }
; __device__ __forceinline__ float sigm(float x) { return __builtin_amdgcn_rcpf(1.f + __expf(-x)); }
;     __device__ __forceinline__ void operator()(f32x4 (&acc)[2][2][4][2], const Unit& u, int wr, int wc, int fr, int fq) const {
;     ...
;             const int colb = u.pn * 256 + bj * 128;
;             if (colb >= NIN) continue;
;             const int act = colb >= OFF_MERGE ? 2 : (colb >= OFF_GATE ? 1 : 0);
;             u16* pb = proj + (size_t)(u.pm * 256 + wr * 64 + fr) * NIN + colb + wc * 32 + 8 * fq;
; #pragma unroll
;             for (int ai = 0; ai < 2; ++ai)
; #pragma unroll
;                 for (int m = 0; m < 4; ++m) {
;                     f32x4 v0 = acc[ai][bj][m][0], v1 = acc[ai][bj][m][1];
;                     if (act == 1) {
; #pragma unroll
;                         for (int j = 0; j < 4; ++j) { v0[j] = v0[j] * sigm(v0[j]); v1[j] = v1[j] * sigm(v1[j]); }
;                     } else if (act == 2) {
; #pragma unroll
;                         for (int j = 0; j < 4; ++j) { v0[j] = sigm(v0[j]); v1[j] = sigm(v1[j]); }
;                     }
;                     u32x4 w; w.x = pk_bf16(v0[0], v0[1]); w.y = pk_bf16(v0[2], v0[3]); w.z = pk_bf16(v1[0], v1[1]); w.w = pk_bf16(v1[2], v1[3]);
;                     *(u32x4*)(pb + (size_t)(ai * 128 + m * 16) * NIN) = w;
.LBB0_1331:
	v_add_co_u32_e32 v144, vcc, 0x507000, v144
	v_cvt_pk_bf16_f32 v146, v146, v147
	v_cvt_pk_bf16_f32 v147, v150, v151
	v_cvt_pk_bf16_f32 v148, v148, v149
	v_cvt_pk_bf16_f32 v149, v152, v153
	s_nop 1
	v_addc_co_u32_e32 v145, vcc, 0, v145, vcc
	global_store_dwordx4 v[144:145], v[146:149], off nt
	s_or_b32 s10, s86, 0x80
	s_cmpk_gt_i32 s10, 0x3a7f
	s_cbranch_scc0 .LBB0_1334

; __device__ __forceinline__ unsigned pk_bf16(float lo, float hi) { unsigned r; asm("v_cvt_pk_bf16_f32 %0, %1, %2" : "=v"(r) : "v"(lo), "v"(hi)); return r; }
; __device__ __forceinline__ float sigm(float x) { return __builtin_amdgcn_rcpf(1.f + __expf(-x)); }
;     __device__ __forceinline__ void operator()(f32x4 (&acc)[2][2][4][2], const Unit& u, int wr, int wc, int fr, int fq) const {
;     ...
;             const int colb = u.pn * 256 + bj * 128;
;             if (colb >= NIN) continue;
;             const int act = colb >= OFF_MERGE ? 2 : (colb >= OFF_GATE ? 1 : 0);
;             u16* pb = proj + (size_t)(u.pm * 256 + wr * 64 + fr) * NIN + colb + wc * 32 + 8 * fq;
; #pragma unroll
;             for (int ai = 0; ai < 2; ++ai)
; #pragma unroll
;                 for (int m = 0; m < 4; ++m) {
;                     f32x4 v0 = acc[ai][bj][m][0], v1 = acc[ai][bj][m][1];
;                     if (act == 1) {
; #pragma unroll
;                         for (int j = 0; j < 4; ++j) { v0[j] = v0[j] * sigm(v0[j]); v1[j] = v1[j] * sigm(v1[j]); }
;                     } else if (act == 2) {
; #pragma unroll
;                         for (int j = 0; j < 4; ++j) { v0[j] = sigm(v0[j]); v1[j] = sigm(v1[j]); }
;                     }
;                     u32x4 w; w.x = pk_bf16(v0[0], v0[1]); w.y = pk_bf16(v0[2], v0[3]); w.z = pk_bf16(v1[0], v1[1]); w.w = pk_bf16(v1[2], v1[3]);
;                     *(u32x4*)(pb + (size_t)(ai * 128 + m * 16) * NIN) = w;
.LBB0_1339:
	v_readlane_b32 s28, v252, 40
	v_readlane_b32 s29, v252, 41
	v_lshl_add_u32 v136, s6, 8, v139
	s_ashr_i32 s87, s86, 31
	v_mov_b64_e32 v[144:145], s[28:29]
	v_mad_i64_i32 v[144:145], s[28:29], v136, s21, v[144:145]
	v_lshl_add_u64 v[144:145], s[86:87], 1, v[144:145]
	s_lshl_b32 s10, s16, 1
	v_lshl_add_u64 v[144:145], v[144:145], 0, s[10:11]
	v_lshlrev_b32_e32 v136, 1, v138
	v_lshl_add_u64 v[156:157], v[144:145], 0, v[136:137]
	s_mov_b64 s[28:29], 0x100
	v_lshl_add_u64 v[144:145], v[156:157], 0, s[28:29]
	v_cvt_pk_bf16_f32 v146, v146, v147
	v_cvt_pk_bf16_f32 v147, v150, v151
	v_cvt_pk_bf16_f32 v148, v148, v149
	v_cvt_pk_bf16_f32 v149, v152, v153
	s_cmp_gt_i32 s27, 1
	s_mov_b64 s[86:87], -1
	global_store_dwordx4 v[156:157], v[146:149], off offset:256 nt
	s_cbranch_scc0 .LBB0_1341
	v_mul_f32_e32 v136, 0xbfb8aa3b, v84
	v_exp_f32_e32 v136, v136
	v_mul_f32_e32 v146, 0xbfb8aa3b, v80
	v_exp_f32_e32 v146, v146
	v_mul_f32_e32 v148, 0xbfb8aa3b, v81
	v_add_f32_e32 v136, 1.0, v136
	v_exp_f32_e32 v149, v148
	v_add_f32_e32 v147, 1.0, v146
	v_rcp_f32_e32 v146, v136
	v_mul_f32_e32 v136, 0xbfb8aa3b, v85
	v_exp_f32_e32 v136, v136
	v_rcp_f32_e32 v148, v147
	v_mul_f32_e32 v152, 0xbfb8aa3b, v83
	v_exp_f32_e32 v153, v152
	v_add_f32_e32 v136, 1.0, v136
	v_rcp_f32_e32 v147, v136
	v_add_f32_e32 v136, 1.0, v149
	v_mul_f32_e32 v149, 0xbfb8aa3b, v86
	v_exp_f32_e32 v150, v149
	v_mul_f32_e32 v149, 0xbfb8aa3b, v82
	v_exp_f32_e32 v151, v149
	v_rcp_f32_e32 v149, v136
	v_add_f32_e32 v136, 1.0, v150
	v_rcp_f32_e32 v150, v136
	v_add_f32_e32 v136, 1.0, v151
	v_mul_f32_e32 v151, 0xbfb8aa3b, v87
	v_exp_f32_e32 v151, v151
	v_rcp_f32_e32 v152, v136
	s_mov_b64 s[86:87], 0
	v_add_f32_e32 v136, 1.0, v151
	v_rcp_f32_e32 v151, v136
	v_add_f32_e32 v136, 1.0, v153
	v_rcp_f32_e32 v153, v136

; __device__ __forceinline__ unsigned pk_bf16(float lo, float hi) { unsigned r; asm("v_cvt_pk_bf16_f32 %0, %1, %2" : "=v"(r) : "v"(lo), "v"(hi)); return r; }
; __device__ __forceinline__ float sigm(float x) { return __builtin_amdgcn_rcpf(1.f + __expf(-x)); }
;     __device__ __forceinline__ void operator()(f32x4 (&acc)[2][2][4][2], const Unit& u, int wr, int wc, int fr, int fq) const {
;     ...
;                     f32x4 v0 = acc[ai][bj][m][0], v1 = acc[ai][bj][m][1];
;                     if (act == 1) {
; #pragma unroll
;                         for (int j = 0; j < 4; ++j) { v0[j] = v0[j] * sigm(v0[j]); v1[j] = v1[j] * sigm(v1[j]); }
;                     } else if (act == 2) {
; #pragma unroll
;                         for (int j = 0; j < 4; ++j) { v0[j] = sigm(v0[j]); v1[j] = sigm(v1[j]); }
;                     }
;                     u32x4 w; w.x = pk_bf16(v0[0], v0[1]); w.y = pk_bf16(v0[2], v0[3]); w.z = pk_bf16(v1[0], v1[1]); w.w = pk_bf16(v1[2], v1[3]);
;                     *(u32x4*)(pb + (size_t)(ai * 128 + m * 16) * NIN) = w;
.LBB0_1344:
	v_cvt_pk_bf16_f32 v146, v146, v147
	v_cvt_pk_bf16_f32 v147, v150, v151
	v_add_co_u32_e32 v150, vcc, 0x75000, v144
	v_cvt_pk_bf16_f32 v148, v148, v149
	v_cvt_pk_bf16_f32 v149, v152, v153
	s_cmp_gt_i32 s27, 1
	s_nop 0
	v_addc_co_u32_e32 v151, vcc, 0, v145, vcc
	s_mov_b64 s[86:87], -1
	global_store_dwordx4 v[150:151], v[146:149], off nt
	s_cbranch_scc0 .LBB0_1346
	v_mul_f32_e32 v136, 0xbfb8aa3b, v76
	v_exp_f32_e32 v136, v136
	v_mul_f32_e32 v146, 0xbfb8aa3b, v72
	v_exp_f32_e32 v146, v146
	v_mul_f32_e32 v148, 0xbfb8aa3b, v73
	v_add_f32_e32 v136, 1.0, v136
	v_exp_f32_e32 v149, v148
	v_add_f32_e32 v147, 1.0, v146
	v_rcp_f32_e32 v146, v136
	v_mul_f32_e32 v136, 0xbfb8aa3b, v77
	v_exp_f32_e32 v136, v136
	v_rcp_f32_e32 v148, v147
	v_mul_f32_e32 v152, 0xbfb8aa3b, v75
	v_exp_f32_e32 v153, v152
	v_add_f32_e32 v136, 1.0, v136
	v_rcp_f32_e32 v147, v136
	v_add_f32_e32 v136, 1.0, v149
	v_mul_f32_e32 v149, 0xbfb8aa3b, v78
	v_exp_f32_e32 v150, v149
	v_mul_f32_e32 v149, 0xbfb8aa3b, v74
	v_exp_f32_e32 v151, v149
	v_rcp_f32_e32 v149, v136
	v_add_f32_e32 v136, 1.0, v150
	v_rcp_f32_e32 v150, v136
	v_add_f32_e32 v136, 1.0, v151
	v_mul_f32_e32 v151, 0xbfb8aa3b, v79
	v_exp_f32_e32 v151, v151
	v_rcp_f32_e32 v152, v136
	s_mov_b64 s[86:87], 0
	v_add_f32_e32 v136, 1.0, v151
	v_rcp_f32_e32 v151, v136
	v_add_f32_e32 v136, 1.0, v153
	v_rcp_f32_e32 v153, v136

; __device__ __forceinline__ unsigned pk_bf16(float lo, float hi) { unsigned r; asm("v_cvt_pk_bf16_f32 %0, %1, %2" : "=v"(r) : "v"(lo), "v"(hi)); return r; }
; __device__ __forceinline__ float sigm(float x) { return __builtin_amdgcn_rcpf(1.f + __expf(-x)); }
;     __device__ __forceinline__ void operator()(f32x4 (&acc)[2][2][4][2], const Unit& u, int wr, int wc, int fr, int fq) const {
;     ...
;                     f32x4 v0 = acc[ai][bj][m][0], v1 = acc[ai][bj][m][1];
;                     if (act == 1) {
; #pragma unroll
;                         for (int j = 0; j < 4; ++j) { v0[j] = v0[j] * sigm(v0[j]); v1[j] = v1[j] * sigm(v1[j]); }
;                     } else if (act == 2) {
; #pragma unroll
;                         for (int j = 0; j < 4; ++j) { v0[j] = sigm(v0[j]); v1[j] = sigm(v1[j]); }
;                     }
;                     u32x4 w; w.x = pk_bf16(v0[0], v0[1]); w.y = pk_bf16(v0[2], v0[3]); w.z = pk_bf16(v1[0], v1[1]); w.w = pk_bf16(v1[2], v1[3]);
;                     *(u32x4*)(pb + (size_t)(ai * 128 + m * 16) * NIN) = w;
.LBB0_1349:
	v_cvt_pk_bf16_f32 v146, v146, v147
	v_cvt_pk_bf16_f32 v147, v150, v151
	v_add_co_u32_e32 v150, vcc, 0xea000, v144
	v_cvt_pk_bf16_f32 v148, v148, v149
	v_cvt_pk_bf16_f32 v149, v152, v153
	s_cmp_gt_i32 s27, 1
	s_nop 0
	v_addc_co_u32_e32 v151, vcc, 0, v145, vcc
	s_mov_b64 s[86:87], -1
	global_store_dwordx4 v[150:151], v[146:149], off nt
	s_cbranch_scc0 .LBB0_1351
	v_mul_f32_e32 v136, 0xbfb8aa3b, v68
	v_exp_f32_e32 v136, v136
	v_mul_f32_e32 v146, 0xbfb8aa3b, v64
	v_exp_f32_e32 v146, v146
	v_mul_f32_e32 v148, 0xbfb8aa3b, v65
	v_add_f32_e32 v136, 1.0, v136
	v_exp_f32_e32 v149, v148
	v_add_f32_e32 v147, 1.0, v146
	v_rcp_f32_e32 v146, v136
	v_mul_f32_e32 v136, 0xbfb8aa3b, v69
	v_exp_f32_e32 v136, v136
	v_rcp_f32_e32 v148, v147
	v_mul_f32_e32 v152, 0xbfb8aa3b, v67
	v_exp_f32_e32 v153, v152
	v_add_f32_e32 v136, 1.0, v136
	v_rcp_f32_e32 v147, v136
	v_add_f32_e32 v136, 1.0, v149
	v_mul_f32_e32 v149, 0xbfb8aa3b, v70
	v_exp_f32_e32 v150, v149
	v_mul_f32_e32 v149, 0xbfb8aa3b, v66
	v_exp_f32_e32 v151, v149
	v_rcp_f32_e32 v149, v136
	v_add_f32_e32 v136, 1.0, v150
	v_rcp_f32_e32 v150, v136
	v_add_f32_e32 v136, 1.0, v151
	v_mul_f32_e32 v151, 0xbfb8aa3b, v71
	v_exp_f32_e32 v151, v151
	v_rcp_f32_e32 v152, v136
	s_mov_b64 s[86:87], 0
	v_add_f32_e32 v136, 1.0, v151
	v_rcp_f32_e32 v151, v136
	v_add_f32_e32 v136, 1.0, v153
	v_rcp_f32_e32 v153, v136

; __device__ __forceinline__ unsigned pk_bf16(float lo, float hi) { unsigned r; asm("v_cvt_pk_bf16_f32 %0, %1, %2" : "=v"(r) : "v"(lo), "v"(hi)); return r; }
; __device__ __forceinline__ float sigm(float x) { return __builtin_amdgcn_rcpf(1.f + __expf(-x)); }
;     __device__ __forceinline__ void operator()(f32x4 (&acc)[2][2][4][2], const Unit& u, int wr, int wc, int fr, int fq) const {
;     ...
;                     f32x4 v0 = acc[ai][bj][m][0], v1 = acc[ai][bj][m][1];
;                     if (act == 1) {
; #pragma unroll
;                         for (int j = 0; j < 4; ++j) { v0[j] = v0[j] * sigm(v0[j]); v1[j] = v1[j] * sigm(v1[j]); }
;                     } else if (act == 2) {
; #pragma unroll
;                         for (int j = 0; j < 4; ++j) { v0[j] = sigm(v0[j]); v1[j] = sigm(v1[j]); }
;                     }
;                     u32x4 w; w.x = pk_bf16(v0[0], v0[1]); w.y = pk_bf16(v0[2], v0[3]); w.z = pk_bf16(v1[0], v1[1]); w.w = pk_bf16(v1[2], v1[3]);
;                     *(u32x4*)(pb + (size_t)(ai * 128 + m * 16) * NIN) = w;
.LBB0_1354:
	v_cvt_pk_bf16_f32 v146, v146, v147
	v_cvt_pk_bf16_f32 v147, v150, v151
	v_add_co_u32_e32 v150, vcc, 0x15f000, v144
	v_cvt_pk_bf16_f32 v148, v148, v149
	v_cvt_pk_bf16_f32 v149, v152, v153
	s_cmp_gt_i32 s27, 1
	s_nop 0
	v_addc_co_u32_e32 v151, vcc, 0, v145, vcc
	s_mov_b64 s[86:87], -1
	global_store_dwordx4 v[150:151], v[146:149], off nt
	s_cbranch_scc0 .LBB0_1356
	v_mul_f32_e32 v136, 0xbfb8aa3b, v28
	v_exp_f32_e32 v136, v136
	v_mul_f32_e32 v146, 0xbfb8aa3b, v24
	v_exp_f32_e32 v146, v146
	v_mul_f32_e32 v148, 0xbfb8aa3b, v25
	v_add_f32_e32 v136, 1.0, v136
	v_exp_f32_e32 v149, v148
	v_add_f32_e32 v147, 1.0, v146
	v_rcp_f32_e32 v146, v136
	v_mul_f32_e32 v136, 0xbfb8aa3b, v29
	v_exp_f32_e32 v136, v136
	v_rcp_f32_e32 v148, v147
	v_mul_f32_e32 v152, 0xbfb8aa3b, v27
	v_exp_f32_e32 v153, v152
	v_add_f32_e32 v136, 1.0, v136
	v_rcp_f32_e32 v147, v136
	v_add_f32_e32 v136, 1.0, v149
	v_mul_f32_e32 v149, 0xbfb8aa3b, v30
	v_exp_f32_e32 v150, v149
	v_mul_f32_e32 v149, 0xbfb8aa3b, v26
	v_exp_f32_e32 v151, v149
	v_rcp_f32_e32 v149, v136
	v_add_f32_e32 v136, 1.0, v150
	v_rcp_f32_e32 v150, v136
	v_add_f32_e32 v136, 1.0, v151
	v_mul_f32_e32 v151, 0xbfb8aa3b, v31
	v_exp_f32_e32 v151, v151
	v_rcp_f32_e32 v152, v136
	s_mov_b64 s[86:87], 0
	v_add_f32_e32 v136, 1.0, v151
	v_rcp_f32_e32 v151, v136
	v_add_f32_e32 v136, 1.0, v153
	v_rcp_f32_e32 v153, v136

; __device__ __forceinline__ unsigned pk_bf16(float lo, float hi) { unsigned r; asm("v_cvt_pk_bf16_f32 %0, %1, %2" : "=v"(r) : "v"(lo), "v"(hi)); return r; }
; __device__ __forceinline__ float sigm(float x) { return __builtin_amdgcn_rcpf(1.f + __expf(-x)); }
;     __device__ __forceinline__ void operator()(f32x4 (&acc)[2][2][4][2], const Unit& u, int wr, int wc, int fr, int fq) const {
;     ...
;                     f32x4 v0 = acc[ai][bj][m][0], v1 = acc[ai][bj][m][1];
;                     if (act == 1) {
; #pragma unroll
;                         for (int j = 0; j < 4; ++j) { v0[j] = v0[j] * sigm(v0[j]); v1[j] = v1[j] * sigm(v1[j]); }
;                     } else if (act == 2) {
; #pragma unroll
;                         for (int j = 0; j < 4; ++j) { v0[j] = sigm(v0[j]); v1[j] = sigm(v1[j]); }
;                     }
;                     u32x4 w; w.x = pk_bf16(v0[0], v0[1]); w.y = pk_bf16(v0[2], v0[3]); w.z = pk_bf16(v1[0], v1[1]); w.w = pk_bf16(v1[2], v1[3]);
;                     *(u32x4*)(pb + (size_t)(ai * 128 + m * 16) * NIN) = w;
.LBB0_1359:
	v_cvt_pk_bf16_f32 v146, v146, v147
	v_cvt_pk_bf16_f32 v147, v150, v151
	v_add_co_u32_e32 v150, vcc, 0x3a8000, v144
	v_cvt_pk_bf16_f32 v148, v148, v149
	v_cvt_pk_bf16_f32 v149, v152, v153
	s_cmp_gt_i32 s27, 1
	s_nop 0
	v_addc_co_u32_e32 v151, vcc, 0, v145, vcc
	s_mov_b64 s[86:87], -1
	global_store_dwordx4 v[150:151], v[146:149], off nt
	s_cbranch_scc0 .LBB0_1361
	v_mul_f32_e32 v136, 0xbfb8aa3b, v20
	v_exp_f32_e32 v136, v136
	v_mul_f32_e32 v146, 0xbfb8aa3b, v16
	v_exp_f32_e32 v146, v146
	v_mul_f32_e32 v148, 0xbfb8aa3b, v17
	v_add_f32_e32 v136, 1.0, v136
	v_exp_f32_e32 v149, v148
	v_add_f32_e32 v147, 1.0, v146
	v_rcp_f32_e32 v146, v136
	v_mul_f32_e32 v136, 0xbfb8aa3b, v21
	v_exp_f32_e32 v136, v136
	v_rcp_f32_e32 v148, v147
	v_mul_f32_e32 v152, 0xbfb8aa3b, v19
	v_exp_f32_e32 v153, v152
	v_add_f32_e32 v136, 1.0, v136
	v_rcp_f32_e32 v147, v136
	v_add_f32_e32 v136, 1.0, v149
	v_mul_f32_e32 v149, 0xbfb8aa3b, v22
	v_exp_f32_e32 v150, v149
	v_mul_f32_e32 v149, 0xbfb8aa3b, v18
	v_exp_f32_e32 v151, v149
	v_rcp_f32_e32 v149, v136
	v_add_f32_e32 v136, 1.0, v150
	v_rcp_f32_e32 v150, v136
	v_add_f32_e32 v136, 1.0, v151
	v_mul_f32_e32 v151, 0xbfb8aa3b, v23
	v_exp_f32_e32 v151, v151
	v_rcp_f32_e32 v152, v136
	s_mov_b64 s[86:87], 0
	v_add_f32_e32 v136, 1.0, v151
	v_rcp_f32_e32 v151, v136
	v_add_f32_e32 v136, 1.0, v153
	v_rcp_f32_e32 v153, v136

; __device__ __forceinline__ unsigned pk_bf16(float lo, float hi) { unsigned r; asm("v_cvt_pk_bf16_f32 %0, %1, %2" : "=v"(r) : "v"(lo), "v"(hi)); return r; }
; __device__ __forceinline__ float sigm(float x) { return __builtin_amdgcn_rcpf(1.f + __expf(-x)); }
;     __device__ __forceinline__ void operator()(f32x4 (&acc)[2][2][4][2], const Unit& u, int wr, int wc, int fr, int fq) const {
;     ...
;                     f32x4 v0 = acc[ai][bj][m][0], v1 = acc[ai][bj][m][1];
;                     if (act == 1) {
; #pragma unroll
;                         for (int j = 0; j < 4; ++j) { v0[j] = v0[j] * sigm(v0[j]); v1[j] = v1[j] * sigm(v1[j]); }
;                     } else if (act == 2) {
; #pragma unroll
;                         for (int j = 0; j < 4; ++j) { v0[j] = sigm(v0[j]); v1[j] = sigm(v1[j]); }
;                     }
;                     u32x4 w; w.x = pk_bf16(v0[0], v0[1]); w.y = pk_bf16(v0[2], v0[3]); w.z = pk_bf16(v1[0], v1[1]); w.w = pk_bf16(v1[2], v1[3]);
;                     *(u32x4*)(pb + (size_t)(ai * 128 + m * 16) * NIN) = w;
.LBB0_1364:
	v_cvt_pk_bf16_f32 v146, v146, v147
	v_cvt_pk_bf16_f32 v147, v150, v151
	v_add_co_u32_e32 v150, vcc, 0x41d000, v144
	v_cvt_pk_bf16_f32 v148, v148, v149
	v_cvt_pk_bf16_f32 v149, v152, v153
	s_cmp_gt_i32 s27, 1
	s_nop 0
	v_addc_co_u32_e32 v151, vcc, 0, v145, vcc
	s_mov_b64 s[86:87], -1
	global_store_dwordx4 v[150:151], v[146:149], off nt
	s_cbranch_scc0 .LBB0_1366
	v_mul_f32_e32 v136, 0xbfb8aa3b, v12
	v_exp_f32_e32 v136, v136
	v_mul_f32_e32 v146, 0xbfb8aa3b, v8
	v_exp_f32_e32 v146, v146
	v_mul_f32_e32 v148, 0xbfb8aa3b, v9
	v_add_f32_e32 v136, 1.0, v136
	v_exp_f32_e32 v149, v148
	v_add_f32_e32 v147, 1.0, v146
	v_rcp_f32_e32 v146, v136
	v_mul_f32_e32 v136, 0xbfb8aa3b, v13
	v_exp_f32_e32 v136, v136
	v_rcp_f32_e32 v148, v147
	v_mul_f32_e32 v152, 0xbfb8aa3b, v11
	v_exp_f32_e32 v153, v152
	v_add_f32_e32 v136, 1.0, v136
	v_rcp_f32_e32 v147, v136
	v_add_f32_e32 v136, 1.0, v149
	v_mul_f32_e32 v149, 0xbfb8aa3b, v14
	v_exp_f32_e32 v150, v149
	v_mul_f32_e32 v149, 0xbfb8aa3b, v10
	v_exp_f32_e32 v151, v149
	v_rcp_f32_e32 v149, v136
	v_add_f32_e32 v136, 1.0, v150
	v_rcp_f32_e32 v150, v136
	v_add_f32_e32 v136, 1.0, v151
	v_mul_f32_e32 v151, 0xbfb8aa3b, v15
	v_exp_f32_e32 v151, v151
	v_rcp_f32_e32 v152, v136
	s_mov_b64 s[86:87], 0
	v_add_f32_e32 v136, 1.0, v151
	v_rcp_f32_e32 v151, v136
	v_add_f32_e32 v136, 1.0, v153
	v_rcp_f32_e32 v153, v136

; __device__ __forceinline__ unsigned pk_bf16(float lo, float hi) { unsigned r; asm("v_cvt_pk_bf16_f32 %0, %1, %2" : "=v"(r) : "v"(lo), "v"(hi)); return r; }
; __device__ __forceinline__ float sigm(float x) { return __builtin_amdgcn_rcpf(1.f + __expf(-x)); }
;     __device__ __forceinline__ void operator()(f32x4 (&acc)[2][2][4][2], const Unit& u, int wr, int wc, int fr, int fq) const {
;     ...
;                     f32x4 v0 = acc[ai][bj][m][0], v1 = acc[ai][bj][m][1];
;                     if (act == 1) {
; #pragma unroll
;                         for (int j = 0; j < 4; ++j) { v0[j] = v0[j] * sigm(v0[j]); v1[j] = v1[j] * sigm(v1[j]); }
;                     } else if (act == 2) {
; #pragma unroll
;                         for (int j = 0; j < 4; ++j) { v0[j] = sigm(v0[j]); v1[j] = sigm(v1[j]); }
;                     }
;                     u32x4 w; w.x = pk_bf16(v0[0], v0[1]); w.y = pk_bf16(v0[2], v0[3]); w.z = pk_bf16(v1[0], v1[1]); w.w = pk_bf16(v1[2], v1[3]);
;                     *(u32x4*)(pb + (size_t)(ai * 128 + m * 16) * NIN) = w;
.LBB0_1369:
	v_cvt_pk_bf16_f32 v146, v146, v147
	v_cvt_pk_bf16_f32 v147, v150, v151
	v_add_co_u32_e32 v150, vcc, 0x492000, v144
	v_cvt_pk_bf16_f32 v148, v148, v149
	v_cvt_pk_bf16_f32 v149, v152, v153
	s_cmp_gt_i32 s27, 1
	s_nop 0
	v_addc_co_u32_e32 v151, vcc, 0, v145, vcc
	s_mov_b64 s[86:87], -1
	global_store_dwordx4 v[150:151], v[146:149], off nt
	s_cbranch_scc0 .LBB0_1371
	v_mul_f32_e32 v136, 0xbfb8aa3b, v4
	v_exp_f32_e32 v136, v136
	v_mul_f32_e32 v146, 0xbfb8aa3b, v0
	v_exp_f32_e32 v146, v146
	v_mul_f32_e32 v148, 0xbfb8aa3b, v1
	v_add_f32_e32 v136, 1.0, v136
	v_exp_f32_e32 v149, v148
	v_add_f32_e32 v147, 1.0, v146
	v_rcp_f32_e32 v146, v136
	v_mul_f32_e32 v136, 0xbfb8aa3b, v5
	v_exp_f32_e32 v136, v136
	v_rcp_f32_e32 v148, v147
	v_mul_f32_e32 v152, 0xbfb8aa3b, v3
	v_exp_f32_e32 v153, v152
	v_add_f32_e32 v136, 1.0, v136
	v_rcp_f32_e32 v147, v136
	v_add_f32_e32 v136, 1.0, v149
	v_mul_f32_e32 v149, 0xbfb8aa3b, v6
	v_exp_f32_e32 v150, v149
	v_mul_f32_e32 v149, 0xbfb8aa3b, v2
	v_exp_f32_e32 v151, v149
	v_rcp_f32_e32 v149, v136
	v_add_f32_e32 v136, 1.0, v150
	v_rcp_f32_e32 v150, v136
	v_add_f32_e32 v136, 1.0, v151
	v_mul_f32_e32 v151, 0xbfb8aa3b, v7
	v_exp_f32_e32 v151, v151
	v_rcp_f32_e32 v152, v136
	s_mov_b64 s[86:87], 0
	v_add_f32_e32 v136, 1.0, v151
	v_rcp_f32_e32 v151, v136
	v_add_f32_e32 v136, 1.0, v153
	v_rcp_f32_e32 v153, v136

; __device__ __forceinline__ unsigned pk_bf16(float lo, float hi) { unsigned r; asm("v_cvt_pk_bf16_f32 %0, %1, %2" : "=v"(r) : "v"(lo), "v"(hi)); return r; }
; __device__ __forceinline__ float sigm(float x) { return __builtin_amdgcn_rcpf(1.f + __expf(-x)); }
;     __device__ __forceinline__ void operator()(f32x4 (&acc)[2][2][4][2], const Unit& u, int wr, int wc, int fr, int fq) const {
;     ...
;         for (int bj = 0; bj < 2; ++bj) {
;             const int colb = u.pn * 256 + bj * 128;
;             if (colb >= NIN) continue;
;             const int act = colb >= OFF_MERGE ? 2 : (colb >= OFF_GATE ? 1 : 0);
;             u16* pb = proj + (size_t)(u.pm * 256 + wr * 64 + fr) * NIN + colb + wc * 32 + 8 * fq;
; #pragma unroll
;             for (int ai = 0; ai < 2; ++ai)
; #pragma unroll
;                 for (int m = 0; m < 4; ++m) {
;                     f32x4 v0 = acc[ai][bj][m][0], v1 = acc[ai][bj][m][1];
;                     if (act == 1) {
; #pragma unroll
;                         for (int j = 0; j < 4; ++j) { v0[j] = v0[j] * sigm(v0[j]); v1[j] = v1[j] * sigm(v1[j]); }
;                     } else if (act == 2) {
; #pragma unroll
;                         for (int j = 0; j < 4; ++j) { v0[j] = sigm(v0[j]); v1[j] = sigm(v1[j]); }
;                     }
;                     u32x4 w; w.x = pk_bf16(v0[0], v0[1]); w.y = pk_bf16(v0[2], v0[3]); w.z = pk_bf16(v1[0], v1[1]); w.w = pk_bf16(v1[2], v1[3]);
;                     *(u32x4*)(pb + (size_t)(ai * 128 + m * 16) * NIN) = w;
.LBB0_1374:
	v_add_co_u32_e32 v144, vcc, 0x507000, v144
	v_cvt_pk_bf16_f32 v146, v146, v147
	v_cvt_pk_bf16_f32 v147, v150, v151
	v_cvt_pk_bf16_f32 v148, v148, v149
	v_cvt_pk_bf16_f32 v149, v152, v153
	s_nop 1
	v_addc_co_u32_e32 v145, vcc, 0, v145, vcc
	global_store_dwordx4 v[144:145], v[146:149], off nt
	s_add_u32 s86, s24, 0xffffff00
	s_addc_u32 s87, s25, -1
	s_andn2_b64 vcc, exec, s[82:83]
	s_cbranch_vccnz .LBB0_1279

; __device__ __forceinline__ unsigned pk_bf16(float lo, float hi) { unsigned r; asm("v_cvt_pk_bf16_f32 %0, %1, %2" : "=v"(r) : "v"(lo), "v"(hi)); return r; }
; __device__ __forceinline__ float sigm(float x) { return __builtin_amdgcn_rcpf(1.f + __expf(-x)); }
;     __device__ __forceinline__ void operator()(f32x4 (&acc)[2][2][4][2], const Unit& u, int wr, int wc, int fr, int fq) const {
;     ...
;             const int colb = u.pn * 256 + bj * 128;
;             if (colb >= NIN) continue;
;             const int act = colb >= OFF_MERGE ? 2 : (colb >= OFF_GATE ? 1 : 0);
;             u16* pb = proj + (size_t)(u.pm * 256 + wr * 64 + fr) * NIN + colb + wc * 32 + 8 * fq;
; #pragma unroll
;             for (int ai = 0; ai < 2; ++ai)
; #pragma unroll
;                 for (int m = 0; m < 4; ++m) {
;                     f32x4 v0 = acc[ai][bj][m][0], v1 = acc[ai][bj][m][1];
;                     if (act == 1) {
; #pragma unroll
;                         for (int j = 0; j < 4; ++j) { v0[j] = v0[j] * sigm(v0[j]); v1[j] = v1[j] * sigm(v1[j]); }
;                     } else if (act == 2) {
; #pragma unroll
;                         for (int j = 0; j < 4; ++j) { v0[j] = sigm(v0[j]); v1[j] = sigm(v1[j]); }
;                     }
;                     u32x4 w; w.x = pk_bf16(v0[0], v0[1]); w.y = pk_bf16(v0[2], v0[3]); w.z = pk_bf16(v1[0], v1[1]); w.w = pk_bf16(v1[2], v1[3]);
;                     *(u32x4*)(pb + (size_t)(ai * 128 + m * 16) * NIN) = w;
.LBB0_2420:
	v_readlane_b32 s4, v252, 40
	v_readlane_b32 s5, v252, 41
	v_lshl_add_u32 v122, s66, 8, v139
	s_ashr_i32 s69, s68, 31
	v_mov_b64_e32 v[120:121], s[4:5]
	v_mad_i64_i32 v[120:121], s[4:5], v122, s25, v[120:121]
	v_lshl_add_u64 v[120:121], s[68:69], 1, v[120:121]
	s_lshl_b32 s0, s20, 1
	v_lshl_add_u64 v[120:121], v[120:121], 0, s[0:1]
	v_lshlrev_b32_e32 v136, 1, v138
	v_lshl_add_u64 v[120:121], v[120:121], 0, v[136:137]
	v_cvt_pk_bf16_f32 v122, v148, v150
	v_cvt_pk_bf16_f32 v123, v152, v155
	v_cvt_pk_bf16_f32 v124, v149, v151
	v_cvt_pk_bf16_f32 v125, v153, v154
	s_cmp_gt_i32 s11, 1
	s_mov_b64 s[76:77], -1
	global_store_dwordx4 v[120:121], v[122:125], off nt
	s_cbranch_scc0 .LBB0_2422
	v_mul_f32_e32 v136, 0xbfb8aa3b, v119
	v_mul_f32_e32 v122, 0xbfb8aa3b, v116
	v_mul_f32_e32 v123, 0xbfb8aa3b, v112
	v_mul_f32_e32 v124, 0xbfb8aa3b, v117
	v_mul_f32_e32 v125, 0xbfb8aa3b, v113
	v_mul_f32_e32 v126, 0xbfb8aa3b, v118
	v_mul_f32_e32 v127, 0xbfb8aa3b, v114
	v_exp_f32_e32 v136, v136
	v_mul_f32_e32 v148, 0xbfb8aa3b, v115
	v_exp_f32_e32 v122, v122
	v_exp_f32_e32 v123, v123
	v_exp_f32_e32 v124, v124
	v_exp_f32_e32 v125, v125
	v_exp_f32_e32 v126, v126
	v_exp_f32_e32 v127, v127
	v_exp_f32_e32 v149, v148
	v_add_f32_e32 v136, 1.0, v136
	v_add_f32_e32 v122, 1.0, v122
	v_add_f32_e32 v123, 1.0, v123
	v_add_f32_e32 v124, 1.0, v124
	v_add_f32_e32 v125, 1.0, v125
	v_add_f32_e32 v126, 1.0, v126
	v_add_f32_e32 v127, 1.0, v127
	v_rcp_f32_e32 v148, v136
	v_add_f32_e32 v136, 1.0, v149
	v_rcp_f32_e32 v122, v122
	v_rcp_f32_e32 v123, v123
	v_rcp_f32_e32 v124, v124
	v_rcp_f32_e32 v125, v125
	v_rcp_f32_e32 v126, v126
	v_rcp_f32_e32 v127, v127
	v_rcp_f32_e32 v136, v136
	s_mov_b64 s[76:77], 0

; __device__ __forceinline__ unsigned pk_bf16(float lo, float hi) { unsigned r; asm("v_cvt_pk_bf16_f32 %0, %1, %2" : "=v"(r) : "v"(lo), "v"(hi)); return r; }
; __device__ __forceinline__ float sigm(float x) { return __builtin_amdgcn_rcpf(1.f + __expf(-x)); }
;     __device__ __forceinline__ void operator()(f32x4 (&acc)[2][2][4][2], const Unit& u, int wr, int wc, int fr, int fq) const {
;     ...
;                     f32x4 v0 = acc[ai][bj][m][0], v1 = acc[ai][bj][m][1];
;                     if (act == 1) {
; #pragma unroll
;                         for (int j = 0; j < 4; ++j) { v0[j] = v0[j] * sigm(v0[j]); v1[j] = v1[j] * sigm(v1[j]); }
;                     } else if (act == 2) {
; #pragma unroll
;                         for (int j = 0; j < 4; ++j) { v0[j] = sigm(v0[j]); v1[j] = sigm(v1[j]); }
;                     }
;                     u32x4 w; w.x = pk_bf16(v0[0], v0[1]); w.y = pk_bf16(v0[2], v0[3]); w.z = pk_bf16(v1[0], v1[1]); w.w = pk_bf16(v1[2], v1[3]);
;                     *(u32x4*)(pb + (size_t)(ai * 128 + m * 16) * NIN) = w;
.LBB0_2426:
	v_add_co_u32_e32 v116, vcc, 0x75000, v120
	v_cvt_pk_bf16_f32 v112, v122, v124
	v_cvt_pk_bf16_f32 v113, v126, v148
	v_cvt_pk_bf16_f32 v114, v123, v125
	v_cvt_pk_bf16_f32 v115, v127, v136
	s_nop 1
	v_addc_co_u32_e32 v117, vcc, 0, v121, vcc
	s_cmp_gt_i32 s11, 1
	s_mov_b64 s[76:77], -1
	global_store_dwordx4 v[116:117], v[112:115], off nt
	s_cbranch_scc0 .LBB0_2428
	v_mul_f32_e32 v118, 0xbfb8aa3b, v111
	v_mul_f32_e32 v112, 0xbfb8aa3b, v108
	v_mul_f32_e32 v113, 0xbfb8aa3b, v104
	v_mul_f32_e32 v114, 0xbfb8aa3b, v109
	v_mul_f32_e32 v115, 0xbfb8aa3b, v105
	v_mul_f32_e32 v116, 0xbfb8aa3b, v110
	v_mul_f32_e32 v117, 0xbfb8aa3b, v106
	v_exp_f32_e32 v118, v118
	v_mul_f32_e32 v119, 0xbfb8aa3b, v107
	v_exp_f32_e32 v112, v112
	v_exp_f32_e32 v113, v113
	v_exp_f32_e32 v114, v114
	v_exp_f32_e32 v115, v115
	v_exp_f32_e32 v116, v116
	v_exp_f32_e32 v117, v117
	v_exp_f32_e32 v122, v119
	v_add_f32_e32 v118, 1.0, v118
	v_add_f32_e32 v112, 1.0, v112
	v_add_f32_e32 v113, 1.0, v113
	v_add_f32_e32 v114, 1.0, v114
	v_add_f32_e32 v115, 1.0, v115
	v_add_f32_e32 v116, 1.0, v116
	v_add_f32_e32 v117, 1.0, v117
	v_rcp_f32_e32 v119, v118
	v_add_f32_e32 v118, 1.0, v122
	v_rcp_f32_e32 v112, v112
	v_rcp_f32_e32 v113, v113
	v_rcp_f32_e32 v114, v114
	v_rcp_f32_e32 v115, v115
	v_rcp_f32_e32 v116, v116
	v_rcp_f32_e32 v117, v117
	v_rcp_f32_e32 v118, v118
	s_mov_b64 s[76:77], 0

; __device__ __forceinline__ unsigned pk_bf16(float lo, float hi) { unsigned r; asm("v_cvt_pk_bf16_f32 %0, %1, %2" : "=v"(r) : "v"(lo), "v"(hi)); return r; }
; __device__ __forceinline__ float sigm(float x) { return __builtin_amdgcn_rcpf(1.f + __expf(-x)); }
;     __device__ __forceinline__ void operator()(f32x4 (&acc)[2][2][4][2], const Unit& u, int wr, int wc, int fr, int fq) const {
;     ...
;                     f32x4 v0 = acc[ai][bj][m][0], v1 = acc[ai][bj][m][1];
;                     if (act == 1) {
; #pragma unroll
;                         for (int j = 0; j < 4; ++j) { v0[j] = v0[j] * sigm(v0[j]); v1[j] = v1[j] * sigm(v1[j]); }
;                     } else if (act == 2) {
; #pragma unroll
;                         for (int j = 0; j < 4; ++j) { v0[j] = sigm(v0[j]); v1[j] = sigm(v1[j]); }
;                     }
;                     u32x4 w; w.x = pk_bf16(v0[0], v0[1]); w.y = pk_bf16(v0[2], v0[3]); w.z = pk_bf16(v1[0], v1[1]); w.w = pk_bf16(v1[2], v1[3]);
;                     *(u32x4*)(pb + (size_t)(ai * 128 + m * 16) * NIN) = w;
.LBB0_2432:
	v_add_co_u32_e32 v108, vcc, 0xea000, v120
	v_cvt_pk_bf16_f32 v104, v112, v114
	v_cvt_pk_bf16_f32 v105, v116, v119
	v_cvt_pk_bf16_f32 v106, v113, v115
	v_cvt_pk_bf16_f32 v107, v117, v118
	s_nop 1
	v_addc_co_u32_e32 v109, vcc, 0, v121, vcc
	s_cmp_gt_i32 s11, 1
	s_mov_b64 s[76:77], -1
	global_store_dwordx4 v[108:109], v[104:107], off nt
	s_cbranch_scc0 .LBB0_2434
	v_mul_f32_e32 v110, 0xbfb8aa3b, v103
	v_mul_f32_e32 v104, 0xbfb8aa3b, v100
	v_mul_f32_e32 v105, 0xbfb8aa3b, v96
	v_mul_f32_e32 v106, 0xbfb8aa3b, v101
	v_mul_f32_e32 v107, 0xbfb8aa3b, v97
	v_mul_f32_e32 v108, 0xbfb8aa3b, v102
	v_mul_f32_e32 v109, 0xbfb8aa3b, v98
	v_exp_f32_e32 v110, v110
	v_mul_f32_e32 v111, 0xbfb8aa3b, v99
	v_exp_f32_e32 v104, v104
	v_exp_f32_e32 v105, v105
	v_exp_f32_e32 v106, v106
	v_exp_f32_e32 v107, v107
	v_exp_f32_e32 v108, v108
	v_exp_f32_e32 v109, v109
	v_exp_f32_e32 v112, v111
	v_add_f32_e32 v110, 1.0, v110
	v_add_f32_e32 v104, 1.0, v104
	v_add_f32_e32 v105, 1.0, v105
	v_add_f32_e32 v106, 1.0, v106
	v_add_f32_e32 v107, 1.0, v107
	v_add_f32_e32 v108, 1.0, v108
	v_add_f32_e32 v109, 1.0, v109
	v_rcp_f32_e32 v111, v110
	v_add_f32_e32 v110, 1.0, v112
	v_rcp_f32_e32 v104, v104
	v_rcp_f32_e32 v105, v105
	v_rcp_f32_e32 v106, v106
	v_rcp_f32_e32 v107, v107
	v_rcp_f32_e32 v108, v108
	v_rcp_f32_e32 v109, v109
	v_rcp_f32_e32 v110, v110
	s_mov_b64 s[76:77], 0

; __device__ __forceinline__ unsigned pk_bf16(float lo, float hi) { unsigned r; asm("v_cvt_pk_bf16_f32 %0, %1, %2" : "=v"(r) : "v"(lo), "v"(hi)); return r; }
; __device__ __forceinline__ float sigm(float x) { return __builtin_amdgcn_rcpf(1.f + __expf(-x)); }
;     __device__ __forceinline__ void operator()(f32x4 (&acc)[2][2][4][2], const Unit& u, int wr, int wc, int fr, int fq) const {
;     ...
;                     f32x4 v0 = acc[ai][bj][m][0], v1 = acc[ai][bj][m][1];
;                     if (act == 1) {
; #pragma unroll
;                         for (int j = 0; j < 4; ++j) { v0[j] = v0[j] * sigm(v0[j]); v1[j] = v1[j] * sigm(v1[j]); }
;                     } else if (act == 2) {
; #pragma unroll
;                         for (int j = 0; j < 4; ++j) { v0[j] = sigm(v0[j]); v1[j] = sigm(v1[j]); }
;                     }
;                     u32x4 w; w.x = pk_bf16(v0[0], v0[1]); w.y = pk_bf16(v0[2], v0[3]); w.z = pk_bf16(v1[0], v1[1]); w.w = pk_bf16(v1[2], v1[3]);
;                     *(u32x4*)(pb + (size_t)(ai * 128 + m * 16) * NIN) = w;
.LBB0_2438:
	v_add_co_u32_e32 v100, vcc, 0x15f000, v120
	v_cvt_pk_bf16_f32 v96, v104, v106
	v_cvt_pk_bf16_f32 v97, v108, v111
	v_cvt_pk_bf16_f32 v98, v105, v107
	v_cvt_pk_bf16_f32 v99, v109, v110
	s_nop 1
	v_addc_co_u32_e32 v101, vcc, 0, v121, vcc
	s_cmp_gt_i32 s11, 1
	s_mov_b64 s[76:77], -1
	global_store_dwordx4 v[100:101], v[96:99], off nt
	s_cbranch_scc0 .LBB0_2440
	v_mul_f32_e32 v102, 0xbfb8aa3b, v95
	v_mul_f32_e32 v96, 0xbfb8aa3b, v92
	v_mul_f32_e32 v97, 0xbfb8aa3b, v88
	v_mul_f32_e32 v98, 0xbfb8aa3b, v93
	v_mul_f32_e32 v99, 0xbfb8aa3b, v89
	v_mul_f32_e32 v100, 0xbfb8aa3b, v94
	v_mul_f32_e32 v101, 0xbfb8aa3b, v90
	v_exp_f32_e32 v102, v102
	v_mul_f32_e32 v103, 0xbfb8aa3b, v91
	v_exp_f32_e32 v96, v96
	v_exp_f32_e32 v97, v97
	v_exp_f32_e32 v98, v98
	v_exp_f32_e32 v99, v99
	v_exp_f32_e32 v100, v100
	v_exp_f32_e32 v101, v101
	v_exp_f32_e32 v104, v103
	v_add_f32_e32 v102, 1.0, v102
	v_add_f32_e32 v96, 1.0, v96
	v_add_f32_e32 v97, 1.0, v97
	v_add_f32_e32 v98, 1.0, v98
	v_add_f32_e32 v99, 1.0, v99
	v_add_f32_e32 v100, 1.0, v100
	v_add_f32_e32 v101, 1.0, v101
	v_rcp_f32_e32 v103, v102
	v_add_f32_e32 v102, 1.0, v104
	v_rcp_f32_e32 v96, v96
	v_rcp_f32_e32 v97, v97
	v_rcp_f32_e32 v98, v98
	v_rcp_f32_e32 v99, v99
	v_rcp_f32_e32 v100, v100
	v_rcp_f32_e32 v101, v101
	v_rcp_f32_e32 v102, v102
	s_mov_b64 s[76:77], 0

; __device__ __forceinline__ unsigned pk_bf16(float lo, float hi) { unsigned r; asm("v_cvt_pk_bf16_f32 %0, %1, %2" : "=v"(r) : "v"(lo), "v"(hi)); return r; }
; __device__ __forceinline__ float sigm(float x) { return __builtin_amdgcn_rcpf(1.f + __expf(-x)); }
;     __device__ __forceinline__ void operator()(f32x4 (&acc)[2][2][4][2], const Unit& u, int wr, int wc, int fr, int fq) const {
;     ...
;                     f32x4 v0 = acc[ai][bj][m][0], v1 = acc[ai][bj][m][1];
;                     if (act == 1) {
; #pragma unroll
;                         for (int j = 0; j < 4; ++j) { v0[j] = v0[j] * sigm(v0[j]); v1[j] = v1[j] * sigm(v1[j]); }
;                     } else if (act == 2) {
; #pragma unroll
;                         for (int j = 0; j < 4; ++j) { v0[j] = sigm(v0[j]); v1[j] = sigm(v1[j]); }
;                     }
;                     u32x4 w; w.x = pk_bf16(v0[0], v0[1]); w.y = pk_bf16(v0[2], v0[3]); w.z = pk_bf16(v1[0], v1[1]); w.w = pk_bf16(v1[2], v1[3]);
;                     *(u32x4*)(pb + (size_t)(ai * 128 + m * 16) * NIN) = w;
.LBB0_2444:
	v_add_co_u32_e32 v92, vcc, 0x3a8000, v120
	v_cvt_pk_bf16_f32 v88, v96, v98
	v_cvt_pk_bf16_f32 v89, v100, v103
	v_cvt_pk_bf16_f32 v90, v97, v99
	v_cvt_pk_bf16_f32 v91, v101, v102
	s_nop 1
	v_addc_co_u32_e32 v93, vcc, 0, v121, vcc
	s_cmp_gt_i32 s11, 1
	s_mov_b64 s[76:77], -1
	global_store_dwordx4 v[92:93], v[88:91], off nt
	s_cbranch_scc0 .LBB0_2446
	v_mul_f32_e32 v94, 0xbfb8aa3b, v87
	v_mul_f32_e32 v88, 0xbfb8aa3b, v84
	v_mul_f32_e32 v89, 0xbfb8aa3b, v80
	v_mul_f32_e32 v90, 0xbfb8aa3b, v85
	v_mul_f32_e32 v91, 0xbfb8aa3b, v81
	v_mul_f32_e32 v92, 0xbfb8aa3b, v86
	v_mul_f32_e32 v93, 0xbfb8aa3b, v82
	v_exp_f32_e32 v94, v94
	v_mul_f32_e32 v95, 0xbfb8aa3b, v83
	v_exp_f32_e32 v88, v88
	v_exp_f32_e32 v89, v89
	v_exp_f32_e32 v90, v90
	v_exp_f32_e32 v91, v91
	v_exp_f32_e32 v92, v92
	v_exp_f32_e32 v93, v93
	v_exp_f32_e32 v96, v95
	v_add_f32_e32 v94, 1.0, v94
	v_add_f32_e32 v88, 1.0, v88
	v_add_f32_e32 v89, 1.0, v89
	v_add_f32_e32 v90, 1.0, v90
	v_add_f32_e32 v91, 1.0, v91
	v_add_f32_e32 v92, 1.0, v92
	v_add_f32_e32 v93, 1.0, v93
	v_rcp_f32_e32 v95, v94
	v_add_f32_e32 v94, 1.0, v96
	v_rcp_f32_e32 v88, v88
	v_rcp_f32_e32 v89, v89
	v_rcp_f32_e32 v90, v90
	v_rcp_f32_e32 v91, v91
	v_rcp_f32_e32 v92, v92
	v_rcp_f32_e32 v93, v93
	v_rcp_f32_e32 v94, v94
	s_mov_b64 s[76:77], 0

; __device__ __forceinline__ unsigned pk_bf16(float lo, float hi) { unsigned r; asm("v_cvt_pk_bf16_f32 %0, %1, %2" : "=v"(r) : "v"(lo), "v"(hi)); return r; }
; __device__ __forceinline__ float sigm(float x) { return __builtin_amdgcn_rcpf(1.f + __expf(-x)); }
;     __device__ __forceinline__ void operator()(f32x4 (&acc)[2][2][4][2], const Unit& u, int wr, int wc, int fr, int fq) const {
;     ...
;                     f32x4 v0 = acc[ai][bj][m][0], v1 = acc[ai][bj][m][1];
;                     if (act == 1) {
; #pragma unroll
;                         for (int j = 0; j < 4; ++j) { v0[j] = v0[j] * sigm(v0[j]); v1[j] = v1[j] * sigm(v1[j]); }
;                     } else if (act == 2) {
; #pragma unroll
;                         for (int j = 0; j < 4; ++j) { v0[j] = sigm(v0[j]); v1[j] = sigm(v1[j]); }
;                     }
;                     u32x4 w; w.x = pk_bf16(v0[0], v0[1]); w.y = pk_bf16(v0[2], v0[3]); w.z = pk_bf16(v1[0], v1[1]); w.w = pk_bf16(v1[2], v1[3]);
;                     *(u32x4*)(pb + (size_t)(ai * 128 + m * 16) * NIN) = w;
.LBB0_2450:
	v_add_co_u32_e32 v84, vcc, 0x41d000, v120
	v_cvt_pk_bf16_f32 v80, v88, v90
	v_cvt_pk_bf16_f32 v81, v92, v95
	v_cvt_pk_bf16_f32 v82, v89, v91
	v_cvt_pk_bf16_f32 v83, v93, v94
	s_nop 1
	v_addc_co_u32_e32 v85, vcc, 0, v121, vcc
	s_cmp_gt_i32 s11, 1
	s_mov_b64 s[76:77], -1
	global_store_dwordx4 v[84:85], v[80:83], off nt
	s_cbranch_scc0 .LBB0_2452
	v_mul_f32_e32 v86, 0xbfb8aa3b, v79
	v_mul_f32_e32 v80, 0xbfb8aa3b, v76
	v_mul_f32_e32 v81, 0xbfb8aa3b, v72
	v_mul_f32_e32 v82, 0xbfb8aa3b, v77
	v_mul_f32_e32 v83, 0xbfb8aa3b, v73
	v_mul_f32_e32 v84, 0xbfb8aa3b, v78
	v_mul_f32_e32 v85, 0xbfb8aa3b, v74
	v_exp_f32_e32 v86, v86
	v_mul_f32_e32 v87, 0xbfb8aa3b, v75
	v_exp_f32_e32 v80, v80
	v_exp_f32_e32 v81, v81
	v_exp_f32_e32 v82, v82
	v_exp_f32_e32 v83, v83
	v_exp_f32_e32 v84, v84
	v_exp_f32_e32 v85, v85
	v_exp_f32_e32 v88, v87
	v_add_f32_e32 v86, 1.0, v86
	v_add_f32_e32 v80, 1.0, v80
	v_add_f32_e32 v81, 1.0, v81
	v_add_f32_e32 v82, 1.0, v82
	v_add_f32_e32 v83, 1.0, v83
	v_add_f32_e32 v84, 1.0, v84
	v_add_f32_e32 v85, 1.0, v85
	v_rcp_f32_e32 v87, v86
	v_add_f32_e32 v86, 1.0, v88
	v_rcp_f32_e32 v80, v80
	v_rcp_f32_e32 v81, v81
	v_rcp_f32_e32 v82, v82
	v_rcp_f32_e32 v83, v83
	v_rcp_f32_e32 v84, v84
	v_rcp_f32_e32 v85, v85
	v_rcp_f32_e32 v86, v86
	s_mov_b64 s[76:77], 0

; __device__ __forceinline__ unsigned pk_bf16(float lo, float hi) { unsigned r; asm("v_cvt_pk_bf16_f32 %0, %1, %2" : "=v"(r) : "v"(lo), "v"(hi)); return r; }
; __device__ __forceinline__ float sigm(float x) { return __builtin_amdgcn_rcpf(1.f + __expf(-x)); }
;     __device__ __forceinline__ void operator()(f32x4 (&acc)[2][2][4][2], const Unit& u, int wr, int wc, int fr, int fq) const {
;     ...
;                     f32x4 v0 = acc[ai][bj][m][0], v1 = acc[ai][bj][m][1];
;                     if (act == 1) {
; #pragma unroll
;                         for (int j = 0; j < 4; ++j) { v0[j] = v0[j] * sigm(v0[j]); v1[j] = v1[j] * sigm(v1[j]); }
;                     } else if (act == 2) {
; #pragma unroll
;                         for (int j = 0; j < 4; ++j) { v0[j] = sigm(v0[j]); v1[j] = sigm(v1[j]); }
;                     }
;                     u32x4 w; w.x = pk_bf16(v0[0], v0[1]); w.y = pk_bf16(v0[2], v0[3]); w.z = pk_bf16(v1[0], v1[1]); w.w = pk_bf16(v1[2], v1[3]);
;                     *(u32x4*)(pb + (size_t)(ai * 128 + m * 16) * NIN) = w;
.LBB0_2456:
	v_add_co_u32_e32 v76, vcc, 0x492000, v120
	v_cvt_pk_bf16_f32 v72, v80, v82
	v_cvt_pk_bf16_f32 v73, v84, v87
	v_cvt_pk_bf16_f32 v74, v81, v83
	v_cvt_pk_bf16_f32 v75, v85, v86
	s_nop 1
	v_addc_co_u32_e32 v77, vcc, 0, v121, vcc
	s_cmp_gt_i32 s11, 1
	s_mov_b64 s[76:77], -1
	global_store_dwordx4 v[76:77], v[72:75], off nt
	s_cbranch_scc0 .LBB0_2458
	v_mul_f32_e32 v78, 0xbfb8aa3b, v71
	v_mul_f32_e32 v72, 0xbfb8aa3b, v68
	v_mul_f32_e32 v73, 0xbfb8aa3b, v64
	v_mul_f32_e32 v74, 0xbfb8aa3b, v69
	v_mul_f32_e32 v75, 0xbfb8aa3b, v65
	v_mul_f32_e32 v76, 0xbfb8aa3b, v70
	v_mul_f32_e32 v77, 0xbfb8aa3b, v66
	v_exp_f32_e32 v78, v78
	v_mul_f32_e32 v79, 0xbfb8aa3b, v67
	v_exp_f32_e32 v72, v72
	v_exp_f32_e32 v73, v73
	v_exp_f32_e32 v74, v74
	v_exp_f32_e32 v75, v75
	v_exp_f32_e32 v76, v76
	v_exp_f32_e32 v77, v77
	v_exp_f32_e32 v80, v79
	v_add_f32_e32 v78, 1.0, v78
	v_add_f32_e32 v72, 1.0, v72
	v_add_f32_e32 v73, 1.0, v73
	v_add_f32_e32 v74, 1.0, v74
	v_add_f32_e32 v75, 1.0, v75
	v_add_f32_e32 v76, 1.0, v76
	v_add_f32_e32 v77, 1.0, v77
	v_rcp_f32_e32 v79, v78
	v_add_f32_e32 v78, 1.0, v80
	v_rcp_f32_e32 v72, v72
	v_rcp_f32_e32 v73, v73
	v_rcp_f32_e32 v74, v74
	v_rcp_f32_e32 v75, v75
	v_rcp_f32_e32 v76, v76
	v_rcp_f32_e32 v77, v77
	v_rcp_f32_e32 v78, v78
	s_mov_b64 s[76:77], 0

; __device__ __forceinline__ unsigned pk_bf16(float lo, float hi) { unsigned r; asm("v_cvt_pk_bf16_f32 %0, %1, %2" : "=v"(r) : "v"(lo), "v"(hi)); return r; }
; __device__ __forceinline__ float sigm(float x) { return __builtin_amdgcn_rcpf(1.f + __expf(-x)); }
;     __device__ __forceinline__ void operator()(f32x4 (&acc)[2][2][4][2], const Unit& u, int wr, int wc, int fr, int fq) const {
;     ...
;             const int colb = u.pn * 256 + bj * 128;
;             if (colb >= NIN) continue;
;             const int act = colb >= OFF_MERGE ? 2 : (colb >= OFF_GATE ? 1 : 0);
;             u16* pb = proj + (size_t)(u.pm * 256 + wr * 64 + fr) * NIN + colb + wc * 32 + 8 * fq;
; #pragma unroll
;             for (int ai = 0; ai < 2; ++ai)
; #pragma unroll
;                 for (int m = 0; m < 4; ++m) {
;                     f32x4 v0 = acc[ai][bj][m][0], v1 = acc[ai][bj][m][1];
;                     if (act == 1) {
; #pragma unroll
;                         for (int j = 0; j < 4; ++j) { v0[j] = v0[j] * sigm(v0[j]); v1[j] = v1[j] * sigm(v1[j]); }
;                     } else if (act == 2) {
; #pragma unroll
;                         for (int j = 0; j < 4; ++j) { v0[j] = sigm(v0[j]); v1[j] = sigm(v1[j]); }
;                     }
;                     u32x4 w; w.x = pk_bf16(v0[0], v0[1]); w.y = pk_bf16(v0[2], v0[3]); w.z = pk_bf16(v1[0], v1[1]); w.w = pk_bf16(v1[2], v1[3]);
;                     *(u32x4*)(pb + (size_t)(ai * 128 + m * 16) * NIN) = w;
.LBB0_2470:
	v_readlane_b32 s4, v252, 40
	v_readlane_b32 s5, v252, 41
	v_lshl_add_u32 v58, s66, 8, v139
	s_ashr_i32 s69, s68, 31
	v_mov_b64_e32 v[56:57], s[4:5]
	v_mad_i64_i32 v[56:57], s[4:5], v58, s25, v[56:57]
	v_lshl_add_u64 v[56:57], s[68:69], 1, v[56:57]
	s_lshl_b32 s0, s20, 1
	v_lshl_add_u64 v[56:57], v[56:57], 0, s[0:1]
	v_lshlrev_b32_e32 v136, 1, v138
	v_lshl_add_u64 v[62:63], v[56:57], 0, v[136:137]
	s_mov_b64 s[4:5], 0x100
	v_lshl_add_u64 v[56:57], v[62:63], 0, s[4:5]
	v_cvt_pk_bf16_f32 v58, v64, v66
	v_cvt_pk_bf16_f32 v59, v68, v71
	v_cvt_pk_bf16_f32 v60, v65, v67
	v_cvt_pk_bf16_f32 v61, v69, v70
	s_cmp_gt_i32 s11, 1
	s_mov_b64 s[66:67], -1
	global_store_dwordx4 v[62:63], v[58:61], off offset:256 nt
	s_cbranch_scc0 .LBB0_2472
	v_mul_f32_e32 v64, 0xbfb8aa3b, v55
	v_mul_f32_e32 v58, 0xbfb8aa3b, v52
	v_mul_f32_e32 v59, 0xbfb8aa3b, v48
	v_mul_f32_e32 v60, 0xbfb8aa3b, v53
	v_mul_f32_e32 v61, 0xbfb8aa3b, v49
	v_mul_f32_e32 v62, 0xbfb8aa3b, v54
	v_mul_f32_e32 v63, 0xbfb8aa3b, v50
	v_exp_f32_e32 v64, v64
	v_mul_f32_e32 v65, 0xbfb8aa3b, v51
	v_exp_f32_e32 v58, v58
	v_exp_f32_e32 v59, v59
	v_exp_f32_e32 v60, v60
	v_exp_f32_e32 v61, v61
	v_exp_f32_e32 v62, v62
	v_exp_f32_e32 v63, v63
	v_exp_f32_e32 v66, v65
	v_add_f32_e32 v64, 1.0, v64
	v_add_f32_e32 v58, 1.0, v58
	v_add_f32_e32 v59, 1.0, v59
	v_add_f32_e32 v60, 1.0, v60
	v_add_f32_e32 v61, 1.0, v61
	v_add_f32_e32 v62, 1.0, v62
	v_add_f32_e32 v63, 1.0, v63
	v_rcp_f32_e32 v65, v64
	v_add_f32_e32 v64, 1.0, v66
	v_rcp_f32_e32 v58, v58
	v_rcp_f32_e32 v59, v59
	v_rcp_f32_e32 v60, v60
	v_rcp_f32_e32 v61, v61
	v_rcp_f32_e32 v62, v62
	v_rcp_f32_e32 v63, v63
	v_rcp_f32_e32 v64, v64
	s_mov_b64 s[66:67], 0

; __device__ __forceinline__ unsigned pk_bf16(float lo, float hi) { unsigned r; asm("v_cvt_pk_bf16_f32 %0, %1, %2" : "=v"(r) : "v"(lo), "v"(hi)); return r; }
; __device__ __forceinline__ float sigm(float x) { return __builtin_amdgcn_rcpf(1.f + __expf(-x)); }
;     __device__ __forceinline__ void operator()(f32x4 (&acc)[2][2][4][2], const Unit& u, int wr, int wc, int fr, int fq) const {
;     ...
;                     f32x4 v0 = acc[ai][bj][m][0], v1 = acc[ai][bj][m][1];
;                     if (act == 1) {
; #pragma unroll
;                         for (int j = 0; j < 4; ++j) { v0[j] = v0[j] * sigm(v0[j]); v1[j] = v1[j] * sigm(v1[j]); }
;                     } else if (act == 2) {
; #pragma unroll
;                         for (int j = 0; j < 4; ++j) { v0[j] = sigm(v0[j]); v1[j] = sigm(v1[j]); }
;                     }
;                     u32x4 w; w.x = pk_bf16(v0[0], v0[1]); w.y = pk_bf16(v0[2], v0[3]); w.z = pk_bf16(v1[0], v1[1]); w.w = pk_bf16(v1[2], v1[3]);
;                     *(u32x4*)(pb + (size_t)(ai * 128 + m * 16) * NIN) = w;
.LBB0_2476:
	v_add_co_u32_e32 v52, vcc, 0x75000, v56
	v_cvt_pk_bf16_f32 v48, v58, v60
	v_cvt_pk_bf16_f32 v49, v62, v65
	v_cvt_pk_bf16_f32 v50, v59, v61
	v_cvt_pk_bf16_f32 v51, v63, v64
	s_nop 1
	v_addc_co_u32_e32 v53, vcc, 0, v57, vcc
	s_cmp_gt_i32 s11, 1
	s_mov_b64 s[66:67], -1
	global_store_dwordx4 v[52:53], v[48:51], off nt
	s_cbranch_scc0 .LBB0_2478
	v_mul_f32_e32 v54, 0xbfb8aa3b, v47
	v_mul_f32_e32 v48, 0xbfb8aa3b, v44
	v_mul_f32_e32 v49, 0xbfb8aa3b, v40
	v_mul_f32_e32 v50, 0xbfb8aa3b, v45
	v_mul_f32_e32 v51, 0xbfb8aa3b, v41
	v_mul_f32_e32 v52, 0xbfb8aa3b, v46
	v_mul_f32_e32 v53, 0xbfb8aa3b, v42
	v_exp_f32_e32 v54, v54
	v_mul_f32_e32 v55, 0xbfb8aa3b, v43
	v_exp_f32_e32 v48, v48
	v_exp_f32_e32 v49, v49
	v_exp_f32_e32 v50, v50
	v_exp_f32_e32 v51, v51
	v_exp_f32_e32 v52, v52
	v_exp_f32_e32 v53, v53
	v_exp_f32_e32 v58, v55
	v_add_f32_e32 v54, 1.0, v54
	v_add_f32_e32 v48, 1.0, v48
	v_add_f32_e32 v49, 1.0, v49
	v_add_f32_e32 v50, 1.0, v50
	v_add_f32_e32 v51, 1.0, v51
	v_add_f32_e32 v52, 1.0, v52
	v_add_f32_e32 v53, 1.0, v53
	v_rcp_f32_e32 v55, v54
	v_add_f32_e32 v54, 1.0, v58
	v_rcp_f32_e32 v48, v48
	v_rcp_f32_e32 v49, v49
	v_rcp_f32_e32 v50, v50
	v_rcp_f32_e32 v51, v51
	v_rcp_f32_e32 v52, v52
	v_rcp_f32_e32 v53, v53
	v_rcp_f32_e32 v54, v54
	s_mov_b64 s[66:67], 0

; __device__ __forceinline__ unsigned pk_bf16(float lo, float hi) { unsigned r; asm("v_cvt_pk_bf16_f32 %0, %1, %2" : "=v"(r) : "v"(lo), "v"(hi)); return r; }
; __device__ __forceinline__ float sigm(float x) { return __builtin_amdgcn_rcpf(1.f + __expf(-x)); }
;     __device__ __forceinline__ void operator()(f32x4 (&acc)[2][2][4][2], const Unit& u, int wr, int wc, int fr, int fq) const {
;     ...
;                     f32x4 v0 = acc[ai][bj][m][0], v1 = acc[ai][bj][m][1];
;                     if (act == 1) {
; #pragma unroll
;                         for (int j = 0; j < 4; ++j) { v0[j] = v0[j] * sigm(v0[j]); v1[j] = v1[j] * sigm(v1[j]); }
;                     } else if (act == 2) {
; #pragma unroll
;                         for (int j = 0; j < 4; ++j) { v0[j] = sigm(v0[j]); v1[j] = sigm(v1[j]); }
;                     }
;                     u32x4 w; w.x = pk_bf16(v0[0], v0[1]); w.y = pk_bf16(v0[2], v0[3]); w.z = pk_bf16(v1[0], v1[1]); w.w = pk_bf16(v1[2], v1[3]);
;                     *(u32x4*)(pb + (size_t)(ai * 128 + m * 16) * NIN) = w;
.LBB0_2482:
	v_add_co_u32_e32 v44, vcc, 0xea000, v56
	v_cvt_pk_bf16_f32 v40, v48, v50
	v_cvt_pk_bf16_f32 v41, v52, v55
	v_cvt_pk_bf16_f32 v42, v49, v51
	v_cvt_pk_bf16_f32 v43, v53, v54
	s_nop 1
	v_addc_co_u32_e32 v45, vcc, 0, v57, vcc
	s_cmp_gt_i32 s11, 1
	s_mov_b64 s[66:67], -1
	global_store_dwordx4 v[44:45], v[40:43], off nt
	s_cbranch_scc0 .LBB0_2484
	v_mul_f32_e32 v46, 0xbfb8aa3b, v39
	v_mul_f32_e32 v40, 0xbfb8aa3b, v36
	v_mul_f32_e32 v41, 0xbfb8aa3b, v32
	v_mul_f32_e32 v42, 0xbfb8aa3b, v37
	v_mul_f32_e32 v43, 0xbfb8aa3b, v33
	v_mul_f32_e32 v44, 0xbfb8aa3b, v38
	v_mul_f32_e32 v45, 0xbfb8aa3b, v34
	v_exp_f32_e32 v46, v46
	v_mul_f32_e32 v47, 0xbfb8aa3b, v35
	v_exp_f32_e32 v40, v40
	v_exp_f32_e32 v41, v41
	v_exp_f32_e32 v42, v42
	v_exp_f32_e32 v43, v43
	v_exp_f32_e32 v44, v44
	v_exp_f32_e32 v45, v45
	v_exp_f32_e32 v48, v47
	v_add_f32_e32 v46, 1.0, v46
	v_add_f32_e32 v40, 1.0, v40
	v_add_f32_e32 v41, 1.0, v41
	v_add_f32_e32 v42, 1.0, v42
	v_add_f32_e32 v43, 1.0, v43
	v_add_f32_e32 v44, 1.0, v44
	v_add_f32_e32 v45, 1.0, v45
	v_rcp_f32_e32 v47, v46
	v_add_f32_e32 v46, 1.0, v48
	v_rcp_f32_e32 v40, v40
	v_rcp_f32_e32 v41, v41
	v_rcp_f32_e32 v42, v42
	v_rcp_f32_e32 v43, v43
	v_rcp_f32_e32 v44, v44
	v_rcp_f32_e32 v45, v45
	v_rcp_f32_e32 v46, v46
	s_mov_b64 s[66:67], 0

; __device__ __forceinline__ unsigned pk_bf16(float lo, float hi) { unsigned r; asm("v_cvt_pk_bf16_f32 %0, %1, %2" : "=v"(r) : "v"(lo), "v"(hi)); return r; }
; __device__ __forceinline__ float sigm(float x) { return __builtin_amdgcn_rcpf(1.f + __expf(-x)); }
;     __device__ __forceinline__ void operator()(f32x4 (&acc)[2][2][4][2], const Unit& u, int wr, int wc, int fr, int fq) const {
;     ...
;                     f32x4 v0 = acc[ai][bj][m][0], v1 = acc[ai][bj][m][1];
;                     if (act == 1) {
; #pragma unroll
;                         for (int j = 0; j < 4; ++j) { v0[j] = v0[j] * sigm(v0[j]); v1[j] = v1[j] * sigm(v1[j]); }
;                     } else if (act == 2) {
; #pragma unroll
;                         for (int j = 0; j < 4; ++j) { v0[j] = sigm(v0[j]); v1[j] = sigm(v1[j]); }
;                     }
;                     u32x4 w; w.x = pk_bf16(v0[0], v0[1]); w.y = pk_bf16(v0[2], v0[3]); w.z = pk_bf16(v1[0], v1[1]); w.w = pk_bf16(v1[2], v1[3]);
;                     *(u32x4*)(pb + (size_t)(ai * 128 + m * 16) * NIN) = w;
.LBB0_2488:
	v_add_co_u32_e32 v36, vcc, 0x15f000, v56
	v_cvt_pk_bf16_f32 v32, v40, v42
	v_cvt_pk_bf16_f32 v33, v44, v47
	v_cvt_pk_bf16_f32 v34, v41, v43
	v_cvt_pk_bf16_f32 v35, v45, v46
	s_nop 1
	v_addc_co_u32_e32 v37, vcc, 0, v57, vcc
	s_cmp_gt_i32 s11, 1
	s_mov_b64 s[66:67], -1
	global_store_dwordx4 v[36:37], v[32:35], off nt
	s_cbranch_scc0 .LBB0_2490
	v_mul_f32_e32 v38, 0xbfb8aa3b, v31
	v_mul_f32_e32 v32, 0xbfb8aa3b, v28
	v_mul_f32_e32 v33, 0xbfb8aa3b, v24
	v_mul_f32_e32 v34, 0xbfb8aa3b, v29
	v_mul_f32_e32 v35, 0xbfb8aa3b, v25
	v_mul_f32_e32 v36, 0xbfb8aa3b, v30
	v_mul_f32_e32 v37, 0xbfb8aa3b, v26
	v_exp_f32_e32 v38, v38
	v_mul_f32_e32 v39, 0xbfb8aa3b, v27
	v_exp_f32_e32 v32, v32
	v_exp_f32_e32 v33, v33
	v_exp_f32_e32 v34, v34
	v_exp_f32_e32 v35, v35
	v_exp_f32_e32 v36, v36
	v_exp_f32_e32 v37, v37
	v_exp_f32_e32 v40, v39
	v_add_f32_e32 v38, 1.0, v38
	v_add_f32_e32 v32, 1.0, v32
	v_add_f32_e32 v33, 1.0, v33
	v_add_f32_e32 v34, 1.0, v34
	v_add_f32_e32 v35, 1.0, v35
	v_add_f32_e32 v36, 1.0, v36
	v_add_f32_e32 v37, 1.0, v37
	v_rcp_f32_e32 v39, v38
	v_add_f32_e32 v38, 1.0, v40
	v_rcp_f32_e32 v32, v32
	v_rcp_f32_e32 v33, v33
	v_rcp_f32_e32 v34, v34
	v_rcp_f32_e32 v35, v35
	v_rcp_f32_e32 v36, v36
	v_rcp_f32_e32 v37, v37
	v_rcp_f32_e32 v38, v38
	s_mov_b64 s[66:67], 0

; __device__ __forceinline__ unsigned pk_bf16(float lo, float hi) { unsigned r; asm("v_cvt_pk_bf16_f32 %0, %1, %2" : "=v"(r) : "v"(lo), "v"(hi)); return r; }
; __device__ __forceinline__ float sigm(float x) { return __builtin_amdgcn_rcpf(1.f + __expf(-x)); }
;     __device__ __forceinline__ void operator()(f32x4 (&acc)[2][2][4][2], const Unit& u, int wr, int wc, int fr, int fq) const {
;     ...
;                     f32x4 v0 = acc[ai][bj][m][0], v1 = acc[ai][bj][m][1];
;                     if (act == 1) {
; #pragma unroll
;                         for (int j = 0; j < 4; ++j) { v0[j] = v0[j] * sigm(v0[j]); v1[j] = v1[j] * sigm(v1[j]); }
;                     } else if (act == 2) {
; #pragma unroll
;                         for (int j = 0; j < 4; ++j) { v0[j] = sigm(v0[j]); v1[j] = sigm(v1[j]); }
;                     }
;                     u32x4 w; w.x = pk_bf16(v0[0], v0[1]); w.y = pk_bf16(v0[2], v0[3]); w.z = pk_bf16(v1[0], v1[1]); w.w = pk_bf16(v1[2], v1[3]);
;                     *(u32x4*)(pb + (size_t)(ai * 128 + m * 16) * NIN) = w;
.LBB0_2494:
	v_add_co_u32_e32 v28, vcc, 0x3a8000, v56
	v_cvt_pk_bf16_f32 v24, v32, v34
	v_cvt_pk_bf16_f32 v25, v36, v39
	v_cvt_pk_bf16_f32 v26, v33, v35
	v_cvt_pk_bf16_f32 v27, v37, v38
	s_nop 1
	v_addc_co_u32_e32 v29, vcc, 0, v57, vcc
	s_cmp_gt_i32 s11, 1
	s_mov_b64 s[66:67], -1
	global_store_dwordx4 v[28:29], v[24:27], off nt
	s_cbranch_scc0 .LBB0_2496
	v_mul_f32_e32 v30, 0xbfb8aa3b, v23
	v_mul_f32_e32 v24, 0xbfb8aa3b, v20
	v_mul_f32_e32 v25, 0xbfb8aa3b, v16
	v_mul_f32_e32 v26, 0xbfb8aa3b, v21
	v_mul_f32_e32 v27, 0xbfb8aa3b, v17
	v_mul_f32_e32 v28, 0xbfb8aa3b, v22
	v_mul_f32_e32 v29, 0xbfb8aa3b, v18
	v_exp_f32_e32 v30, v30
	v_mul_f32_e32 v31, 0xbfb8aa3b, v19
	v_exp_f32_e32 v24, v24
	v_exp_f32_e32 v25, v25
	v_exp_f32_e32 v26, v26
	v_exp_f32_e32 v27, v27
	v_exp_f32_e32 v28, v28
	v_exp_f32_e32 v29, v29
	v_exp_f32_e32 v32, v31
	v_add_f32_e32 v30, 1.0, v30
	v_add_f32_e32 v24, 1.0, v24
	v_add_f32_e32 v25, 1.0, v25
	v_add_f32_e32 v26, 1.0, v26
	v_add_f32_e32 v27, 1.0, v27
	v_add_f32_e32 v28, 1.0, v28
	v_add_f32_e32 v29, 1.0, v29
	v_rcp_f32_e32 v31, v30
	v_add_f32_e32 v30, 1.0, v32
	v_rcp_f32_e32 v24, v24
	v_rcp_f32_e32 v25, v25
	v_rcp_f32_e32 v26, v26
	v_rcp_f32_e32 v27, v27
	v_rcp_f32_e32 v28, v28
	v_rcp_f32_e32 v29, v29
	v_rcp_f32_e32 v30, v30
	s_mov_b64 s[66:67], 0

; __device__ __forceinline__ unsigned pk_bf16(float lo, float hi) { unsigned r; asm("v_cvt_pk_bf16_f32 %0, %1, %2" : "=v"(r) : "v"(lo), "v"(hi)); return r; }
; __device__ __forceinline__ float sigm(float x) { return __builtin_amdgcn_rcpf(1.f + __expf(-x)); }
;     __device__ __forceinline__ void operator()(f32x4 (&acc)[2][2][4][2], const Unit& u, int wr, int wc, int fr, int fq) const {
;     ...
;                     f32x4 v0 = acc[ai][bj][m][0], v1 = acc[ai][bj][m][1];
;                     if (act == 1) {
; #pragma unroll
;                         for (int j = 0; j < 4; ++j) { v0[j] = v0[j] * sigm(v0[j]); v1[j] = v1[j] * sigm(v1[j]); }
;                     } else if (act == 2) {
; #pragma unroll
;                         for (int j = 0; j < 4; ++j) { v0[j] = sigm(v0[j]); v1[j] = sigm(v1[j]); }
;                     }
;                     u32x4 w; w.x = pk_bf16(v0[0], v0[1]); w.y = pk_bf16(v0[2], v0[3]); w.z = pk_bf16(v1[0], v1[1]); w.w = pk_bf16(v1[2], v1[3]);
;                     *(u32x4*)(pb + (size_t)(ai * 128 + m * 16) * NIN) = w;
.LBB0_2500:
	v_add_co_u32_e32 v20, vcc, 0x41d000, v56
	v_cvt_pk_bf16_f32 v16, v24, v26
	v_cvt_pk_bf16_f32 v17, v28, v31
	v_cvt_pk_bf16_f32 v18, v25, v27
	v_cvt_pk_bf16_f32 v19, v29, v30
	s_nop 1
	v_addc_co_u32_e32 v21, vcc, 0, v57, vcc
	s_cmp_gt_i32 s11, 1
	s_mov_b64 s[66:67], -1
	global_store_dwordx4 v[20:21], v[16:19], off nt
	s_cbranch_scc0 .LBB0_2502
	v_mul_f32_e32 v22, 0xbfb8aa3b, v15
	v_mul_f32_e32 v16, 0xbfb8aa3b, v12
	v_mul_f32_e32 v17, 0xbfb8aa3b, v8
	v_mul_f32_e32 v18, 0xbfb8aa3b, v13
	v_mul_f32_e32 v19, 0xbfb8aa3b, v9
	v_mul_f32_e32 v20, 0xbfb8aa3b, v14
	v_mul_f32_e32 v21, 0xbfb8aa3b, v10
	v_exp_f32_e32 v22, v22
	v_mul_f32_e32 v23, 0xbfb8aa3b, v11
	v_exp_f32_e32 v16, v16
	v_exp_f32_e32 v17, v17
	v_exp_f32_e32 v18, v18
	v_exp_f32_e32 v19, v19
	v_exp_f32_e32 v20, v20
	v_exp_f32_e32 v21, v21
	v_exp_f32_e32 v24, v23
	v_add_f32_e32 v22, 1.0, v22
	v_add_f32_e32 v16, 1.0, v16
	v_add_f32_e32 v17, 1.0, v17
	v_add_f32_e32 v18, 1.0, v18
	v_add_f32_e32 v19, 1.0, v19
	v_add_f32_e32 v20, 1.0, v20
	v_add_f32_e32 v21, 1.0, v21
	v_rcp_f32_e32 v23, v22
	v_add_f32_e32 v22, 1.0, v24
	v_rcp_f32_e32 v16, v16
	v_rcp_f32_e32 v17, v17
	v_rcp_f32_e32 v18, v18
	v_rcp_f32_e32 v19, v19
	v_rcp_f32_e32 v20, v20
	v_rcp_f32_e32 v21, v21
	v_rcp_f32_e32 v22, v22
	s_mov_b64 s[66:67], 0

; __device__ __forceinline__ unsigned pk_bf16(float lo, float hi) { unsigned r; asm("v_cvt_pk_bf16_f32 %0, %1, %2" : "=v"(r) : "v"(lo), "v"(hi)); return r; }
; __device__ __forceinline__ float sigm(float x) { return __builtin_amdgcn_rcpf(1.f + __expf(-x)); }
;     __device__ __forceinline__ void operator()(f32x4 (&acc)[2][2][4][2], const Unit& u, int wr, int wc, int fr, int fq) const {
;     ...
;                     f32x4 v0 = acc[ai][bj][m][0], v1 = acc[ai][bj][m][1];
;                     if (act == 1) {
; #pragma unroll
;                         for (int j = 0; j < 4; ++j) { v0[j] = v0[j] * sigm(v0[j]); v1[j] = v1[j] * sigm(v1[j]); }
;                     } else if (act == 2) {
; #pragma unroll
;                         for (int j = 0; j < 4; ++j) { v0[j] = sigm(v0[j]); v1[j] = sigm(v1[j]); }
;                     }
;                     u32x4 w; w.x = pk_bf16(v0[0], v0[1]); w.y = pk_bf16(v0[2], v0[3]); w.z = pk_bf16(v1[0], v1[1]); w.w = pk_bf16(v1[2], v1[3]);
;                     *(u32x4*)(pb + (size_t)(ai * 128 + m * 16) * NIN) = w;
.LBB0_2506:
	v_add_co_u32_e32 v12, vcc, 0x492000, v56
	v_cvt_pk_bf16_f32 v8, v16, v18
	v_cvt_pk_bf16_f32 v9, v20, v23
	v_cvt_pk_bf16_f32 v10, v17, v19
	v_cvt_pk_bf16_f32 v11, v21, v22
	s_nop 1
	v_addc_co_u32_e32 v13, vcc, 0, v57, vcc
	s_cmp_gt_i32 s11, 1
	s_mov_b64 s[66:67], -1
	global_store_dwordx4 v[12:13], v[8:11], off nt
	s_cbranch_scc0 .LBB0_2508
	v_mul_f32_e32 v14, 0xbfb8aa3b, v7
	v_mul_f32_e32 v8, 0xbfb8aa3b, v4
	v_mul_f32_e32 v9, 0xbfb8aa3b, v0
	v_mul_f32_e32 v10, 0xbfb8aa3b, v5
	v_mul_f32_e32 v11, 0xbfb8aa3b, v1
	v_mul_f32_e32 v12, 0xbfb8aa3b, v6
	v_mul_f32_e32 v13, 0xbfb8aa3b, v2
	v_exp_f32_e32 v14, v14
	v_mul_f32_e32 v15, 0xbfb8aa3b, v3
	v_exp_f32_e32 v8, v8
	v_exp_f32_e32 v9, v9
	v_exp_f32_e32 v10, v10
	v_exp_f32_e32 v11, v11
	v_exp_f32_e32 v12, v12
	v_exp_f32_e32 v13, v13
	v_exp_f32_e32 v16, v15
	v_add_f32_e32 v14, 1.0, v14
	v_add_f32_e32 v8, 1.0, v8
	v_add_f32_e32 v9, 1.0, v9
	v_add_f32_e32 v10, 1.0, v10
	v_add_f32_e32 v11, 1.0, v11
	v_add_f32_e32 v12, 1.0, v12
	v_add_f32_e32 v13, 1.0, v13
	v_rcp_f32_e32 v15, v14
	v_add_f32_e32 v14, 1.0, v16
	v_rcp_f32_e32 v8, v8
	v_rcp_f32_e32 v9, v9
	v_rcp_f32_e32 v10, v10
	v_rcp_f32_e32 v11, v11
	v_rcp_f32_e32 v12, v12
	v_rcp_f32_e32 v13, v13
	v_rcp_f32_e32 v14, v14
	s_mov_b64 s[66:67], 0

; __device__ __forceinline__ unsigned pk_bf16(float lo, float hi) { unsigned r; asm("v_cvt_pk_bf16_f32 %0, %1, %2" : "=v"(r) : "v"(lo), "v"(hi)); return r; }
; __device__ __forceinline__ float sigm(float x) { return __builtin_amdgcn_rcpf(1.f + __expf(-x)); }
;     __device__ __forceinline__ void operator()(f32x4 (&acc)[2][2][4][2], const Unit& u, int wr, int wc, int fr, int fq) const {
;     ...
;             const int colb = u.pn * 256 + bj * 128;
;             if (colb >= NIN) continue;
;             const int act = colb >= OFF_MERGE ? 2 : (colb >= OFF_GATE ? 1 : 0);
;             u16* pb = proj + (size_t)(u.pm * 256 + wr * 64 + fr) * NIN + colb + wc * 32 + 8 * fq;
; #pragma unroll
;             for (int ai = 0; ai < 2; ++ai)
; #pragma unroll
;                 for (int m = 0; m < 4; ++m) {
;                     f32x4 v0 = acc[ai][bj][m][0], v1 = acc[ai][bj][m][1];
;                     if (act == 1) {
; #pragma unroll
;                         for (int j = 0; j < 4; ++j) { v0[j] = v0[j] * sigm(v0[j]); v1[j] = v1[j] * sigm(v1[j]); }
;                     } else if (act == 2) {
; #pragma unroll
;                         for (int j = 0; j < 4; ++j) { v0[j] = sigm(v0[j]); v1[j] = sigm(v1[j]); }
;                     }
;                     u32x4 w; w.x = pk_bf16(v0[0], v0[1]); w.y = pk_bf16(v0[2], v0[3]); w.z = pk_bf16(v1[0], v1[1]); w.w = pk_bf16(v1[2], v1[3]);
;                     *(u32x4*)(pb + (size_t)(ai * 128 + m * 16) * NIN) = w;
.LBB0_3607:
	v_readlane_b32 s4, v252, 40
	v_readlane_b32 s5, v252, 41
	v_lshl_add_u32 v136, s8, 8, v139
	s_ashr_i32 s69, s68, 31
	v_mov_b64_e32 v[144:145], s[4:5]
	v_mad_i64_i32 v[144:145], s[4:5], v136, s28, v[144:145]
	v_lshl_add_u64 v[144:145], s[68:69], 1, v[144:145]
	s_lshl_b32 s12, s22, 1
	v_lshl_add_u64 v[144:145], v[144:145], 0, s[12:13]
	v_lshlrev_b32_e32 v136, 1, v138
	v_lshl_add_u64 v[144:145], v[144:145], 0, v[136:137]
	v_cvt_pk_bf16_f32 v146, v146, v147
	v_cvt_pk_bf16_f32 v147, v150, v151
	v_cvt_pk_bf16_f32 v148, v148, v149
	v_cvt_pk_bf16_f32 v149, v152, v153
	s_cmp_gt_i32 s53, 1
	s_mov_b64 s[76:77], -1
	global_store_dwordx4 v[144:145], v[146:149], off nt
	s_cbranch_scc0 .LBB0_3609
	v_mul_f32_e32 v136, 0xbfb8aa3b, v116
	v_exp_f32_e32 v136, v136
	v_mul_f32_e32 v146, 0xbfb8aa3b, v112
	v_exp_f32_e32 v146, v146
	v_mul_f32_e32 v148, 0xbfb8aa3b, v113
	v_add_f32_e32 v136, 1.0, v136
	v_exp_f32_e32 v149, v148
	v_add_f32_e32 v147, 1.0, v146
	v_rcp_f32_e32 v146, v136
	v_mul_f32_e32 v136, 0xbfb8aa3b, v117
	v_exp_f32_e32 v136, v136
	v_rcp_f32_e32 v148, v147
	v_mul_f32_e32 v152, 0xbfb8aa3b, v115
	v_exp_f32_e32 v153, v152
	v_add_f32_e32 v136, 1.0, v136
	v_rcp_f32_e32 v147, v136
	v_add_f32_e32 v136, 1.0, v149
	v_mul_f32_e32 v149, 0xbfb8aa3b, v118
	v_exp_f32_e32 v150, v149
	v_mul_f32_e32 v149, 0xbfb8aa3b, v114
	v_exp_f32_e32 v151, v149
	v_rcp_f32_e32 v149, v136
	v_add_f32_e32 v136, 1.0, v150
	v_rcp_f32_e32 v150, v136
	v_add_f32_e32 v136, 1.0, v151
	v_mul_f32_e32 v151, 0xbfb8aa3b, v119
	v_exp_f32_e32 v151, v151
	v_rcp_f32_e32 v152, v136
	s_mov_b64 s[76:77], 0
	v_add_f32_e32 v136, 1.0, v151
	v_rcp_f32_e32 v151, v136
	v_add_f32_e32 v136, 1.0, v153
	v_rcp_f32_e32 v153, v136

; __device__ __forceinline__ unsigned pk_bf16(float lo, float hi) { unsigned r; asm("v_cvt_pk_bf16_f32 %0, %1, %2" : "=v"(r) : "v"(lo), "v"(hi)); return r; }
; __device__ __forceinline__ float sigm(float x) { return __builtin_amdgcn_rcpf(1.f + __expf(-x)); }
;     __device__ __forceinline__ void operator()(f32x4 (&acc)[2][2][4][2], const Unit& u, int wr, int wc, int fr, int fq) const {
;     ...
;                     f32x4 v0 = acc[ai][bj][m][0], v1 = acc[ai][bj][m][1];
;                     if (act == 1) {
; #pragma unroll
;                         for (int j = 0; j < 4; ++j) { v0[j] = v0[j] * sigm(v0[j]); v1[j] = v1[j] * sigm(v1[j]); }
;                     } else if (act == 2) {
; #pragma unroll
;                         for (int j = 0; j < 4; ++j) { v0[j] = sigm(v0[j]); v1[j] = sigm(v1[j]); }
;                     }
;                     u32x4 w; w.x = pk_bf16(v0[0], v0[1]); w.y = pk_bf16(v0[2], v0[3]); w.z = pk_bf16(v1[0], v1[1]); w.w = pk_bf16(v1[2], v1[3]);
;                     *(u32x4*)(pb + (size_t)(ai * 128 + m * 16) * NIN) = w;
.LBB0_3612:
	v_cvt_pk_bf16_f32 v146, v146, v147
	v_cvt_pk_bf16_f32 v147, v150, v151
	v_add_co_u32_e32 v150, vcc, 0x75000, v144
	v_cvt_pk_bf16_f32 v148, v148, v149
	v_cvt_pk_bf16_f32 v149, v152, v153
	s_cmp_gt_i32 s53, 1
	s_nop 0
	v_addc_co_u32_e32 v151, vcc, 0, v145, vcc
	s_mov_b64 s[76:77], -1
	global_store_dwordx4 v[150:151], v[146:149], off nt
	s_cbranch_scc0 .LBB0_3614
	v_mul_f32_e32 v136, 0xbfb8aa3b, v108
	v_exp_f32_e32 v136, v136
	v_mul_f32_e32 v146, 0xbfb8aa3b, v104
	v_exp_f32_e32 v146, v146
	v_mul_f32_e32 v148, 0xbfb8aa3b, v105
	v_add_f32_e32 v136, 1.0, v136
	v_exp_f32_e32 v149, v148
	v_add_f32_e32 v147, 1.0, v146
	v_rcp_f32_e32 v146, v136
	v_mul_f32_e32 v136, 0xbfb8aa3b, v109
	v_exp_f32_e32 v136, v136
	v_rcp_f32_e32 v148, v147
	v_mul_f32_e32 v152, 0xbfb8aa3b, v107
	v_exp_f32_e32 v153, v152
	v_add_f32_e32 v136, 1.0, v136
	v_rcp_f32_e32 v147, v136
	v_add_f32_e32 v136, 1.0, v149
	v_mul_f32_e32 v149, 0xbfb8aa3b, v110
	v_exp_f32_e32 v150, v149
	v_mul_f32_e32 v149, 0xbfb8aa3b, v106
	v_exp_f32_e32 v151, v149
	v_rcp_f32_e32 v149, v136
	v_add_f32_e32 v136, 1.0, v150
	v_rcp_f32_e32 v150, v136
	v_add_f32_e32 v136, 1.0, v151
	v_mul_f32_e32 v151, 0xbfb8aa3b, v111
	v_exp_f32_e32 v151, v151
	v_rcp_f32_e32 v152, v136
	s_mov_b64 s[76:77], 0
	v_add_f32_e32 v136, 1.0, v151
	v_rcp_f32_e32 v151, v136
	v_add_f32_e32 v136, 1.0, v153
	v_rcp_f32_e32 v153, v136

; __device__ __forceinline__ unsigned pk_bf16(float lo, float hi) { unsigned r; asm("v_cvt_pk_bf16_f32 %0, %1, %2" : "=v"(r) : "v"(lo), "v"(hi)); return r; }
; __device__ __forceinline__ float sigm(float x) { return __builtin_amdgcn_rcpf(1.f + __expf(-x)); }
;     __device__ __forceinline__ void operator()(f32x4 (&acc)[2][2][4][2], const Unit& u, int wr, int wc, int fr, int fq) const {
;     ...
;                     f32x4 v0 = acc[ai][bj][m][0], v1 = acc[ai][bj][m][1];
;                     if (act == 1) {
; #pragma unroll
;                         for (int j = 0; j < 4; ++j) { v0[j] = v0[j] * sigm(v0[j]); v1[j] = v1[j] * sigm(v1[j]); }
;                     } else if (act == 2) {
; #pragma unroll
;                         for (int j = 0; j < 4; ++j) { v0[j] = sigm(v0[j]); v1[j] = sigm(v1[j]); }
;                     }
;                     u32x4 w; w.x = pk_bf16(v0[0], v0[1]); w.y = pk_bf16(v0[2], v0[3]); w.z = pk_bf16(v1[0], v1[1]); w.w = pk_bf16(v1[2], v1[3]);
;                     *(u32x4*)(pb + (size_t)(ai * 128 + m * 16) * NIN) = w;
.LBB0_3617:
	v_cvt_pk_bf16_f32 v146, v146, v147
	v_cvt_pk_bf16_f32 v147, v150, v151
	v_add_co_u32_e32 v150, vcc, 0xea000, v144
	v_cvt_pk_bf16_f32 v148, v148, v149
	v_cvt_pk_bf16_f32 v149, v152, v153
	s_cmp_gt_i32 s53, 1
	s_nop 0
	v_addc_co_u32_e32 v151, vcc, 0, v145, vcc
	s_mov_b64 s[76:77], -1
	global_store_dwordx4 v[150:151], v[146:149], off nt
	s_cbranch_scc0 .LBB0_3619
	v_mul_f32_e32 v136, 0xbfb8aa3b, v100
	v_exp_f32_e32 v136, v136
	v_mul_f32_e32 v146, 0xbfb8aa3b, v96
	v_exp_f32_e32 v146, v146
	v_mul_f32_e32 v148, 0xbfb8aa3b, v97
	v_add_f32_e32 v136, 1.0, v136
	v_exp_f32_e32 v149, v148
	v_add_f32_e32 v147, 1.0, v146
	v_rcp_f32_e32 v146, v136
	v_mul_f32_e32 v136, 0xbfb8aa3b, v101
	v_exp_f32_e32 v136, v136
	v_rcp_f32_e32 v148, v147
	v_mul_f32_e32 v152, 0xbfb8aa3b, v99
	v_exp_f32_e32 v153, v152
	v_add_f32_e32 v136, 1.0, v136
	v_rcp_f32_e32 v147, v136
	v_add_f32_e32 v136, 1.0, v149
	v_mul_f32_e32 v149, 0xbfb8aa3b, v102
	v_exp_f32_e32 v150, v149
	v_mul_f32_e32 v149, 0xbfb8aa3b, v98
	v_exp_f32_e32 v151, v149
	v_rcp_f32_e32 v149, v136
	v_add_f32_e32 v136, 1.0, v150
	v_rcp_f32_e32 v150, v136
	v_add_f32_e32 v136, 1.0, v151
	v_mul_f32_e32 v151, 0xbfb8aa3b, v103
	v_exp_f32_e32 v151, v151
	v_rcp_f32_e32 v152, v136
	s_mov_b64 s[76:77], 0
	v_add_f32_e32 v136, 1.0, v151
	v_rcp_f32_e32 v151, v136
	v_add_f32_e32 v136, 1.0, v153
	v_rcp_f32_e32 v153, v136

; __device__ __forceinline__ unsigned pk_bf16(float lo, float hi) { unsigned r; asm("v_cvt_pk_bf16_f32 %0, %1, %2" : "=v"(r) : "v"(lo), "v"(hi)); return r; }
; __device__ __forceinline__ float sigm(float x) { return __builtin_amdgcn_rcpf(1.f + __expf(-x)); }
;     __device__ __forceinline__ void operator()(f32x4 (&acc)[2][2][4][2], const Unit& u, int wr, int wc, int fr, int fq) const {
;     ...
;                     f32x4 v0 = acc[ai][bj][m][0], v1 = acc[ai][bj][m][1];
;                     if (act == 1) {
; #pragma unroll
;                         for (int j = 0; j < 4; ++j) { v0[j] = v0[j] * sigm(v0[j]); v1[j] = v1[j] * sigm(v1[j]); }
;                     } else if (act == 2) {
; #pragma unroll
;                         for (int j = 0; j < 4; ++j) { v0[j] = sigm(v0[j]); v1[j] = sigm(v1[j]); }
;                     }
;                     u32x4 w; w.x = pk_bf16(v0[0], v0[1]); w.y = pk_bf16(v0[2], v0[3]); w.z = pk_bf16(v1[0], v1[1]); w.w = pk_bf16(v1[2], v1[3]);
;                     *(u32x4*)(pb + (size_t)(ai * 128 + m * 16) * NIN) = w;
.LBB0_3622:
	v_cvt_pk_bf16_f32 v146, v146, v147
	v_cvt_pk_bf16_f32 v147, v150, v151
	v_add_co_u32_e32 v150, vcc, 0x15f000, v144
	v_cvt_pk_bf16_f32 v148, v148, v149
	v_cvt_pk_bf16_f32 v149, v152, v153
	s_cmp_gt_i32 s53, 1
	s_nop 0
	v_addc_co_u32_e32 v151, vcc, 0, v145, vcc
	s_mov_b64 s[76:77], -1
	global_store_dwordx4 v[150:151], v[146:149], off nt
	s_cbranch_scc0 .LBB0_3624
	v_mul_f32_e32 v136, 0xbfb8aa3b, v60
	v_exp_f32_e32 v136, v136
	v_mul_f32_e32 v146, 0xbfb8aa3b, v56
	v_exp_f32_e32 v146, v146
	v_mul_f32_e32 v148, 0xbfb8aa3b, v57
	v_add_f32_e32 v136, 1.0, v136
	v_exp_f32_e32 v149, v148
	v_add_f32_e32 v147, 1.0, v146
	v_rcp_f32_e32 v146, v136
	v_mul_f32_e32 v136, 0xbfb8aa3b, v61
	v_exp_f32_e32 v136, v136
	v_rcp_f32_e32 v148, v147
	v_mul_f32_e32 v152, 0xbfb8aa3b, v59
	v_exp_f32_e32 v153, v152
	v_add_f32_e32 v136, 1.0, v136
	v_rcp_f32_e32 v147, v136
	v_add_f32_e32 v136, 1.0, v149
	v_mul_f32_e32 v149, 0xbfb8aa3b, v62
	v_exp_f32_e32 v150, v149
	v_mul_f32_e32 v149, 0xbfb8aa3b, v58
	v_exp_f32_e32 v151, v149
	v_rcp_f32_e32 v149, v136
	v_add_f32_e32 v136, 1.0, v150
	v_rcp_f32_e32 v150, v136
	v_add_f32_e32 v136, 1.0, v151
	v_mul_f32_e32 v151, 0xbfb8aa3b, v63
	v_exp_f32_e32 v151, v151
	v_rcp_f32_e32 v152, v136
	s_mov_b64 s[76:77], 0
	v_add_f32_e32 v136, 1.0, v151
	v_rcp_f32_e32 v151, v136
	v_add_f32_e32 v136, 1.0, v153
	v_rcp_f32_e32 v153, v136

; __device__ __forceinline__ unsigned pk_bf16(float lo, float hi) { unsigned r; asm("v_cvt_pk_bf16_f32 %0, %1, %2" : "=v"(r) : "v"(lo), "v"(hi)); return r; }
; __device__ __forceinline__ float sigm(float x) { return __builtin_amdgcn_rcpf(1.f + __expf(-x)); }
;     __device__ __forceinline__ void operator()(f32x4 (&acc)[2][2][4][2], const Unit& u, int wr, int wc, int fr, int fq) const {
;     ...
;                     f32x4 v0 = acc[ai][bj][m][0], v1 = acc[ai][bj][m][1];
;                     if (act == 1) {
; #pragma unroll
;                         for (int j = 0; j < 4; ++j) { v0[j] = v0[j] * sigm(v0[j]); v1[j] = v1[j] * sigm(v1[j]); }
;                     } else if (act == 2) {
; #pragma unroll
;                         for (int j = 0; j < 4; ++j) { v0[j] = sigm(v0[j]); v1[j] = sigm(v1[j]); }
;                     }
;                     u32x4 w; w.x = pk_bf16(v0[0], v0[1]); w.y = pk_bf16(v0[2], v0[3]); w.z = pk_bf16(v1[0], v1[1]); w.w = pk_bf16(v1[2], v1[3]);
;                     *(u32x4*)(pb + (size_t)(ai * 128 + m * 16) * NIN) = w;
.LBB0_3627:
	v_cvt_pk_bf16_f32 v146, v146, v147
	v_cvt_pk_bf16_f32 v147, v150, v151
	v_add_co_u32_e32 v150, vcc, 0x3a8000, v144
	v_cvt_pk_bf16_f32 v148, v148, v149
	v_cvt_pk_bf16_f32 v149, v152, v153
	s_cmp_gt_i32 s53, 1
	s_nop 0
	v_addc_co_u32_e32 v151, vcc, 0, v145, vcc
	s_mov_b64 s[76:77], -1
	global_store_dwordx4 v[150:151], v[146:149], off nt
	s_cbranch_scc0 .LBB0_3629
	v_mul_f32_e32 v136, 0xbfb8aa3b, v52
	v_exp_f32_e32 v136, v136
	v_mul_f32_e32 v146, 0xbfb8aa3b, v48
	v_exp_f32_e32 v146, v146
	v_mul_f32_e32 v148, 0xbfb8aa3b, v49
	v_add_f32_e32 v136, 1.0, v136
	v_exp_f32_e32 v149, v148
	v_add_f32_e32 v147, 1.0, v146
	v_rcp_f32_e32 v146, v136
	v_mul_f32_e32 v136, 0xbfb8aa3b, v53
	v_exp_f32_e32 v136, v136
	v_rcp_f32_e32 v148, v147
	v_mul_f32_e32 v152, 0xbfb8aa3b, v51
	v_exp_f32_e32 v153, v152
	v_add_f32_e32 v136, 1.0, v136
	v_rcp_f32_e32 v147, v136
	v_add_f32_e32 v136, 1.0, v149
	v_mul_f32_e32 v149, 0xbfb8aa3b, v54
	v_exp_f32_e32 v150, v149
	v_mul_f32_e32 v149, 0xbfb8aa3b, v50
	v_exp_f32_e32 v151, v149
	v_rcp_f32_e32 v149, v136
	v_add_f32_e32 v136, 1.0, v150
	v_rcp_f32_e32 v150, v136
	v_add_f32_e32 v136, 1.0, v151
	v_mul_f32_e32 v151, 0xbfb8aa3b, v55
	v_exp_f32_e32 v151, v151
	v_rcp_f32_e32 v152, v136
	s_mov_b64 s[76:77], 0
	v_add_f32_e32 v136, 1.0, v151
	v_rcp_f32_e32 v151, v136
	v_add_f32_e32 v136, 1.0, v153
	v_rcp_f32_e32 v153, v136

; __device__ __forceinline__ unsigned pk_bf16(float lo, float hi) { unsigned r; asm("v_cvt_pk_bf16_f32 %0, %1, %2" : "=v"(r) : "v"(lo), "v"(hi)); return r; }
; __device__ __forceinline__ float sigm(float x) { return __builtin_amdgcn_rcpf(1.f + __expf(-x)); }
;     __device__ __forceinline__ void operator()(f32x4 (&acc)[2][2][4][2], const Unit& u, int wr, int wc, int fr, int fq) const {
;     ...
;                     f32x4 v0 = acc[ai][bj][m][0], v1 = acc[ai][bj][m][1];
;                     if (act == 1) {
; #pragma unroll
;                         for (int j = 0; j < 4; ++j) { v0[j] = v0[j] * sigm(v0[j]); v1[j] = v1[j] * sigm(v1[j]); }
;                     } else if (act == 2) {
; #pragma unroll
;                         for (int j = 0; j < 4; ++j) { v0[j] = sigm(v0[j]); v1[j] = sigm(v1[j]); }
;                     }
;                     u32x4 w; w.x = pk_bf16(v0[0], v0[1]); w.y = pk_bf16(v0[2], v0[3]); w.z = pk_bf16(v1[0], v1[1]); w.w = pk_bf16(v1[2], v1[3]);
;                     *(u32x4*)(pb + (size_t)(ai * 128 + m * 16) * NIN) = w;
.LBB0_3632:
	v_cvt_pk_bf16_f32 v146, v146, v147
	v_cvt_pk_bf16_f32 v147, v150, v151
	v_add_co_u32_e32 v150, vcc, 0x41d000, v144
	v_cvt_pk_bf16_f32 v148, v148, v149
	v_cvt_pk_bf16_f32 v149, v152, v153
	s_cmp_gt_i32 s53, 1
	s_nop 0
	v_addc_co_u32_e32 v151, vcc, 0, v145, vcc
	s_mov_b64 s[76:77], -1
	global_store_dwordx4 v[150:151], v[146:149], off nt
	s_cbranch_scc0 .LBB0_3634
	v_mul_f32_e32 v136, 0xbfb8aa3b, v44
	v_exp_f32_e32 v136, v136
	v_mul_f32_e32 v146, 0xbfb8aa3b, v40
	v_exp_f32_e32 v146, v146
	v_mul_f32_e32 v148, 0xbfb8aa3b, v41
	v_add_f32_e32 v136, 1.0, v136
	v_exp_f32_e32 v149, v148
	v_add_f32_e32 v147, 1.0, v146
	v_rcp_f32_e32 v146, v136
	v_mul_f32_e32 v136, 0xbfb8aa3b, v45
	v_exp_f32_e32 v136, v136
	v_rcp_f32_e32 v148, v147
	v_mul_f32_e32 v152, 0xbfb8aa3b, v43
	v_exp_f32_e32 v153, v152
	v_add_f32_e32 v136, 1.0, v136
	v_rcp_f32_e32 v147, v136
	v_add_f32_e32 v136, 1.0, v149
	v_mul_f32_e32 v149, 0xbfb8aa3b, v46
	v_exp_f32_e32 v150, v149
	v_mul_f32_e32 v149, 0xbfb8aa3b, v42
	v_exp_f32_e32 v151, v149
	v_rcp_f32_e32 v149, v136
	v_add_f32_e32 v136, 1.0, v150
	v_rcp_f32_e32 v150, v136
	v_add_f32_e32 v136, 1.0, v151
	v_mul_f32_e32 v151, 0xbfb8aa3b, v47
	v_exp_f32_e32 v151, v151
	v_rcp_f32_e32 v152, v136
	s_mov_b64 s[76:77], 0
	v_add_f32_e32 v136, 1.0, v151
	v_rcp_f32_e32 v151, v136
	v_add_f32_e32 v136, 1.0, v153
	v_rcp_f32_e32 v153, v136

; __device__ __forceinline__ unsigned pk_bf16(float lo, float hi) { unsigned r; asm("v_cvt_pk_bf16_f32 %0, %1, %2" : "=v"(r) : "v"(lo), "v"(hi)); return r; }
; __device__ __forceinline__ float sigm(float x) { return __builtin_amdgcn_rcpf(1.f + __expf(-x)); }
;     __device__ __forceinline__ void operator()(f32x4 (&acc)[2][2][4][2], const Unit& u, int wr, int wc, int fr, int fq) const {
;     ...
;                     f32x4 v0 = acc[ai][bj][m][0], v1 = acc[ai][bj][m][1];
;                     if (act == 1) {
; #pragma unroll
;                         for (int j = 0; j < 4; ++j) { v0[j] = v0[j] * sigm(v0[j]); v1[j] = v1[j] * sigm(v1[j]); }
;                     } else if (act == 2) {
; #pragma unroll
;                         for (int j = 0; j < 4; ++j) { v0[j] = sigm(v0[j]); v1[j] = sigm(v1[j]); }
;                     }
;                     u32x4 w; w.x = pk_bf16(v0[0], v0[1]); w.y = pk_bf16(v0[2], v0[3]); w.z = pk_bf16(v1[0], v1[1]); w.w = pk_bf16(v1[2], v1[3]);
;                     *(u32x4*)(pb + (size_t)(ai * 128 + m * 16) * NIN) = w;
.LBB0_3637:
	v_cvt_pk_bf16_f32 v146, v146, v147
	v_cvt_pk_bf16_f32 v147, v150, v151
	v_add_co_u32_e32 v150, vcc, 0x492000, v144
	v_cvt_pk_bf16_f32 v148, v148, v149
	v_cvt_pk_bf16_f32 v149, v152, v153
	s_cmp_gt_i32 s53, 1
	s_nop 0
	v_addc_co_u32_e32 v151, vcc, 0, v145, vcc
	s_mov_b64 s[76:77], -1
	global_store_dwordx4 v[150:151], v[146:149], off nt
	s_cbranch_scc0 .LBB0_3639
	v_mul_f32_e32 v136, 0xbfb8aa3b, v36
	v_exp_f32_e32 v136, v136
	v_mul_f32_e32 v146, 0xbfb8aa3b, v32
	v_exp_f32_e32 v146, v146
	v_mul_f32_e32 v148, 0xbfb8aa3b, v33
	v_add_f32_e32 v136, 1.0, v136
	v_exp_f32_e32 v149, v148
	v_add_f32_e32 v147, 1.0, v146
	v_rcp_f32_e32 v146, v136
	v_mul_f32_e32 v136, 0xbfb8aa3b, v37
	v_exp_f32_e32 v136, v136
	v_rcp_f32_e32 v148, v147
	v_mul_f32_e32 v152, 0xbfb8aa3b, v35
	v_exp_f32_e32 v153, v152
	v_add_f32_e32 v136, 1.0, v136
	v_rcp_f32_e32 v147, v136
	v_add_f32_e32 v136, 1.0, v149
	v_mul_f32_e32 v149, 0xbfb8aa3b, v38
	v_exp_f32_e32 v150, v149
	v_mul_f32_e32 v149, 0xbfb8aa3b, v34
	v_exp_f32_e32 v151, v149
	v_rcp_f32_e32 v149, v136
	v_add_f32_e32 v136, 1.0, v150
	v_rcp_f32_e32 v150, v136
	v_add_f32_e32 v136, 1.0, v151
	v_mul_f32_e32 v151, 0xbfb8aa3b, v39
	v_exp_f32_e32 v151, v151
	v_rcp_f32_e32 v152, v136
	s_mov_b64 s[76:77], 0
	v_add_f32_e32 v136, 1.0, v151
	v_rcp_f32_e32 v151, v136
	v_add_f32_e32 v136, 1.0, v153
	v_rcp_f32_e32 v153, v136

; __device__ __forceinline__ unsigned pk_bf16(float lo, float hi) { unsigned r; asm("v_cvt_pk_bf16_f32 %0, %1, %2" : "=v"(r) : "v"(lo), "v"(hi)); return r; }
; __device__ __forceinline__ float sigm(float x) { return __builtin_amdgcn_rcpf(1.f + __expf(-x)); }
;     __device__ __forceinline__ void operator()(f32x4 (&acc)[2][2][4][2], const Unit& u, int wr, int wc, int fr, int fq) const {
;     ...
;         for (int bj = 0; bj < 2; ++bj) {
;             const int colb = u.pn * 256 + bj * 128;
;             if (colb >= NIN) continue;
;             const int act = colb >= OFF_MERGE ? 2 : (colb >= OFF_GATE ? 1 : 0);
;             u16* pb = proj + (size_t)(u.pm * 256 + wr * 64 + fr) * NIN + colb + wc * 32 + 8 * fq;
; #pragma unroll
;             for (int ai = 0; ai < 2; ++ai)
; #pragma unroll
;                 for (int m = 0; m < 4; ++m) {
;                     f32x4 v0 = acc[ai][bj][m][0], v1 = acc[ai][bj][m][1];
;                     if (act == 1) {
; #pragma unroll
;                         for (int j = 0; j < 4; ++j) { v0[j] = v0[j] * sigm(v0[j]); v1[j] = v1[j] * sigm(v1[j]); }
;                     } else if (act == 2) {
; #pragma unroll
;                         for (int j = 0; j < 4; ++j) { v0[j] = sigm(v0[j]); v1[j] = sigm(v1[j]); }
;                     }
;                     u32x4 w; w.x = pk_bf16(v0[0], v0[1]); w.y = pk_bf16(v0[2], v0[3]); w.z = pk_bf16(v1[0], v1[1]); w.w = pk_bf16(v1[2], v1[3]);
;                     *(u32x4*)(pb + (size_t)(ai * 128 + m * 16) * NIN) = w;
.LBB0_3642:
	v_add_co_u32_e32 v144, vcc, 0x507000, v144
	v_cvt_pk_bf16_f32 v146, v146, v147
	v_cvt_pk_bf16_f32 v147, v150, v151
	v_cvt_pk_bf16_f32 v148, v148, v149
	v_cvt_pk_bf16_f32 v149, v152, v153
	s_nop 1
	v_addc_co_u32_e32 v145, vcc, 0, v145, vcc
	global_store_dwordx4 v[144:145], v[146:149], off nt
	s_or_b32 s4, s68, 0x80
	s_cmpk_gt_i32 s4, 0x3a7f
	s_cbranch_scc0 .LBB0_3645

; __device__ __forceinline__ unsigned pk_bf16(float lo, float hi) { unsigned r; asm("v_cvt_pk_bf16_f32 %0, %1, %2" : "=v"(r) : "v"(lo), "v"(hi)); return r; }
; __device__ __forceinline__ float sigm(float x) { return __builtin_amdgcn_rcpf(1.f + __expf(-x)); }
;     __device__ __forceinline__ void operator()(f32x4 (&acc)[2][2][4][2], const Unit& u, int wr, int wc, int fr, int fq) const {
;     ...
;             const int colb = u.pn * 256 + bj * 128;
;             if (colb >= NIN) continue;
;             const int act = colb >= OFF_MERGE ? 2 : (colb >= OFF_GATE ? 1 : 0);
;             u16* pb = proj + (size_t)(u.pm * 256 + wr * 64 + fr) * NIN + colb + wc * 32 + 8 * fq;
; #pragma unroll
;             for (int ai = 0; ai < 2; ++ai)
; #pragma unroll
;                 for (int m = 0; m < 4; ++m) {
;                     f32x4 v0 = acc[ai][bj][m][0], v1 = acc[ai][bj][m][1];
;                     if (act == 1) {
; #pragma unroll
;                         for (int j = 0; j < 4; ++j) { v0[j] = v0[j] * sigm(v0[j]); v1[j] = v1[j] * sigm(v1[j]); }
;                     } else if (act == 2) {
; #pragma unroll
;                         for (int j = 0; j < 4; ++j) { v0[j] = sigm(v0[j]); v1[j] = sigm(v1[j]); }
;                     }
;                     u32x4 w; w.x = pk_bf16(v0[0], v0[1]); w.y = pk_bf16(v0[2], v0[3]); w.z = pk_bf16(v1[0], v1[1]); w.w = pk_bf16(v1[2], v1[3]);
;                     *(u32x4*)(pb + (size_t)(ai * 128 + m * 16) * NIN) = w;
.LBB0_3650:
	v_readlane_b32 s4, v252, 40
	v_readlane_b32 s5, v252, 41
	v_lshl_add_u32 v136, s8, 8, v139
	s_ashr_i32 s69, s68, 31
	v_mov_b64_e32 v[144:145], s[4:5]
	v_mad_i64_i32 v[144:145], s[4:5], v136, s28, v[144:145]
	v_lshl_add_u64 v[144:145], s[68:69], 1, v[144:145]
	s_lshl_b32 s12, s22, 1
	v_lshl_add_u64 v[144:145], v[144:145], 0, s[12:13]
	v_lshlrev_b32_e32 v136, 1, v138
	v_lshl_add_u64 v[156:157], v[144:145], 0, v[136:137]
	s_mov_b64 s[4:5], 0x100
	v_lshl_add_u64 v[144:145], v[156:157], 0, s[4:5]
	v_cvt_pk_bf16_f32 v146, v146, v147
	v_cvt_pk_bf16_f32 v147, v150, v151
	v_cvt_pk_bf16_f32 v148, v148, v149
	v_cvt_pk_bf16_f32 v149, v152, v153
	s_cmp_gt_i32 s53, 1
	s_mov_b64 s[68:69], -1
	global_store_dwordx4 v[156:157], v[146:149], off offset:256 nt
	s_cbranch_scc0 .LBB0_3652
	v_mul_f32_e32 v136, 0xbfb8aa3b, v84
	v_exp_f32_e32 v136, v136
	v_mul_f32_e32 v146, 0xbfb8aa3b, v80
	v_exp_f32_e32 v146, v146
	v_mul_f32_e32 v148, 0xbfb8aa3b, v81
	v_add_f32_e32 v136, 1.0, v136
	v_exp_f32_e32 v149, v148
	v_add_f32_e32 v147, 1.0, v146
	v_rcp_f32_e32 v146, v136
	v_mul_f32_e32 v136, 0xbfb8aa3b, v85
	v_exp_f32_e32 v136, v136
	v_rcp_f32_e32 v148, v147
	v_mul_f32_e32 v152, 0xbfb8aa3b, v83
	v_exp_f32_e32 v153, v152
	v_add_f32_e32 v136, 1.0, v136
	v_rcp_f32_e32 v147, v136
	v_add_f32_e32 v136, 1.0, v149
	v_mul_f32_e32 v149, 0xbfb8aa3b, v86
	v_exp_f32_e32 v150, v149
	v_mul_f32_e32 v149, 0xbfb8aa3b, v82
	v_exp_f32_e32 v151, v149
	v_rcp_f32_e32 v149, v136
	v_add_f32_e32 v136, 1.0, v150
	v_rcp_f32_e32 v150, v136
	v_add_f32_e32 v136, 1.0, v151
	v_mul_f32_e32 v151, 0xbfb8aa3b, v87
	v_exp_f32_e32 v151, v151
	v_rcp_f32_e32 v152, v136
	s_mov_b64 s[68:69], 0
	v_add_f32_e32 v136, 1.0, v151
	v_rcp_f32_e32 v151, v136
	v_add_f32_e32 v136, 1.0, v153
	v_rcp_f32_e32 v153, v136

; __device__ __forceinline__ unsigned pk_bf16(float lo, float hi) { unsigned r; asm("v_cvt_pk_bf16_f32 %0, %1, %2" : "=v"(r) : "v"(lo), "v"(hi)); return r; }
; __device__ __forceinline__ float sigm(float x) { return __builtin_amdgcn_rcpf(1.f + __expf(-x)); }
;     __device__ __forceinline__ void operator()(f32x4 (&acc)[2][2][4][2], const Unit& u, int wr, int wc, int fr, int fq) const {
;     ...
;                     f32x4 v0 = acc[ai][bj][m][0], v1 = acc[ai][bj][m][1];
;                     if (act == 1) {
; #pragma unroll
;                         for (int j = 0; j < 4; ++j) { v0[j] = v0[j] * sigm(v0[j]); v1[j] = v1[j] * sigm(v1[j]); }
;                     } else if (act == 2) {
; #pragma unroll
;                         for (int j = 0; j < 4; ++j) { v0[j] = sigm(v0[j]); v1[j] = sigm(v1[j]); }
;                     }
;                     u32x4 w; w.x = pk_bf16(v0[0], v0[1]); w.y = pk_bf16(v0[2], v0[3]); w.z = pk_bf16(v1[0], v1[1]); w.w = pk_bf16(v1[2], v1[3]);
;                     *(u32x4*)(pb + (size_t)(ai * 128 + m * 16) * NIN) = w;
.LBB0_3655:
	v_cvt_pk_bf16_f32 v146, v146, v147
	v_cvt_pk_bf16_f32 v147, v150, v151
	v_add_co_u32_e32 v150, vcc, 0x75000, v144
	v_cvt_pk_bf16_f32 v148, v148, v149
	v_cvt_pk_bf16_f32 v149, v152, v153
	s_cmp_gt_i32 s53, 1
	s_nop 0
	v_addc_co_u32_e32 v151, vcc, 0, v145, vcc
	s_mov_b64 s[68:69], -1
	global_store_dwordx4 v[150:151], v[146:149], off nt
	s_cbranch_scc0 .LBB0_3657
	v_mul_f32_e32 v136, 0xbfb8aa3b, v76
	v_exp_f32_e32 v136, v136
	v_mul_f32_e32 v146, 0xbfb8aa3b, v72
	v_exp_f32_e32 v146, v146
	v_mul_f32_e32 v148, 0xbfb8aa3b, v73
	v_add_f32_e32 v136, 1.0, v136
	v_exp_f32_e32 v149, v148
	v_add_f32_e32 v147, 1.0, v146
	v_rcp_f32_e32 v146, v136
	v_mul_f32_e32 v136, 0xbfb8aa3b, v77
	v_exp_f32_e32 v136, v136
	v_rcp_f32_e32 v148, v147
	v_mul_f32_e32 v152, 0xbfb8aa3b, v75
	v_exp_f32_e32 v153, v152
	v_add_f32_e32 v136, 1.0, v136
	v_rcp_f32_e32 v147, v136
	v_add_f32_e32 v136, 1.0, v149
	v_mul_f32_e32 v149, 0xbfb8aa3b, v78
	v_exp_f32_e32 v150, v149
	v_mul_f32_e32 v149, 0xbfb8aa3b, v74
	v_exp_f32_e32 v151, v149
	v_rcp_f32_e32 v149, v136
	v_add_f32_e32 v136, 1.0, v150
	v_rcp_f32_e32 v150, v136
	v_add_f32_e32 v136, 1.0, v151
	v_mul_f32_e32 v151, 0xbfb8aa3b, v79
	v_exp_f32_e32 v151, v151
	v_rcp_f32_e32 v152, v136
	s_mov_b64 s[68:69], 0
	v_add_f32_e32 v136, 1.0, v151
	v_rcp_f32_e32 v151, v136
	v_add_f32_e32 v136, 1.0, v153
	v_rcp_f32_e32 v153, v136

; __device__ __forceinline__ unsigned pk_bf16(float lo, float hi) { unsigned r; asm("v_cvt_pk_bf16_f32 %0, %1, %2" : "=v"(r) : "v"(lo), "v"(hi)); return r; }
; __device__ __forceinline__ float sigm(float x) { return __builtin_amdgcn_rcpf(1.f + __expf(-x)); }
;     __device__ __forceinline__ void operator()(f32x4 (&acc)[2][2][4][2], const Unit& u, int wr, int wc, int fr, int fq) const {
;     ...
;                     f32x4 v0 = acc[ai][bj][m][0], v1 = acc[ai][bj][m][1];
;                     if (act == 1) {
; #pragma unroll
;                         for (int j = 0; j < 4; ++j) { v0[j] = v0[j] * sigm(v0[j]); v1[j] = v1[j] * sigm(v1[j]); }
;                     } else if (act == 2) {
; #pragma unroll
;                         for (int j = 0; j < 4; ++j) { v0[j] = sigm(v0[j]); v1[j] = sigm(v1[j]); }
;                     }
;                     u32x4 w; w.x = pk_bf16(v0[0], v0[1]); w.y = pk_bf16(v0[2], v0[3]); w.z = pk_bf16(v1[0], v1[1]); w.w = pk_bf16(v1[2], v1[3]);
;                     *(u32x4*)(pb + (size_t)(ai * 128 + m * 16) * NIN) = w;
.LBB0_3660:
	v_cvt_pk_bf16_f32 v146, v146, v147
	v_cvt_pk_bf16_f32 v147, v150, v151
	v_add_co_u32_e32 v150, vcc, 0xea000, v144
	v_cvt_pk_bf16_f32 v148, v148, v149
	v_cvt_pk_bf16_f32 v149, v152, v153
	s_cmp_gt_i32 s53, 1
	s_nop 0
	v_addc_co_u32_e32 v151, vcc, 0, v145, vcc
	s_mov_b64 s[68:69], -1
	global_store_dwordx4 v[150:151], v[146:149], off nt
	s_cbranch_scc0 .LBB0_3662
	v_mul_f32_e32 v136, 0xbfb8aa3b, v68
	v_exp_f32_e32 v136, v136
	v_mul_f32_e32 v146, 0xbfb8aa3b, v64
	v_exp_f32_e32 v146, v146
	v_mul_f32_e32 v148, 0xbfb8aa3b, v65
	v_add_f32_e32 v136, 1.0, v136
	v_exp_f32_e32 v149, v148
	v_add_f32_e32 v147, 1.0, v146
	v_rcp_f32_e32 v146, v136
	v_mul_f32_e32 v136, 0xbfb8aa3b, v69
	v_exp_f32_e32 v136, v136
	v_rcp_f32_e32 v148, v147
	v_mul_f32_e32 v152, 0xbfb8aa3b, v67
	v_exp_f32_e32 v153, v152
	v_add_f32_e32 v136, 1.0, v136
	v_rcp_f32_e32 v147, v136
	v_add_f32_e32 v136, 1.0, v149
	v_mul_f32_e32 v149, 0xbfb8aa3b, v70
	v_exp_f32_e32 v150, v149
	v_mul_f32_e32 v149, 0xbfb8aa3b, v66
	v_exp_f32_e32 v151, v149
	v_rcp_f32_e32 v149, v136
	v_add_f32_e32 v136, 1.0, v150
	v_rcp_f32_e32 v150, v136
	v_add_f32_e32 v136, 1.0, v151
	v_mul_f32_e32 v151, 0xbfb8aa3b, v71
	v_exp_f32_e32 v151, v151
	v_rcp_f32_e32 v152, v136
	s_mov_b64 s[68:69], 0
	v_add_f32_e32 v136, 1.0, v151
	v_rcp_f32_e32 v151, v136
	v_add_f32_e32 v136, 1.0, v153
	v_rcp_f32_e32 v153, v136

; __device__ __forceinline__ unsigned pk_bf16(float lo, float hi) { unsigned r; asm("v_cvt_pk_bf16_f32 %0, %1, %2" : "=v"(r) : "v"(lo), "v"(hi)); return r; }
; __device__ __forceinline__ float sigm(float x) { return __builtin_amdgcn_rcpf(1.f + __expf(-x)); }
;     __device__ __forceinline__ void operator()(f32x4 (&acc)[2][2][4][2], const Unit& u, int wr, int wc, int fr, int fq) const {
;     ...
;                     f32x4 v0 = acc[ai][bj][m][0], v1 = acc[ai][bj][m][1];
;                     if (act == 1) {
; #pragma unroll
;                         for (int j = 0; j < 4; ++j) { v0[j] = v0[j] * sigm(v0[j]); v1[j] = v1[j] * sigm(v1[j]); }
;                     } else if (act == 2) {
; #pragma unroll
;                         for (int j = 0; j < 4; ++j) { v0[j] = sigm(v0[j]); v1[j] = sigm(v1[j]); }
;                     }
;                     u32x4 w; w.x = pk_bf16(v0[0], v0[1]); w.y = pk_bf16(v0[2], v0[3]); w.z = pk_bf16(v1[0], v1[1]); w.w = pk_bf16(v1[2], v1[3]);
;                     *(u32x4*)(pb + (size_t)(ai * 128 + m * 16) * NIN) = w;
.LBB0_3665:
	v_cvt_pk_bf16_f32 v146, v146, v147
	v_cvt_pk_bf16_f32 v147, v150, v151
	v_add_co_u32_e32 v150, vcc, 0x15f000, v144
	v_cvt_pk_bf16_f32 v148, v148, v149
	v_cvt_pk_bf16_f32 v149, v152, v153
	s_cmp_gt_i32 s53, 1
	s_nop 0
	v_addc_co_u32_e32 v151, vcc, 0, v145, vcc
	s_mov_b64 s[68:69], -1
	global_store_dwordx4 v[150:151], v[146:149], off nt
	s_cbranch_scc0 .LBB0_3667
	v_mul_f32_e32 v136, 0xbfb8aa3b, v28
	v_exp_f32_e32 v136, v136
	v_mul_f32_e32 v146, 0xbfb8aa3b, v24
	v_exp_f32_e32 v146, v146
	v_mul_f32_e32 v148, 0xbfb8aa3b, v25
	v_add_f32_e32 v136, 1.0, v136
	v_exp_f32_e32 v149, v148
	v_add_f32_e32 v147, 1.0, v146
	v_rcp_f32_e32 v146, v136
	v_mul_f32_e32 v136, 0xbfb8aa3b, v29
	v_exp_f32_e32 v136, v136
	v_rcp_f32_e32 v148, v147
	v_mul_f32_e32 v152, 0xbfb8aa3b, v27
	v_exp_f32_e32 v153, v152
	v_add_f32_e32 v136, 1.0, v136
	v_rcp_f32_e32 v147, v136
	v_add_f32_e32 v136, 1.0, v149
	v_mul_f32_e32 v149, 0xbfb8aa3b, v30
	v_exp_f32_e32 v150, v149
	v_mul_f32_e32 v149, 0xbfb8aa3b, v26
	v_exp_f32_e32 v151, v149
	v_rcp_f32_e32 v149, v136
	v_add_f32_e32 v136, 1.0, v150
	v_rcp_f32_e32 v150, v136
	v_add_f32_e32 v136, 1.0, v151
	v_mul_f32_e32 v151, 0xbfb8aa3b, v31
	v_exp_f32_e32 v151, v151
	v_rcp_f32_e32 v152, v136
	s_mov_b64 s[68:69], 0
	v_add_f32_e32 v136, 1.0, v151
	v_rcp_f32_e32 v151, v136
	v_add_f32_e32 v136, 1.0, v153
	v_rcp_f32_e32 v153, v136

; __device__ __forceinline__ unsigned pk_bf16(float lo, float hi) { unsigned r; asm("v_cvt_pk_bf16_f32 %0, %1, %2" : "=v"(r) : "v"(lo), "v"(hi)); return r; }
; __device__ __forceinline__ float sigm(float x) { return __builtin_amdgcn_rcpf(1.f + __expf(-x)); }
;     __device__ __forceinline__ void operator()(f32x4 (&acc)[2][2][4][2], const Unit& u, int wr, int wc, int fr, int fq) const {
;     ...
;                     f32x4 v0 = acc[ai][bj][m][0], v1 = acc[ai][bj][m][1];
;                     if (act == 1) {
; #pragma unroll
;                         for (int j = 0; j < 4; ++j) { v0[j] = v0[j] * sigm(v0[j]); v1[j] = v1[j] * sigm(v1[j]); }
;                     } else if (act == 2) {
; #pragma unroll
;                         for (int j = 0; j < 4; ++j) { v0[j] = sigm(v0[j]); v1[j] = sigm(v1[j]); }
;                     }
;                     u32x4 w; w.x = pk_bf16(v0[0], v0[1]); w.y = pk_bf16(v0[2], v0[3]); w.z = pk_bf16(v1[0], v1[1]); w.w = pk_bf16(v1[2], v1[3]);
;                     *(u32x4*)(pb + (size_t)(ai * 128 + m * 16) * NIN) = w;
.LBB0_3670:
	v_cvt_pk_bf16_f32 v146, v146, v147
	v_cvt_pk_bf16_f32 v147, v150, v151
	v_add_co_u32_e32 v150, vcc, 0x3a8000, v144
	v_cvt_pk_bf16_f32 v148, v148, v149
	v_cvt_pk_bf16_f32 v149, v152, v153
	s_cmp_gt_i32 s53, 1
	s_nop 0
	v_addc_co_u32_e32 v151, vcc, 0, v145, vcc
	s_mov_b64 s[68:69], -1
	global_store_dwordx4 v[150:151], v[146:149], off nt
	s_cbranch_scc0 .LBB0_3672
	v_mul_f32_e32 v136, 0xbfb8aa3b, v20
	v_exp_f32_e32 v136, v136
	v_mul_f32_e32 v146, 0xbfb8aa3b, v16
	v_exp_f32_e32 v146, v146
	v_mul_f32_e32 v148, 0xbfb8aa3b, v17
	v_add_f32_e32 v136, 1.0, v136
	v_exp_f32_e32 v149, v148
	v_add_f32_e32 v147, 1.0, v146
	v_rcp_f32_e32 v146, v136
	v_mul_f32_e32 v136, 0xbfb8aa3b, v21
	v_exp_f32_e32 v136, v136
	v_rcp_f32_e32 v148, v147
	v_mul_f32_e32 v152, 0xbfb8aa3b, v19
	v_exp_f32_e32 v153, v152
	v_add_f32_e32 v136, 1.0, v136
	v_rcp_f32_e32 v147, v136
	v_add_f32_e32 v136, 1.0, v149
	v_mul_f32_e32 v149, 0xbfb8aa3b, v22
	v_exp_f32_e32 v150, v149
	v_mul_f32_e32 v149, 0xbfb8aa3b, v18
	v_exp_f32_e32 v151, v149
	v_rcp_f32_e32 v149, v136
	v_add_f32_e32 v136, 1.0, v150
	v_rcp_f32_e32 v150, v136
	v_add_f32_e32 v136, 1.0, v151
	v_mul_f32_e32 v151, 0xbfb8aa3b, v23
	v_exp_f32_e32 v151, v151
	v_rcp_f32_e32 v152, v136
	s_mov_b64 s[68:69], 0
	v_add_f32_e32 v136, 1.0, v151
	v_rcp_f32_e32 v151, v136
	v_add_f32_e32 v136, 1.0, v153
	v_rcp_f32_e32 v153, v136

; __device__ __forceinline__ unsigned pk_bf16(float lo, float hi) { unsigned r; asm("v_cvt_pk_bf16_f32 %0, %1, %2" : "=v"(r) : "v"(lo), "v"(hi)); return r; }
; __device__ __forceinline__ float sigm(float x) { return __builtin_amdgcn_rcpf(1.f + __expf(-x)); }
;     __device__ __forceinline__ void operator()(f32x4 (&acc)[2][2][4][2], const Unit& u, int wr, int wc, int fr, int fq) const {
;     ...
;                     f32x4 v0 = acc[ai][bj][m][0], v1 = acc[ai][bj][m][1];
;                     if (act == 1) {
; #pragma unroll
;                         for (int j = 0; j < 4; ++j) { v0[j] = v0[j] * sigm(v0[j]); v1[j] = v1[j] * sigm(v1[j]); }
;                     } else if (act == 2) {
; #pragma unroll
;                         for (int j = 0; j < 4; ++j) { v0[j] = sigm(v0[j]); v1[j] = sigm(v1[j]); }
;                     }
;                     u32x4 w; w.x = pk_bf16(v0[0], v0[1]); w.y = pk_bf16(v0[2], v0[3]); w.z = pk_bf16(v1[0], v1[1]); w.w = pk_bf16(v1[2], v1[3]);
;                     *(u32x4*)(pb + (size_t)(ai * 128 + m * 16) * NIN) = w;
.LBB0_3675:
	v_cvt_pk_bf16_f32 v146, v146, v147
	v_cvt_pk_bf16_f32 v147, v150, v151
	v_add_co_u32_e32 v150, vcc, 0x41d000, v144
	v_cvt_pk_bf16_f32 v148, v148, v149
	v_cvt_pk_bf16_f32 v149, v152, v153
	s_cmp_gt_i32 s53, 1
	s_nop 0
	v_addc_co_u32_e32 v151, vcc, 0, v145, vcc
	s_mov_b64 s[68:69], -1
	global_store_dwordx4 v[150:151], v[146:149], off nt
	s_cbranch_scc0 .LBB0_3677
	v_mul_f32_e32 v136, 0xbfb8aa3b, v12
	v_exp_f32_e32 v136, v136
	v_mul_f32_e32 v146, 0xbfb8aa3b, v8
	v_exp_f32_e32 v146, v146
	v_mul_f32_e32 v148, 0xbfb8aa3b, v9
	v_add_f32_e32 v136, 1.0, v136
	v_exp_f32_e32 v149, v148
	v_add_f32_e32 v147, 1.0, v146
	v_rcp_f32_e32 v146, v136
	v_mul_f32_e32 v136, 0xbfb8aa3b, v13
	v_exp_f32_e32 v136, v136
	v_rcp_f32_e32 v148, v147
	v_mul_f32_e32 v152, 0xbfb8aa3b, v11
	v_exp_f32_e32 v153, v152
	v_add_f32_e32 v136, 1.0, v136
	v_rcp_f32_e32 v147, v136
	v_add_f32_e32 v136, 1.0, v149
	v_mul_f32_e32 v149, 0xbfb8aa3b, v14
	v_exp_f32_e32 v150, v149
	v_mul_f32_e32 v149, 0xbfb8aa3b, v10
	v_exp_f32_e32 v151, v149
	v_rcp_f32_e32 v149, v136
	v_add_f32_e32 v136, 1.0, v150
	v_rcp_f32_e32 v150, v136
	v_add_f32_e32 v136, 1.0, v151
	v_mul_f32_e32 v151, 0xbfb8aa3b, v15
	v_exp_f32_e32 v151, v151
	v_rcp_f32_e32 v152, v136
	s_mov_b64 s[68:69], 0
	v_add_f32_e32 v136, 1.0, v151
	v_rcp_f32_e32 v151, v136
	v_add_f32_e32 v136, 1.0, v153
	v_rcp_f32_e32 v153, v136

; __device__ __forceinline__ unsigned pk_bf16(float lo, float hi) { unsigned r; asm("v_cvt_pk_bf16_f32 %0, %1, %2" : "=v"(r) : "v"(lo), "v"(hi)); return r; }
; __device__ __forceinline__ float sigm(float x) { return __builtin_amdgcn_rcpf(1.f + __expf(-x)); }
;     __device__ __forceinline__ void operator()(f32x4 (&acc)[2][2][4][2], const Unit& u, int wr, int wc, int fr, int fq) const {
;     ...
;                     f32x4 v0 = acc[ai][bj][m][0], v1 = acc[ai][bj][m][1];
;                     if (act == 1) {
; #pragma unroll
;                         for (int j = 0; j < 4; ++j) { v0[j] = v0[j] * sigm(v0[j]); v1[j] = v1[j] * sigm(v1[j]); }
;                     } else if (act == 2) {
; #pragma unroll
;                         for (int j = 0; j < 4; ++j) { v0[j] = sigm(v0[j]); v1[j] = sigm(v1[j]); }
;                     }
;                     u32x4 w; w.x = pk_bf16(v0[0], v0[1]); w.y = pk_bf16(v0[2], v0[3]); w.z = pk_bf16(v1[0], v1[1]); w.w = pk_bf16(v1[2], v1[3]);
;                     *(u32x4*)(pb + (size_t)(ai * 128 + m * 16) * NIN) = w;
.LBB0_3680:
	v_cvt_pk_bf16_f32 v146, v146, v147
	v_cvt_pk_bf16_f32 v147, v150, v151
	v_add_co_u32_e32 v150, vcc, 0x492000, v144
	v_cvt_pk_bf16_f32 v148, v148, v149
	v_cvt_pk_bf16_f32 v149, v152, v153
	s_cmp_gt_i32 s53, 1
	s_nop 0
	v_addc_co_u32_e32 v151, vcc, 0, v145, vcc
	s_mov_b64 s[68:69], -1
	global_store_dwordx4 v[150:151], v[146:149], off nt
	s_cbranch_scc0 .LBB0_3682
	v_mul_f32_e32 v136, 0xbfb8aa3b, v4
	v_exp_f32_e32 v136, v136
	v_mul_f32_e32 v146, 0xbfb8aa3b, v0
	v_exp_f32_e32 v146, v146
	v_mul_f32_e32 v148, 0xbfb8aa3b, v1
	v_add_f32_e32 v136, 1.0, v136
	v_exp_f32_e32 v149, v148
	v_add_f32_e32 v147, 1.0, v146
	v_rcp_f32_e32 v146, v136
	v_mul_f32_e32 v136, 0xbfb8aa3b, v5
	v_exp_f32_e32 v136, v136
	v_rcp_f32_e32 v148, v147
	v_mul_f32_e32 v152, 0xbfb8aa3b, v3
	v_exp_f32_e32 v153, v152
	v_add_f32_e32 v136, 1.0, v136
	v_rcp_f32_e32 v147, v136
	v_add_f32_e32 v136, 1.0, v149
	v_mul_f32_e32 v149, 0xbfb8aa3b, v6
	v_exp_f32_e32 v150, v149
	v_mul_f32_e32 v149, 0xbfb8aa3b, v2
	v_exp_f32_e32 v151, v149
	v_rcp_f32_e32 v149, v136
	v_add_f32_e32 v136, 1.0, v150
	v_rcp_f32_e32 v150, v136
	v_add_f32_e32 v136, 1.0, v151
	v_mul_f32_e32 v151, 0xbfb8aa3b, v7
	v_exp_f32_e32 v151, v151
	v_rcp_f32_e32 v152, v136
	s_mov_b64 s[68:69], 0
	v_add_f32_e32 v136, 1.0, v151
	v_rcp_f32_e32 v151, v136
	v_add_f32_e32 v136, 1.0, v153
	v_rcp_f32_e32 v153, v136

; __device__ __forceinline__ unsigned pk_bf16(float lo, float hi) { unsigned r; asm("v_cvt_pk_bf16_f32 %0, %1, %2" : "=v"(r) : "v"(lo), "v"(hi)); return r; }
; __device__ __forceinline__ float sigm(float x) { return __builtin_amdgcn_rcpf(1.f + __expf(-x)); }
;     __device__ __forceinline__ void operator()(f32x4 (&acc)[2][2][4][2], const Unit& u, int wr, int wc, int fr, int fq) const {
;     ...
;                     f32x4 v0 = acc[ai][bj][m][0], v1 = acc[ai][bj][m][1];
;                     if (act == 1) {
; #pragma unroll
;                         for (int j = 0; j < 4; ++j) { v0[j] = v0[j] * sigm(v0[j]); v1[j] = v1[j] * sigm(v1[j]); }
;                     } else if (act == 2) {
; #pragma unroll
;                         for (int j = 0; j < 4; ++j) { v0[j] = sigm(v0[j]); v1[j] = sigm(v1[j]); }
;                     }
;                     u32x4 w; w.x = pk_bf16(v0[0], v0[1]); w.y = pk_bf16(v0[2], v0[3]); w.z = pk_bf16(v1[0], v1[1]); w.w = pk_bf16(v1[2], v1[3]);
;                     *(u32x4*)(pb + (size_t)(ai * 128 + m * 16) * NIN) = w;
;                 }
;         }
;     }
.LBB0_3685:
	v_add_co_u32_e32 v144, vcc, 0x507000, v144
	v_cvt_pk_bf16_f32 v146, v146, v147
	v_cvt_pk_bf16_f32 v147, v150, v151
	v_cvt_pk_bf16_f32 v148, v148, v149
	v_cvt_pk_bf16_f32 v149, v152, v153
	s_nop 1
	v_addc_co_u32_e32 v145, vcc, 0, v145, vcc
	global_store_dwordx4 v[144:145], v[146:149], off nt
	s_add_u32 s68, s81, 0xffffff00
	s_addc_u32 s69, s82, -1
	s_andn2_b64 vcc, exec, s[64:65]
	s_cbranch_vccnz .LBB0_3590
